# steady K-loop MFMA order: both k-steps of each accumulator issued back to back (same math order per accumulator)
# speedup vs baseline: 1.0151x; 1.0151x over previous
.LBB0_257:
	s_or_b64 exec, exec, s[50:51]
	s_add_u32 s0, s12, s6
	ds_read_b128 v[146:149], v137
	ds_read_b128 v[150:153], v137 offset:1024
	ds_read_b128 v[154:157], v137 offset:2048
	ds_read_b128 v[158:161], v137 offset:3072
	ds_read_b128 v[162:165], v138
	ds_read_b128 v[166:169], v138 offset:1024
	ds_read_b128 v[170:173], v138 offset:2048
	ds_read_b128 v[174:177], v138 offset:3072
	s_addc_u32 s1, s13, s7
	s_add_u32 s50, s0, 0x20000
	s_addc_u32 s51, s1, 0
	s_add_u32 s52, s93, s6
	s_addc_u32 s53, s94, s7
	s_cmp_eq_u32 s6, 0x60000
	s_cselect_b32 s62, s95, s50
	s_cselect_b32 s63, s31, s51
	s_cselect_b32 s51, s29, s53
	s_cselect_b32 s50, s96, s52
	s_add_u32 s52, s62, 0x8000
	s_addc_u32 s53, s63, 0
	s_add_u32 s54, s50, 0x8000
	s_addc_u32 s55, s51, 0
	ds_read_b128 v[178:181], v139
	ds_read_b128 v[182:185], v139 offset:1024
	ds_read_b128 v[186:189], v139 offset:2048
	ds_read_b128 v[190:193], v139 offset:3072
	ds_read_b128 v[198:201], v139 offset:4096
	ds_read_b128 v[202:205], v139 offset:5120
	ds_read_b128 v[206:209], v139 offset:6144
	ds_read_b128 v[212:215], v139 offset:7168
	s_add_u32 s0, s0, 0x1c000
	s_addc_u32 s1, s1, 0
	s_mov_b32 m0, s78
	s_nop 0
	global_load_lds_dwordx4 v134, s[0:1]
	s_add_u32 m0, s78, 0x2000
	s_nop 0
	global_load_lds_dwordx4 v135, s[0:1]
	s_waitcnt vmcnt(8)
	s_waitcnt lgkmcnt(0)
	s_setprio 1
	s_barrier
	v_mfma_f32_16x16x32_bf16 v[122:125], v[146:149], v[178:181], v[122:125]
	v_mfma_f32_16x16x32_bf16 v[122:125], v[150:153], v[182:185], v[122:125]
	s_waitcnt lgkmcnt(5)
	v_mfma_f32_16x16x32_bf16 v[114:117], v[154:157], v[178:181], v[114:117]
	v_mfma_f32_16x16x32_bf16 v[114:117], v[158:161], v[182:185], v[114:117]
	s_waitcnt lgkmcnt(3)
	v_mfma_f32_16x16x32_bf16 v[106:109], v[146:149], v[186:189], v[106:109]
	v_mfma_f32_16x16x32_bf16 v[106:109], v[150:153], v[190:193], v[106:109]
	s_waitcnt lgkmcnt(1)
	v_mfma_f32_16x16x32_bf16 v[98:101], v[154:157], v[186:189], v[98:101]
	v_mfma_f32_16x16x32_bf16 v[98:101], v[158:161], v[190:193], v[98:101]
	v_mfma_f32_16x16x32_bf16 v[90:93], v[146:149], v[198:201], v[90:93]
	v_mfma_f32_16x16x32_bf16 v[90:93], v[150:153], v[202:205], v[90:93]
	v_mfma_f32_16x16x32_bf16 v[82:85], v[154:157], v[198:201], v[82:85]
	v_mfma_f32_16x16x32_bf16 v[82:85], v[158:161], v[202:205], v[82:85]
	v_mfma_f32_16x16x32_bf16 v[74:77], v[146:149], v[206:209], v[74:77]
	v_mfma_f32_16x16x32_bf16 v[74:77], v[150:153], v[212:215], v[74:77]
	s_waitcnt lgkmcnt(0)
	v_mfma_f32_16x16x32_bf16 v[66:69], v[154:157], v[206:209], v[66:69]
	v_mfma_f32_16x16x32_bf16 v[66:69], v[158:161], v[212:215], v[66:69]
	s_setprio 0
	s_setprio 1
	v_mfma_f32_16x16x32_bf16 v[126:129], v[162:165], v[178:181], v[126:129]
	v_mfma_f32_16x16x32_bf16 v[126:129], v[166:169], v[182:185], v[126:129]
	v_mfma_f32_16x16x32_bf16 v[118:121], v[170:173], v[178:181], v[118:121]
	v_mfma_f32_16x16x32_bf16 v[118:121], v[174:177], v[182:185], v[118:121]
	v_mfma_f32_16x16x32_bf16 v[110:113], v[162:165], v[186:189], v[110:113]
	v_mfma_f32_16x16x32_bf16 v[110:113], v[166:169], v[190:193], v[110:113]
	v_mfma_f32_16x16x32_bf16 v[102:105], v[170:173], v[186:189], v[102:105]
	v_mfma_f32_16x16x32_bf16 v[102:105], v[174:177], v[190:193], v[102:105]
	v_mfma_f32_16x16x32_bf16 v[94:97], v[162:165], v[198:201], v[94:97]
	v_mfma_f32_16x16x32_bf16 v[94:97], v[166:169], v[202:205], v[94:97]
	v_mfma_f32_16x16x32_bf16 v[86:89], v[170:173], v[198:201], v[86:89]
	v_mfma_f32_16x16x32_bf16 v[86:89], v[174:177], v[202:205], v[86:89]
	v_mfma_f32_16x16x32_bf16 v[78:81], v[162:165], v[206:209], v[78:81]
	v_mfma_f32_16x16x32_bf16 v[78:81], v[166:169], v[212:215], v[78:81]
	s_setprio 2
	s_barrier
	v_mfma_f32_16x16x32_bf16 v[70:73], v[170:173], v[206:209], v[70:73]
	v_mfma_f32_16x16x32_bf16 v[70:73], v[174:177], v[212:215], v[70:73]
	s_setprio 0
	s_nop 0
	ds_read_b128 v[178:181], v139 offset:16384
	ds_read_b128 v[182:185], v139 offset:17408
	ds_read_b128 v[186:189], v139 offset:18432
	ds_read_b128 v[190:193], v139 offset:19456
	ds_read_b128 v[198:201], v139 offset:20480
	ds_read_b128 v[202:205], v139 offset:21504
	ds_read_b128 v[206:209], v139 offset:22528
	ds_read_b128 v[212:215], v139 offset:23552
	s_mov_b32 m0, s11
	s_nop 0
	global_load_lds_dwordx4 v134, s[50:51]
	s_add_u32 m0, s11, 0x2000
	s_nop 0
	global_load_lds_dwordx4 v135, s[50:51]
	s_add_u32 s0, s50, 0x4000
	s_addc_u32 s1, s51, 0
	s_mov_b32 m0, s68
	s_nop 0
	global_load_lds_dwordx4 v134, s[0:1]
	s_add_u32 m0, s68, 0x2000
	s_nop 0
	global_load_lds_dwordx4 v135, s[0:1]
	s_nop 0
	s_mov_b32 m0, s65
	s_nop 0
	global_load_lds_dwordx4 v134, s[62:63]
	s_add_u32 m0, s65, 0x2000
	s_nop 0
	global_load_lds_dwordx4 v135, s[62:63]
	s_waitcnt vmcnt(8)
	s_waitcnt lgkmcnt(0)
	s_setprio 1
	s_barrier
	v_mfma_f32_16x16x32_bf16 v[58:61], v[146:149], v[178:181], v[58:61]
	v_mfma_f32_16x16x32_bf16 v[58:61], v[150:153], v[182:185], v[58:61]
	s_waitcnt lgkmcnt(5)
	v_mfma_f32_16x16x32_bf16 v[50:53], v[154:157], v[178:181], v[50:53]
	v_mfma_f32_16x16x32_bf16 v[50:53], v[158:161], v[182:185], v[50:53]
	s_waitcnt lgkmcnt(3)
	v_mfma_f32_16x16x32_bf16 v[42:45], v[146:149], v[186:189], v[42:45]
	v_mfma_f32_16x16x32_bf16 v[42:45], v[150:153], v[190:193], v[42:45]
	s_waitcnt lgkmcnt(1)
	v_mfma_f32_16x16x32_bf16 v[34:37], v[154:157], v[186:189], v[34:37]
	v_mfma_f32_16x16x32_bf16 v[34:37], v[158:161], v[190:193], v[34:37]
	v_mfma_f32_16x16x32_bf16 v[26:29], v[146:149], v[198:201], v[26:29]
	v_mfma_f32_16x16x32_bf16 v[26:29], v[150:153], v[202:205], v[26:29]
	v_mfma_f32_16x16x32_bf16 v[18:21], v[154:157], v[198:201], v[18:21]
	v_mfma_f32_16x16x32_bf16 v[18:21], v[158:161], v[202:205], v[18:21]
	v_mfma_f32_16x16x32_bf16 v[10:13], v[146:149], v[206:209], v[10:13]
	v_mfma_f32_16x16x32_bf16 v[10:13], v[150:153], v[212:215], v[10:13]
	s_waitcnt lgkmcnt(0)
	v_mfma_f32_16x16x32_bf16 v[2:5], v[154:157], v[206:209], v[2:5]
	v_mfma_f32_16x16x32_bf16 v[2:5], v[158:161], v[212:215], v[2:5]
	s_setprio 0
	s_setprio 1
	v_mfma_f32_16x16x32_bf16 v[62:65], v[162:165], v[178:181], v[62:65]
	v_mfma_f32_16x16x32_bf16 v[62:65], v[166:169], v[182:185], v[62:65]
	v_mfma_f32_16x16x32_bf16 v[54:57], v[170:173], v[178:181], v[54:57]
	v_mfma_f32_16x16x32_bf16 v[54:57], v[174:177], v[182:185], v[54:57]
	v_mfma_f32_16x16x32_bf16 v[46:49], v[162:165], v[186:189], v[46:49]
	v_mfma_f32_16x16x32_bf16 v[46:49], v[166:169], v[190:193], v[46:49]
	v_mfma_f32_16x16x32_bf16 v[38:41], v[170:173], v[186:189], v[38:41]
	v_mfma_f32_16x16x32_bf16 v[38:41], v[174:177], v[190:193], v[38:41]
	v_mfma_f32_16x16x32_bf16 v[30:33], v[162:165], v[198:201], v[30:33]
	v_mfma_f32_16x16x32_bf16 v[30:33], v[166:169], v[202:205], v[30:33]
	v_mfma_f32_16x16x32_bf16 v[22:25], v[170:173], v[198:201], v[22:25]
	v_mfma_f32_16x16x32_bf16 v[22:25], v[174:177], v[202:205], v[22:25]
	v_mfma_f32_16x16x32_bf16 v[14:17], v[162:165], v[206:209], v[14:17]
	v_mfma_f32_16x16x32_bf16 v[14:17], v[166:169], v[212:215], v[14:17]
	s_setprio 2
	s_barrier
	v_mfma_f32_16x16x32_bf16 v[6:9], v[170:173], v[206:209], v[6:9]
	v_mfma_f32_16x16x32_bf16 v[6:9], v[174:177], v[212:215], v[6:9]
	s_setprio 0
	s_nop 0
	ds_read_b128 v[146:149], v140
	ds_read_b128 v[150:153], v140 offset:1024
	ds_read_b128 v[154:157], v140 offset:2048
	ds_read_b128 v[158:161], v140 offset:3072
	ds_read_b128 v[162:165], v141
	ds_read_b128 v[166:169], v141 offset:1024
	ds_read_b128 v[170:173], v141 offset:2048
	ds_read_b128 v[174:177], v141 offset:3072
	ds_read_b128 v[178:181], v139 offset:32768
	ds_read_b128 v[182:185], v139 offset:33792
	ds_read_b128 v[186:189], v139 offset:34816
	ds_read_b128 v[190:193], v139 offset:35840
	ds_read_b128 v[198:201], v139 offset:36864
	ds_read_b128 v[202:205], v139 offset:37888
	ds_read_b128 v[206:209], v139 offset:38912
	ds_read_b128 v[212:215], v139 offset:39936
	s_add_u32 s0, s62, 0x4000
	s_addc_u32 s1, s63, 0
	s_mov_b32 m0, s69
	s_nop 0
	global_load_lds_dwordx4 v134, s[0:1]
	s_add_u32 m0, s69, 0x2000
	s_nop 0
	global_load_lds_dwordx4 v135, s[0:1]
	s_waitcnt vmcnt(8)
	s_waitcnt lgkmcnt(0)
	s_setprio 1
	s_barrier
	v_mfma_f32_16x16x32_bf16 v[122:125], v[146:149], v[178:181], v[122:125]
	v_mfma_f32_16x16x32_bf16 v[122:125], v[150:153], v[182:185], v[122:125]
	s_waitcnt lgkmcnt(5)
	v_mfma_f32_16x16x32_bf16 v[114:117], v[154:157], v[178:181], v[114:117]
	v_mfma_f32_16x16x32_bf16 v[114:117], v[158:161], v[182:185], v[114:117]
	s_waitcnt lgkmcnt(3)
	v_mfma_f32_16x16x32_bf16 v[106:109], v[146:149], v[186:189], v[106:109]
	v_mfma_f32_16x16x32_bf16 v[106:109], v[150:153], v[190:193], v[106:109]
	s_waitcnt lgkmcnt(1)
	v_mfma_f32_16x16x32_bf16 v[98:101], v[154:157], v[186:189], v[98:101]
	v_mfma_f32_16x16x32_bf16 v[98:101], v[158:161], v[190:193], v[98:101]
	v_mfma_f32_16x16x32_bf16 v[90:93], v[146:149], v[198:201], v[90:93]
	v_mfma_f32_16x16x32_bf16 v[90:93], v[150:153], v[202:205], v[90:93]
	v_mfma_f32_16x16x32_bf16 v[82:85], v[154:157], v[198:201], v[82:85]
	v_mfma_f32_16x16x32_bf16 v[82:85], v[158:161], v[202:205], v[82:85]
	v_mfma_f32_16x16x32_bf16 v[74:77], v[146:149], v[206:209], v[74:77]
	v_mfma_f32_16x16x32_bf16 v[74:77], v[150:153], v[212:215], v[74:77]
	s_waitcnt lgkmcnt(0)
	v_mfma_f32_16x16x32_bf16 v[66:69], v[154:157], v[206:209], v[66:69]
	v_mfma_f32_16x16x32_bf16 v[66:69], v[158:161], v[212:215], v[66:69]
	s_setprio 0
	s_setprio 1
	v_mfma_f32_16x16x32_bf16 v[126:129], v[162:165], v[178:181], v[126:129]
	v_mfma_f32_16x16x32_bf16 v[126:129], v[166:169], v[182:185], v[126:129]
	v_mfma_f32_16x16x32_bf16 v[118:121], v[170:173], v[178:181], v[118:121]
	v_mfma_f32_16x16x32_bf16 v[118:121], v[174:177], v[182:185], v[118:121]
	v_mfma_f32_16x16x32_bf16 v[110:113], v[162:165], v[186:189], v[110:113]
	v_mfma_f32_16x16x32_bf16 v[110:113], v[166:169], v[190:193], v[110:113]
	v_mfma_f32_16x16x32_bf16 v[102:105], v[170:173], v[186:189], v[102:105]
	v_mfma_f32_16x16x32_bf16 v[102:105], v[174:177], v[190:193], v[102:105]
	v_mfma_f32_16x16x32_bf16 v[94:97], v[162:165], v[198:201], v[94:97]
	v_mfma_f32_16x16x32_bf16 v[94:97], v[166:169], v[202:205], v[94:97]
	v_mfma_f32_16x16x32_bf16 v[86:89], v[170:173], v[198:201], v[86:89]
	v_mfma_f32_16x16x32_bf16 v[86:89], v[174:177], v[202:205], v[86:89]
	v_mfma_f32_16x16x32_bf16 v[78:81], v[162:165], v[206:209], v[78:81]
	v_mfma_f32_16x16x32_bf16 v[78:81], v[166:169], v[212:215], v[78:81]
	s_setprio 2
	s_barrier
	v_mfma_f32_16x16x32_bf16 v[70:73], v[170:173], v[206:209], v[70:73]
	v_mfma_f32_16x16x32_bf16 v[70:73], v[174:177], v[212:215], v[70:73]
	s_setprio 0
	s_nop 0
	ds_read_b128 v[178:181], v139 offset:49152
	ds_read_b128 v[182:185], v139 offset:50176
	ds_read_b128 v[186:189], v139 offset:51200
	ds_read_b128 v[190:193], v139 offset:52224
	ds_read_b128 v[198:201], v139 offset:53248
	ds_read_b128 v[202:205], v139 offset:54272
	ds_read_b128 v[206:209], v139 offset:55296
	ds_read_b128 v[212:215], v139 offset:56320
	s_mov_b32 m0, s74
	s_nop 0
	global_load_lds_dwordx4 v134, s[54:55]
	s_add_u32 m0, s74, 0x2000
	s_nop 0
	global_load_lds_dwordx4 v135, s[54:55]
	s_add_u32 s0, s50, 0xc000
	s_addc_u32 s1, s51, 0
	s_mov_b32 m0, s77
	s_nop 0
	global_load_lds_dwordx4 v134, s[0:1]
	s_add_u32 m0, s77, 0x2000
	s_nop 0
	global_load_lds_dwordx4 v135, s[0:1]
	s_nop 0
	s_mov_b32 m0, s76
	s_nop 0
	global_load_lds_dwordx4 v134, s[52:53]
	s_add_u32 m0, s76, 0x2000
	s_nop 0
	global_load_lds_dwordx4 v135, s[52:53]
	s_waitcnt vmcnt(8)
	s_waitcnt lgkmcnt(0)
	s_setprio 1
	s_barrier
	v_mfma_f32_16x16x32_bf16 v[58:61], v[146:149], v[178:181], v[58:61]
	v_mfma_f32_16x16x32_bf16 v[58:61], v[150:153], v[182:185], v[58:61]
	s_waitcnt lgkmcnt(5)
	v_mfma_f32_16x16x32_bf16 v[50:53], v[154:157], v[178:181], v[50:53]
	v_mfma_f32_16x16x32_bf16 v[50:53], v[158:161], v[182:185], v[50:53]
	s_waitcnt lgkmcnt(3)
	v_mfma_f32_16x16x32_bf16 v[42:45], v[146:149], v[186:189], v[42:45]
	v_mfma_f32_16x16x32_bf16 v[42:45], v[150:153], v[190:193], v[42:45]
	s_waitcnt lgkmcnt(1)
	v_mfma_f32_16x16x32_bf16 v[34:37], v[154:157], v[186:189], v[34:37]
	v_mfma_f32_16x16x32_bf16 v[34:37], v[158:161], v[190:193], v[34:37]
	v_mfma_f32_16x16x32_bf16 v[26:29], v[146:149], v[198:201], v[26:29]
	v_mfma_f32_16x16x32_bf16 v[26:29], v[150:153], v[202:205], v[26:29]
	v_mfma_f32_16x16x32_bf16 v[18:21], v[154:157], v[198:201], v[18:21]
	v_mfma_f32_16x16x32_bf16 v[18:21], v[158:161], v[202:205], v[18:21]
	v_mfma_f32_16x16x32_bf16 v[10:13], v[146:149], v[206:209], v[10:13]
	v_mfma_f32_16x16x32_bf16 v[10:13], v[150:153], v[212:215], v[10:13]
	s_waitcnt lgkmcnt(0)
	v_mfma_f32_16x16x32_bf16 v[2:5], v[154:157], v[206:209], v[2:5]
	v_mfma_f32_16x16x32_bf16 v[2:5], v[158:161], v[212:215], v[2:5]
	s_setprio 0
	s_setprio 1
	v_mfma_f32_16x16x32_bf16 v[62:65], v[162:165], v[178:181], v[62:65]
	v_mfma_f32_16x16x32_bf16 v[62:65], v[166:169], v[182:185], v[62:65]
	v_mfma_f32_16x16x32_bf16 v[54:57], v[170:173], v[178:181], v[54:57]
	v_mfma_f32_16x16x32_bf16 v[54:57], v[174:177], v[182:185], v[54:57]
	v_mfma_f32_16x16x32_bf16 v[46:49], v[162:165], v[186:189], v[46:49]
	v_mfma_f32_16x16x32_bf16 v[46:49], v[166:169], v[190:193], v[46:49]
	v_mfma_f32_16x16x32_bf16 v[38:41], v[170:173], v[186:189], v[38:41]
	v_mfma_f32_16x16x32_bf16 v[38:41], v[174:177], v[190:193], v[38:41]
	v_mfma_f32_16x16x32_bf16 v[30:33], v[162:165], v[198:201], v[30:33]
	v_mfma_f32_16x16x32_bf16 v[30:33], v[166:169], v[202:205], v[30:33]
	v_mfma_f32_16x16x32_bf16 v[22:25], v[170:173], v[198:201], v[22:25]
	v_mfma_f32_16x16x32_bf16 v[22:25], v[174:177], v[202:205], v[22:25]
	v_mfma_f32_16x16x32_bf16 v[14:17], v[162:165], v[206:209], v[14:17]
	v_mfma_f32_16x16x32_bf16 v[14:17], v[166:169], v[212:215], v[14:17]
	s_setprio 2
	s_barrier
	v_mfma_f32_16x16x32_bf16 v[6:9], v[170:173], v[206:209], v[6:9]
	v_mfma_f32_16x16x32_bf16 v[6:9], v[174:177], v[212:215], v[6:9]
	s_setprio 0
	s_nop 0
	s_add_i32 s97, s97, 2
	s_add_u32 s6, s6, 0x10000
	s_addc_u32 s7, s7, 0
	s_cmp_gt_u32 s97, 13
	s_cbranch_scc1 .LBB0_259
	v_mov_b32_e32 v145, v130
	s_branch .LBB0_255

.LBB0_364:
	s_add_i32 s26, s93, 2
	s_lshl_b64 s[62:63], s[26:27], 15
	s_add_u32 s64, s18, s62
	s_addc_u32 s65, s19, s63
	s_and_b64 s[52:53], s[50:51], exec
	s_cselect_b32 s53, s65, s39
	s_cselect_b32 s52, s64, s38
	s_add_u32 s62, s20, s62
	s_waitcnt vmcnt(8)
	s_addc_u32 s63, s21, s63
	s_waitcnt lgkmcnt(0)
	s_and_b64 s[50:51], s[50:51], exec
	s_cselect_b32 s51, s63, s49
	s_cselect_b32 s50, s62, s48
	s_setprio 1
	s_barrier
	v_mfma_f32_16x16x32_bf16 v[126:129], v[146:149], v[186:189], v[126:129]
	v_mfma_f32_16x16x32_bf16 v[126:129], v[150:153], v[190:193], v[126:129]
	s_waitcnt lgkmcnt(5)
	v_mfma_f32_16x16x32_bf16 v[122:125], v[154:157], v[186:189], v[122:125]
	v_mfma_f32_16x16x32_bf16 v[122:125], v[158:161], v[190:193], v[122:125]
	s_waitcnt lgkmcnt(3)
	v_mfma_f32_16x16x32_bf16 v[118:121], v[146:149], v[178:181], v[118:121]
	v_mfma_f32_16x16x32_bf16 v[118:121], v[150:153], v[182:185], v[118:121]
	s_waitcnt lgkmcnt(1)
	v_mfma_f32_16x16x32_bf16 v[114:117], v[154:157], v[178:181], v[114:117]
	v_mfma_f32_16x16x32_bf16 v[114:117], v[158:161], v[182:185], v[114:117]
	v_mfma_f32_16x16x32_bf16 v[110:113], v[146:149], v[170:173], v[110:113]
	v_mfma_f32_16x16x32_bf16 v[110:113], v[150:153], v[174:177], v[110:113]
	v_mfma_f32_16x16x32_bf16 v[106:109], v[154:157], v[170:173], v[106:109]
	v_mfma_f32_16x16x32_bf16 v[106:109], v[158:161], v[174:177], v[106:109]
	v_mfma_f32_16x16x32_bf16 v[102:105], v[146:149], v[162:165], v[102:105]
	v_mfma_f32_16x16x32_bf16 v[102:105], v[150:153], v[166:169], v[102:105]
	s_waitcnt lgkmcnt(0)
	v_mfma_f32_16x16x32_bf16 v[98:101], v[154:157], v[162:165], v[98:101]
	v_mfma_f32_16x16x32_bf16 v[98:101], v[158:161], v[166:169], v[98:101]
	s_setprio 0
	s_setprio 1
	v_mfma_f32_16x16x32_bf16 v[94:97], v[130:133], v[186:189], v[94:97]
	v_mfma_f32_16x16x32_bf16 v[94:97], v[134:137], v[190:193], v[94:97]
	v_mfma_f32_16x16x32_bf16 v[90:93], v[138:141], v[186:189], v[90:93]
	v_mfma_f32_16x16x32_bf16 v[90:93], v[142:145], v[190:193], v[90:93]
	v_mfma_f32_16x16x32_bf16 v[86:89], v[130:133], v[178:181], v[86:89]
	v_mfma_f32_16x16x32_bf16 v[86:89], v[134:137], v[182:185], v[86:89]
	v_mfma_f32_16x16x32_bf16 v[82:85], v[138:141], v[178:181], v[82:85]
	v_mfma_f32_16x16x32_bf16 v[82:85], v[142:145], v[182:185], v[82:85]
	v_mfma_f32_16x16x32_bf16 v[78:81], v[130:133], v[170:173], v[78:81]
	v_mfma_f32_16x16x32_bf16 v[78:81], v[134:137], v[174:177], v[78:81]
	v_mfma_f32_16x16x32_bf16 v[74:77], v[138:141], v[170:173], v[74:77]
	v_mfma_f32_16x16x32_bf16 v[74:77], v[142:145], v[174:177], v[74:77]
	v_mfma_f32_16x16x32_bf16 v[70:73], v[130:133], v[162:165], v[70:73]
	v_mfma_f32_16x16x32_bf16 v[70:73], v[134:137], v[166:169], v[70:73]
	s_setprio 2
	s_barrier
	v_mfma_f32_16x16x32_bf16 v[66:69], v[138:141], v[162:165], v[66:69]
	v_mfma_f32_16x16x32_bf16 v[66:69], v[142:145], v[166:169], v[66:69]
	s_setprio 0
	s_nop 0
	ds_read_b128 v[186:189], v219 offset:16384
	ds_read_b128 v[190:193], v219 offset:17408
	ds_read_b128 v[178:181], v219 offset:18432
	ds_read_b128 v[182:185], v219 offset:19456
	ds_read_b128 v[170:173], v219 offset:20480
	ds_read_b128 v[174:177], v219 offset:21504
	ds_read_b128 v[162:165], v219 offset:22528
	ds_read_b128 v[166:169], v219 offset:23552
	s_mov_b32 m0, s74
	s_nop 0
	global_load_lds_dwordx4 v195, s[50:51]
	s_add_u32 m0, s74, 0x2000
	s_nop 0
	global_load_lds_dwordx4 v212, s[50:51]
	s_add_u32 s62, s50, 0x4000
	s_addc_u32 s63, s51, 0
	s_mov_b32 m0, s75
	s_nop 0
	global_load_lds_dwordx4 v195, s[62:63]
	s_add_u32 m0, s75, 0x2000
	s_nop 0
	global_load_lds_dwordx4 v212, s[62:63]
	s_andn2_b64 vcc, exec, s[54:55]
	s_mov_b32 m0, s73
	s_nop 0
	global_load_lds_dwordx4 v195, s[52:53]
	s_add_u32 m0, s73, 0x2000
	s_nop 0
	global_load_lds_dwordx4 v212, s[52:53]
	s_cbranch_vccnz .LBB0_366
	v_mov_b32_e32 v2, 0
	v_mov_b32_e32 v3, v2
	v_mov_b32_e32 v4, v2
	v_mov_b32_e32 v5, v2
	v_mov_b32_e32 v6, v2
	v_mov_b32_e32 v7, v2
	v_mov_b32_e32 v8, v2
	v_mov_b32_e32 v9, v2
	v_mov_b32_e32 v10, v2
	v_mov_b32_e32 v11, v2
	v_mov_b32_e32 v12, v2
	v_mov_b32_e32 v13, v2
	v_mov_b32_e32 v14, v2
	v_mov_b32_e32 v15, v2
	v_mov_b32_e32 v16, v2
	v_mov_b32_e32 v17, v2
	v_mov_b32_e32 v18, v2
	v_mov_b32_e32 v19, v2
	v_mov_b32_e32 v20, v2
	v_mov_b32_e32 v21, v2
	v_mov_b32_e32 v22, v2
	v_mov_b32_e32 v23, v2
	v_mov_b32_e32 v24, v2
	v_mov_b32_e32 v25, v2
	v_mov_b32_e32 v26, v2
	v_mov_b32_e32 v27, v2
	v_mov_b32_e32 v28, v2
	v_mov_b32_e32 v29, v2
	v_mov_b32_e32 v30, v2
	v_mov_b32_e32 v31, v2
	v_mov_b32_e32 v32, v2
	v_mov_b32_e32 v33, v2
	v_mov_b32_e32 v34, v2
	v_mov_b32_e32 v35, v2
	v_mov_b32_e32 v36, v2
	v_mov_b32_e32 v37, v2
	v_mov_b32_e32 v38, v2
	v_mov_b32_e32 v39, v2
	v_mov_b32_e32 v40, v2
	v_mov_b32_e32 v41, v2
	v_mov_b32_e32 v42, v2
	v_mov_b32_e32 v43, v2
	v_mov_b32_e32 v44, v2
	v_mov_b32_e32 v45, v2
	v_mov_b32_e32 v46, v2
	v_mov_b32_e32 v47, v2
	v_mov_b32_e32 v48, v2
	v_mov_b32_e32 v49, v2
	v_mov_b32_e32 v50, v2
	v_mov_b32_e32 v51, v2
	v_mov_b32_e32 v52, v2
	v_mov_b32_e32 v53, v2
	v_mov_b32_e32 v54, v2
	v_mov_b32_e32 v55, v2
	v_mov_b32_e32 v56, v2
	v_mov_b32_e32 v57, v2
	v_mov_b32_e32 v58, v2
	v_mov_b32_e32 v59, v2
	v_mov_b32_e32 v60, v2
	v_mov_b32_e32 v61, v2
	v_mov_b32_e32 v62, v2
	v_mov_b32_e32 v63, v2
	v_mov_b32_e32 v64, v2
	v_mov_b32_e32 v65, v2
.LBB0_366:
	s_waitcnt vmcnt(8)
	s_add_u32 s54, s52, 0x8000
	s_waitcnt lgkmcnt(0)
	s_addc_u32 s55, s53, 0
	s_add_u32 s62, s50, 0x8000
	s_addc_u32 s63, s51, 0
	s_setprio 1
	s_barrier
	v_mfma_f32_16x16x32_bf16 v[62:65], v[146:149], v[186:189], v[62:65]
	v_mfma_f32_16x16x32_bf16 v[62:65], v[150:153], v[190:193], v[62:65]
	s_waitcnt lgkmcnt(5)
	v_mfma_f32_16x16x32_bf16 v[58:61], v[154:157], v[186:189], v[58:61]
	v_mfma_f32_16x16x32_bf16 v[58:61], v[158:161], v[190:193], v[58:61]
	s_waitcnt lgkmcnt(3)
	v_mfma_f32_16x16x32_bf16 v[54:57], v[146:149], v[178:181], v[54:57]
	v_mfma_f32_16x16x32_bf16 v[54:57], v[150:153], v[182:185], v[54:57]
	s_waitcnt lgkmcnt(1)
	v_mfma_f32_16x16x32_bf16 v[50:53], v[154:157], v[178:181], v[50:53]
	v_mfma_f32_16x16x32_bf16 v[50:53], v[158:161], v[182:185], v[50:53]
	v_mfma_f32_16x16x32_bf16 v[46:49], v[146:149], v[170:173], v[46:49]
	v_mfma_f32_16x16x32_bf16 v[46:49], v[150:153], v[174:177], v[46:49]
	v_mfma_f32_16x16x32_bf16 v[42:45], v[154:157], v[170:173], v[42:45]
	v_mfma_f32_16x16x32_bf16 v[42:45], v[158:161], v[174:177], v[42:45]
	v_mfma_f32_16x16x32_bf16 v[38:41], v[146:149], v[162:165], v[38:41]
	v_mfma_f32_16x16x32_bf16 v[38:41], v[150:153], v[166:169], v[38:41]
	s_waitcnt lgkmcnt(0)
	v_mfma_f32_16x16x32_bf16 v[34:37], v[154:157], v[162:165], v[34:37]
	v_mfma_f32_16x16x32_bf16 v[34:37], v[158:161], v[166:169], v[34:37]
	s_setprio 0
	s_setprio 1
	v_mfma_f32_16x16x32_bf16 v[30:33], v[130:133], v[186:189], v[30:33]
	v_mfma_f32_16x16x32_bf16 v[30:33], v[134:137], v[190:193], v[30:33]
	v_mfma_f32_16x16x32_bf16 v[26:29], v[138:141], v[186:189], v[26:29]
	v_mfma_f32_16x16x32_bf16 v[26:29], v[142:145], v[190:193], v[26:29]
	v_mfma_f32_16x16x32_bf16 v[22:25], v[130:133], v[178:181], v[22:25]
	v_mfma_f32_16x16x32_bf16 v[22:25], v[134:137], v[182:185], v[22:25]
	v_mfma_f32_16x16x32_bf16 v[18:21], v[138:141], v[178:181], v[18:21]
	v_mfma_f32_16x16x32_bf16 v[18:21], v[142:145], v[182:185], v[18:21]
	v_mfma_f32_16x16x32_bf16 v[14:17], v[130:133], v[170:173], v[14:17]
	v_mfma_f32_16x16x32_bf16 v[14:17], v[134:137], v[174:177], v[14:17]
	v_mfma_f32_16x16x32_bf16 v[10:13], v[138:141], v[170:173], v[10:13]
	v_mfma_f32_16x16x32_bf16 v[10:13], v[142:145], v[174:177], v[10:13]
	v_mfma_f32_16x16x32_bf16 v[6:9], v[130:133], v[162:165], v[6:9]
	v_mfma_f32_16x16x32_bf16 v[6:9], v[134:137], v[166:169], v[6:9]
	s_setprio 2
	s_barrier
	v_mfma_f32_16x16x32_bf16 v[2:5], v[138:141], v[162:165], v[2:5]
	v_mfma_f32_16x16x32_bf16 v[2:5], v[142:145], v[166:169], v[2:5]
	s_setprio 0
	s_nop 0
	v_add_u32_e32 v142, 0x18000, v218
	v_add_u32_e32 v158, 0x1c000, v218
	ds_read_b128 v[130:133], v142
	ds_read_b128 v[134:137], v142 offset:1024
	ds_read_b128 v[138:141], v142 offset:2048
	ds_read_b128 v[142:145], v142 offset:3072
	ds_read_b128 v[146:149], v158
	ds_read_b128 v[150:153], v158 offset:1024
	ds_read_b128 v[154:157], v158 offset:2048
	ds_read_b128 v[158:161], v158 offset:3072
	ds_read_b128 v[162:165], v219 offset:32768
	ds_read_b128 v[166:169], v219 offset:33792
	ds_read_b128 v[170:173], v219 offset:34816
	ds_read_b128 v[174:177], v219 offset:35840
	ds_read_b128 v[178:181], v219 offset:36864
	ds_read_b128 v[182:185], v219 offset:37888
	ds_read_b128 v[186:189], v219 offset:38912
	ds_read_b128 v[190:193], v219 offset:39936
	s_add_u32 s52, s52, 0x4000
	s_addc_u32 s53, s53, 0
	s_mov_b32 m0, s76
	s_nop 0
	global_load_lds_dwordx4 v195, s[52:53]
	s_add_u32 m0, s76, 0x2000
	s_nop 0
	global_load_lds_dwordx4 v212, s[52:53]
	s_waitcnt vmcnt(8)
	s_waitcnt lgkmcnt(0)
	s_setprio 1
	s_barrier
	v_mfma_f32_16x16x32_bf16 v[126:129], v[130:133], v[162:165], v[126:129]
	v_mfma_f32_16x16x32_bf16 v[126:129], v[134:137], v[166:169], v[126:129]
	s_waitcnt lgkmcnt(5)
	v_mfma_f32_16x16x32_bf16 v[122:125], v[138:141], v[162:165], v[122:125]
	v_mfma_f32_16x16x32_bf16 v[122:125], v[142:145], v[166:169], v[122:125]
	s_waitcnt lgkmcnt(3)
	v_mfma_f32_16x16x32_bf16 v[118:121], v[130:133], v[170:173], v[118:121]
	v_mfma_f32_16x16x32_bf16 v[118:121], v[134:137], v[174:177], v[118:121]
	s_waitcnt lgkmcnt(1)
	v_mfma_f32_16x16x32_bf16 v[114:117], v[138:141], v[170:173], v[114:117]
	v_mfma_f32_16x16x32_bf16 v[114:117], v[142:145], v[174:177], v[114:117]
	v_mfma_f32_16x16x32_bf16 v[110:113], v[130:133], v[178:181], v[110:113]
	v_mfma_f32_16x16x32_bf16 v[110:113], v[134:137], v[182:185], v[110:113]
	v_mfma_f32_16x16x32_bf16 v[106:109], v[138:141], v[178:181], v[106:109]
	v_mfma_f32_16x16x32_bf16 v[106:109], v[142:145], v[182:185], v[106:109]
	v_mfma_f32_16x16x32_bf16 v[102:105], v[130:133], v[186:189], v[102:105]
	v_mfma_f32_16x16x32_bf16 v[102:105], v[134:137], v[190:193], v[102:105]
	s_waitcnt lgkmcnt(0)
	v_mfma_f32_16x16x32_bf16 v[98:101], v[138:141], v[186:189], v[98:101]
	v_mfma_f32_16x16x32_bf16 v[98:101], v[142:145], v[190:193], v[98:101]
	s_setprio 0
	s_setprio 1
	v_mfma_f32_16x16x32_bf16 v[94:97], v[146:149], v[162:165], v[94:97]
	v_mfma_f32_16x16x32_bf16 v[94:97], v[150:153], v[166:169], v[94:97]
	v_mfma_f32_16x16x32_bf16 v[90:93], v[154:157], v[162:165], v[90:93]
	v_mfma_f32_16x16x32_bf16 v[90:93], v[158:161], v[166:169], v[90:93]
	v_mfma_f32_16x16x32_bf16 v[86:89], v[146:149], v[170:173], v[86:89]
	v_mfma_f32_16x16x32_bf16 v[86:89], v[150:153], v[174:177], v[86:89]
	v_mfma_f32_16x16x32_bf16 v[82:85], v[154:157], v[170:173], v[82:85]
	v_mfma_f32_16x16x32_bf16 v[82:85], v[158:161], v[174:177], v[82:85]
	v_mfma_f32_16x16x32_bf16 v[78:81], v[146:149], v[178:181], v[78:81]
	v_mfma_f32_16x16x32_bf16 v[78:81], v[150:153], v[182:185], v[78:81]
	v_mfma_f32_16x16x32_bf16 v[74:77], v[154:157], v[178:181], v[74:77]
	v_mfma_f32_16x16x32_bf16 v[74:77], v[158:161], v[182:185], v[74:77]
	v_mfma_f32_16x16x32_bf16 v[70:73], v[146:149], v[186:189], v[70:73]
	v_mfma_f32_16x16x32_bf16 v[70:73], v[150:153], v[190:193], v[70:73]
	s_setprio 2
	s_barrier
	v_mfma_f32_16x16x32_bf16 v[66:69], v[154:157], v[186:189], v[66:69]
	v_mfma_f32_16x16x32_bf16 v[66:69], v[158:161], v[190:193], v[66:69]
	s_setprio 0
	s_nop 0
	ds_read_b128 v[162:165], v219 offset:49152
	ds_read_b128 v[166:169], v219 offset:50176
	ds_read_b128 v[170:173], v219 offset:51200
	ds_read_b128 v[174:177], v219 offset:52224
	ds_read_b128 v[178:181], v219 offset:53248
	ds_read_b128 v[182:185], v219 offset:54272
	ds_read_b128 v[186:189], v219 offset:55296
	ds_read_b128 v[190:193], v219 offset:56320
	s_mov_b32 m0, s80
	s_nop 0
	global_load_lds_dwordx4 v195, s[62:63]
	s_add_u32 m0, s80, 0x2000
	s_nop 0
	global_load_lds_dwordx4 v212, s[62:63]
	s_add_u32 s50, s50, 0xc000
	s_addc_u32 s51, s51, 0
	s_mov_b32 m0, s82
	s_nop 0
	global_load_lds_dwordx4 v195, s[50:51]
	s_add_u32 m0, s82, 0x2000
	s_nop 0
	global_load_lds_dwordx4 v212, s[50:51]
	s_nop 0
	s_mov_b32 m0, s81
	s_nop 0
	global_load_lds_dwordx4 v195, s[54:55]
	s_add_u32 m0, s81, 0x2000
	s_nop 0
	global_load_lds_dwordx4 v212, s[54:55]
	s_waitcnt vmcnt(8)
	s_waitcnt lgkmcnt(0)
	s_setprio 1
	s_barrier
	v_mfma_f32_16x16x32_bf16 v[62:65], v[130:133], v[162:165], v[62:65]
	v_mfma_f32_16x16x32_bf16 v[62:65], v[134:137], v[166:169], v[62:65]
	s_waitcnt lgkmcnt(5)
	v_mfma_f32_16x16x32_bf16 v[58:61], v[138:141], v[162:165], v[58:61]
	v_mfma_f32_16x16x32_bf16 v[58:61], v[142:145], v[166:169], v[58:61]
	s_waitcnt lgkmcnt(3)
	v_mfma_f32_16x16x32_bf16 v[54:57], v[130:133], v[170:173], v[54:57]
	v_mfma_f32_16x16x32_bf16 v[54:57], v[134:137], v[174:177], v[54:57]
	s_waitcnt lgkmcnt(1)
	v_mfma_f32_16x16x32_bf16 v[50:53], v[138:141], v[170:173], v[50:53]
	v_mfma_f32_16x16x32_bf16 v[50:53], v[142:145], v[174:177], v[50:53]
	v_mfma_f32_16x16x32_bf16 v[46:49], v[130:133], v[178:181], v[46:49]
	v_mfma_f32_16x16x32_bf16 v[46:49], v[134:137], v[182:185], v[46:49]
	v_mfma_f32_16x16x32_bf16 v[42:45], v[138:141], v[178:181], v[42:45]
	v_mfma_f32_16x16x32_bf16 v[42:45], v[142:145], v[182:185], v[42:45]
	v_mfma_f32_16x16x32_bf16 v[38:41], v[130:133], v[186:189], v[38:41]
	v_mfma_f32_16x16x32_bf16 v[38:41], v[134:137], v[190:193], v[38:41]
	s_waitcnt lgkmcnt(0)
	v_mfma_f32_16x16x32_bf16 v[34:37], v[138:141], v[186:189], v[34:37]
	v_mfma_f32_16x16x32_bf16 v[34:37], v[142:145], v[190:193], v[34:37]
	s_setprio 0
	s_setprio 1
	v_mfma_f32_16x16x32_bf16 v[30:33], v[146:149], v[162:165], v[30:33]
	v_mfma_f32_16x16x32_bf16 v[30:33], v[150:153], v[166:169], v[30:33]
	v_mfma_f32_16x16x32_bf16 v[26:29], v[154:157], v[162:165], v[26:29]
	v_mfma_f32_16x16x32_bf16 v[26:29], v[158:161], v[166:169], v[26:29]
	v_mfma_f32_16x16x32_bf16 v[22:25], v[146:149], v[170:173], v[22:25]
	v_mfma_f32_16x16x32_bf16 v[22:25], v[150:153], v[174:177], v[22:25]
	v_mfma_f32_16x16x32_bf16 v[18:21], v[154:157], v[170:173], v[18:21]
	v_mfma_f32_16x16x32_bf16 v[18:21], v[158:161], v[174:177], v[18:21]
	v_mfma_f32_16x16x32_bf16 v[14:17], v[146:149], v[178:181], v[14:17]
	v_mfma_f32_16x16x32_bf16 v[14:17], v[150:153], v[182:185], v[14:17]
	v_mfma_f32_16x16x32_bf16 v[10:13], v[154:157], v[178:181], v[10:13]
	v_mfma_f32_16x16x32_bf16 v[10:13], v[158:161], v[182:185], v[10:13]
	v_mfma_f32_16x16x32_bf16 v[6:9], v[146:149], v[186:189], v[6:9]
	v_mfma_f32_16x16x32_bf16 v[6:9], v[150:153], v[190:193], v[6:9]
	s_setprio 2
	s_barrier
	v_mfma_f32_16x16x32_bf16 v[2:5], v[154:157], v[186:189], v[2:5]
	v_mfma_f32_16x16x32_bf16 v[2:5], v[158:161], v[190:193], v[2:5]
	s_setprio 0
	s_nop 0
	s_cmp_gt_u32 s93, 41
	s_cbranch_scc1 .LBB0_368
	v_mov_b32_e32 v130, v198
	s_mov_b32 s93, s26
	s_branch .LBB0_343

.LBB0_519:
	ds_read_b128 v[130:133], v141
	ds_read_b128 v[134:137], v141 offset:1024
	ds_read_b128 v[146:149], v141 offset:2048
	ds_read_b128 v[150:153], v141 offset:3072
	ds_read_b128 v[154:157], v142
	ds_read_b128 v[158:161], v142 offset:1024
	ds_read_b128 v[162:165], v142 offset:2048
	ds_read_b128 v[166:169], v142 offset:3072
	s_add_u32 s24, s26, 0x10000
	s_addc_u32 s25, s27, 0
	s_cmp_eq_u32 s77, 12
	s_cselect_b32 s48, s17, s24
	s_cselect_b32 s49, s1, s25
	s_cselect_b32 s30, s23, s75
	s_cselect_b32 s31, s15, s76
	s_add_u32 s28, s48, 0x8000
	s_addc_u32 s29, s49, 0
	ds_read_b128 v[170:173], v143
	ds_read_b128 v[174:177], v143 offset:1024
	ds_read_b128 v[178:181], v143 offset:2048
	ds_read_b128 v[182:185], v143 offset:3072
	ds_read_b128 v[186:189], v143 offset:4096
	ds_read_b128 v[190:193], v143 offset:5120
	ds_read_b128 v[198:201], v143 offset:6144
	ds_read_b128 v[202:205], v143 offset:7168
	s_add_u32 s38, s30, 0x8000
	s_addc_u32 s39, s31, 0
	s_add_u32 s26, s26, 0xc000
	s_addc_u32 s27, s27, 0
	s_mov_b32 m0, s72
	s_nop 0
	global_load_lds_dwordx4 v195, s[26:27]
	s_add_u32 m0, s72, 0x2000
	s_nop 0
	global_load_lds_dwordx4 v212, s[26:27]
	s_waitcnt vmcnt(8)
	s_waitcnt lgkmcnt(0)
	s_setprio 1
	s_barrier
	v_mfma_f32_16x16x32_bf16 v[122:125], v[130:133], v[170:173], v[122:125]
	v_mfma_f32_16x16x32_bf16 v[122:125], v[134:137], v[174:177], v[122:125]
	s_waitcnt lgkmcnt(5)
	v_mfma_f32_16x16x32_bf16 v[126:129], v[146:149], v[170:173], v[126:129]
	v_mfma_f32_16x16x32_bf16 v[126:129], v[150:153], v[174:177], v[126:129]
	s_waitcnt lgkmcnt(3)
	v_mfma_f32_16x16x32_bf16 v[110:113], v[130:133], v[178:181], v[110:113]
	v_mfma_f32_16x16x32_bf16 v[110:113], v[134:137], v[182:185], v[110:113]
	s_waitcnt lgkmcnt(1)
	v_mfma_f32_16x16x32_bf16 v[106:109], v[146:149], v[178:181], v[106:109]
	v_mfma_f32_16x16x32_bf16 v[106:109], v[150:153], v[182:185], v[106:109]
	v_mfma_f32_16x16x32_bf16 v[94:97], v[130:133], v[186:189], v[94:97]
	v_mfma_f32_16x16x32_bf16 v[94:97], v[134:137], v[190:193], v[94:97]
	v_mfma_f32_16x16x32_bf16 v[90:93], v[146:149], v[186:189], v[90:93]
	v_mfma_f32_16x16x32_bf16 v[90:93], v[150:153], v[190:193], v[90:93]
	v_mfma_f32_16x16x32_bf16 v[78:81], v[130:133], v[198:201], v[78:81]
	v_mfma_f32_16x16x32_bf16 v[78:81], v[134:137], v[202:205], v[78:81]
	s_waitcnt lgkmcnt(0)
	v_mfma_f32_16x16x32_bf16 v[74:77], v[146:149], v[198:201], v[74:77]
	v_mfma_f32_16x16x32_bf16 v[74:77], v[150:153], v[202:205], v[74:77]
	s_setprio 0
	s_setprio 1
	v_mfma_f32_16x16x32_bf16 v[114:117], v[154:157], v[170:173], v[114:117]
	v_mfma_f32_16x16x32_bf16 v[114:117], v[158:161], v[174:177], v[114:117]
	v_mfma_f32_16x16x32_bf16 v[118:121], v[162:165], v[170:173], v[118:121]
	v_mfma_f32_16x16x32_bf16 v[118:121], v[166:169], v[174:177], v[118:121]
	v_mfma_f32_16x16x32_bf16 v[98:101], v[154:157], v[178:181], v[98:101]
	v_mfma_f32_16x16x32_bf16 v[98:101], v[158:161], v[182:185], v[98:101]
	v_mfma_f32_16x16x32_bf16 v[102:105], v[162:165], v[178:181], v[102:105]
	v_mfma_f32_16x16x32_bf16 v[102:105], v[166:169], v[182:185], v[102:105]
	v_mfma_f32_16x16x32_bf16 v[82:85], v[154:157], v[186:189], v[82:85]
	v_mfma_f32_16x16x32_bf16 v[82:85], v[158:161], v[190:193], v[82:85]
	v_mfma_f32_16x16x32_bf16 v[86:89], v[162:165], v[186:189], v[86:89]
	v_mfma_f32_16x16x32_bf16 v[86:89], v[166:169], v[190:193], v[86:89]
	v_mfma_f32_16x16x32_bf16 v[66:69], v[154:157], v[198:201], v[66:69]
	v_mfma_f32_16x16x32_bf16 v[66:69], v[158:161], v[202:205], v[66:69]
	s_setprio 2
	s_barrier
	v_mfma_f32_16x16x32_bf16 v[70:73], v[162:165], v[198:201], v[70:73]
	v_mfma_f32_16x16x32_bf16 v[70:73], v[166:169], v[202:205], v[70:73]
	s_setprio 0
	s_nop 0
	ds_read_b128 v[170:173], v143 offset:16384
	ds_read_b128 v[174:177], v143 offset:17408
	ds_read_b128 v[178:181], v143 offset:18432
	ds_read_b128 v[182:185], v143 offset:19456
	ds_read_b128 v[186:189], v143 offset:20480
	ds_read_b128 v[190:193], v143 offset:21504
	ds_read_b128 v[198:201], v143 offset:22528
	ds_read_b128 v[202:205], v143 offset:23552
	s_mov_b32 m0, s55
	s_nop 0
	global_load_lds_dwordx4 v195, s[30:31]
	s_add_u32 m0, s55, 0x2000
	s_nop 0
	global_load_lds_dwordx4 v212, s[30:31]
	s_add_u32 s26, s30, 0x4000
	s_addc_u32 s27, s31, 0
	s_mov_b32 m0, s62
	s_nop 0
	global_load_lds_dwordx4 v195, s[26:27]
	s_add_u32 m0, s62, 0x2000
	s_nop 0
	global_load_lds_dwordx4 v212, s[26:27]
	s_nop 0
	s_mov_b32 m0, s54
	s_nop 0
	global_load_lds_dwordx4 v195, s[48:49]
	s_add_u32 m0, s54, 0x2000
	s_nop 0
	global_load_lds_dwordx4 v212, s[48:49]
	s_waitcnt vmcnt(8)
	s_waitcnt lgkmcnt(0)
	s_setprio 1
	s_barrier
	v_mfma_f32_16x16x32_bf16 v[62:65], v[130:133], v[170:173], v[62:65]
	v_mfma_f32_16x16x32_bf16 v[62:65], v[134:137], v[174:177], v[62:65]
	s_waitcnt lgkmcnt(5)
	v_mfma_f32_16x16x32_bf16 v[58:61], v[146:149], v[170:173], v[58:61]
	v_mfma_f32_16x16x32_bf16 v[58:61], v[150:153], v[174:177], v[58:61]
	s_waitcnt lgkmcnt(3)
	v_mfma_f32_16x16x32_bf16 v[46:49], v[130:133], v[178:181], v[46:49]
	v_mfma_f32_16x16x32_bf16 v[46:49], v[134:137], v[182:185], v[46:49]
	s_waitcnt lgkmcnt(1)
	v_mfma_f32_16x16x32_bf16 v[42:45], v[146:149], v[178:181], v[42:45]
	v_mfma_f32_16x16x32_bf16 v[42:45], v[150:153], v[182:185], v[42:45]
	v_mfma_f32_16x16x32_bf16 v[30:33], v[130:133], v[186:189], v[30:33]
	v_mfma_f32_16x16x32_bf16 v[30:33], v[134:137], v[190:193], v[30:33]
	v_mfma_f32_16x16x32_bf16 v[26:29], v[146:149], v[186:189], v[26:29]
	v_mfma_f32_16x16x32_bf16 v[26:29], v[150:153], v[190:193], v[26:29]
	v_mfma_f32_16x16x32_bf16 v[14:17], v[130:133], v[198:201], v[14:17]
	v_mfma_f32_16x16x32_bf16 v[14:17], v[134:137], v[202:205], v[14:17]
	s_waitcnt lgkmcnt(0)
	v_mfma_f32_16x16x32_bf16 v[10:13], v[146:149], v[198:201], v[10:13]
	v_mfma_f32_16x16x32_bf16 v[10:13], v[150:153], v[202:205], v[10:13]
	s_setprio 0
	s_setprio 1
	v_mfma_f32_16x16x32_bf16 v[50:53], v[154:157], v[170:173], v[50:53]
	v_mfma_f32_16x16x32_bf16 v[50:53], v[158:161], v[174:177], v[50:53]
	v_mfma_f32_16x16x32_bf16 v[54:57], v[162:165], v[170:173], v[54:57]
	v_mfma_f32_16x16x32_bf16 v[54:57], v[166:169], v[174:177], v[54:57]
	v_mfma_f32_16x16x32_bf16 v[34:37], v[154:157], v[178:181], v[34:37]
	v_mfma_f32_16x16x32_bf16 v[34:37], v[158:161], v[182:185], v[34:37]
	v_mfma_f32_16x16x32_bf16 v[38:41], v[162:165], v[178:181], v[38:41]
	v_mfma_f32_16x16x32_bf16 v[38:41], v[166:169], v[182:185], v[38:41]
	v_mfma_f32_16x16x32_bf16 v[18:21], v[154:157], v[186:189], v[18:21]
	v_mfma_f32_16x16x32_bf16 v[18:21], v[158:161], v[190:193], v[18:21]
	v_mfma_f32_16x16x32_bf16 v[22:25], v[162:165], v[186:189], v[22:25]
	v_mfma_f32_16x16x32_bf16 v[22:25], v[166:169], v[190:193], v[22:25]
	v_mfma_f32_16x16x32_bf16 v[2:5], v[154:157], v[198:201], v[2:5]
	v_mfma_f32_16x16x32_bf16 v[2:5], v[158:161], v[202:205], v[2:5]
	s_setprio 2
	s_barrier
	v_mfma_f32_16x16x32_bf16 v[6:9], v[162:165], v[198:201], v[6:9]
	v_mfma_f32_16x16x32_bf16 v[6:9], v[166:169], v[202:205], v[6:9]
	s_setprio 0
	s_nop 0
	ds_read_b128 v[130:133], v144
	ds_read_b128 v[134:137], v144 offset:1024
	ds_read_b128 v[146:149], v144 offset:2048
	ds_read_b128 v[150:153], v144 offset:3072
	ds_read_b128 v[154:157], v145
	ds_read_b128 v[158:161], v145 offset:1024
	ds_read_b128 v[162:165], v145 offset:2048
	ds_read_b128 v[166:169], v145 offset:3072
	ds_read_b128 v[170:173], v143 offset:32768
	ds_read_b128 v[174:177], v143 offset:33792
	ds_read_b128 v[178:181], v143 offset:34816
	ds_read_b128 v[182:185], v143 offset:35840
	ds_read_b128 v[186:189], v143 offset:36864
	ds_read_b128 v[190:193], v143 offset:37888
	ds_read_b128 v[198:201], v143 offset:38912
	ds_read_b128 v[202:205], v143 offset:39936
	s_add_u32 s26, s48, 0x4000
	s_addc_u32 s27, s49, 0
	s_mov_b32 m0, s63
	s_nop 0
	global_load_lds_dwordx4 v195, s[26:27]
	s_add_u32 m0, s63, 0x2000
	s_nop 0
	global_load_lds_dwordx4 v212, s[26:27]
	s_waitcnt vmcnt(8)
	s_waitcnt lgkmcnt(0)
	s_setprio 1
	s_barrier
	v_mfma_f32_16x16x32_bf16 v[122:125], v[130:133], v[170:173], v[122:125]
	v_mfma_f32_16x16x32_bf16 v[122:125], v[134:137], v[174:177], v[122:125]
	s_waitcnt lgkmcnt(5)
	v_mfma_f32_16x16x32_bf16 v[126:129], v[146:149], v[170:173], v[126:129]
	v_mfma_f32_16x16x32_bf16 v[126:129], v[150:153], v[174:177], v[126:129]
	s_waitcnt lgkmcnt(3)
	v_mfma_f32_16x16x32_bf16 v[110:113], v[130:133], v[178:181], v[110:113]
	v_mfma_f32_16x16x32_bf16 v[110:113], v[134:137], v[182:185], v[110:113]
	s_waitcnt lgkmcnt(1)
	v_mfma_f32_16x16x32_bf16 v[106:109], v[146:149], v[178:181], v[106:109]
	v_mfma_f32_16x16x32_bf16 v[106:109], v[150:153], v[182:185], v[106:109]
	v_mfma_f32_16x16x32_bf16 v[94:97], v[130:133], v[186:189], v[94:97]
	v_mfma_f32_16x16x32_bf16 v[94:97], v[134:137], v[190:193], v[94:97]
	v_mfma_f32_16x16x32_bf16 v[90:93], v[146:149], v[186:189], v[90:93]
	v_mfma_f32_16x16x32_bf16 v[90:93], v[150:153], v[190:193], v[90:93]
	v_mfma_f32_16x16x32_bf16 v[78:81], v[130:133], v[198:201], v[78:81]
	v_mfma_f32_16x16x32_bf16 v[78:81], v[134:137], v[202:205], v[78:81]
	s_waitcnt lgkmcnt(0)
	v_mfma_f32_16x16x32_bf16 v[74:77], v[146:149], v[198:201], v[74:77]
	v_mfma_f32_16x16x32_bf16 v[74:77], v[150:153], v[202:205], v[74:77]
	s_setprio 0
	s_setprio 1
	v_mfma_f32_16x16x32_bf16 v[114:117], v[154:157], v[170:173], v[114:117]
	v_mfma_f32_16x16x32_bf16 v[114:117], v[158:161], v[174:177], v[114:117]
	v_mfma_f32_16x16x32_bf16 v[118:121], v[162:165], v[170:173], v[118:121]
	v_mfma_f32_16x16x32_bf16 v[118:121], v[166:169], v[174:177], v[118:121]
	v_mfma_f32_16x16x32_bf16 v[98:101], v[154:157], v[178:181], v[98:101]
	v_mfma_f32_16x16x32_bf16 v[98:101], v[158:161], v[182:185], v[98:101]
	v_mfma_f32_16x16x32_bf16 v[102:105], v[162:165], v[178:181], v[102:105]
	v_mfma_f32_16x16x32_bf16 v[102:105], v[166:169], v[182:185], v[102:105]
	v_mfma_f32_16x16x32_bf16 v[82:85], v[154:157], v[186:189], v[82:85]
	v_mfma_f32_16x16x32_bf16 v[82:85], v[158:161], v[190:193], v[82:85]
	v_mfma_f32_16x16x32_bf16 v[86:89], v[162:165], v[186:189], v[86:89]
	v_mfma_f32_16x16x32_bf16 v[86:89], v[166:169], v[190:193], v[86:89]
	v_mfma_f32_16x16x32_bf16 v[66:69], v[154:157], v[198:201], v[66:69]
	v_mfma_f32_16x16x32_bf16 v[66:69], v[158:161], v[202:205], v[66:69]
	s_setprio 2
	s_barrier
	v_mfma_f32_16x16x32_bf16 v[70:73], v[162:165], v[198:201], v[70:73]
	v_mfma_f32_16x16x32_bf16 v[70:73], v[166:169], v[202:205], v[70:73]
	s_setprio 0
	s_nop 0
	ds_read_b128 v[170:173], v143 offset:49152
	ds_read_b128 v[174:177], v143 offset:50176
	ds_read_b128 v[178:181], v143 offset:51200
	ds_read_b128 v[182:185], v143 offset:52224
	ds_read_b128 v[186:189], v143 offset:53248
	ds_read_b128 v[190:193], v143 offset:54272
	ds_read_b128 v[198:201], v143 offset:55296
	ds_read_b128 v[202:205], v143 offset:56320
	s_mov_b32 m0, s69
	s_nop 0
	global_load_lds_dwordx4 v195, s[38:39]
	s_add_u32 m0, s69, 0x2000
	s_nop 0
	global_load_lds_dwordx4 v212, s[38:39]
	s_add_u32 s26, s30, 0xc000
	s_addc_u32 s27, s31, 0
	s_mov_b32 m0, s71
	s_nop 0
	global_load_lds_dwordx4 v195, s[26:27]
	s_add_u32 m0, s71, 0x2000
	s_nop 0
	global_load_lds_dwordx4 v212, s[26:27]
	s_nop 0
	s_mov_b32 m0, s70
	s_nop 0
	global_load_lds_dwordx4 v195, s[28:29]
	s_add_u32 m0, s70, 0x2000
	s_nop 0
	global_load_lds_dwordx4 v212, s[28:29]
	s_waitcnt vmcnt(8)
	s_waitcnt lgkmcnt(0)
	s_setprio 1
	s_barrier
	v_mfma_f32_16x16x32_bf16 v[62:65], v[130:133], v[170:173], v[62:65]
	v_mfma_f32_16x16x32_bf16 v[62:65], v[134:137], v[174:177], v[62:65]
	s_waitcnt lgkmcnt(5)
	v_mfma_f32_16x16x32_bf16 v[58:61], v[146:149], v[170:173], v[58:61]
	v_mfma_f32_16x16x32_bf16 v[58:61], v[150:153], v[174:177], v[58:61]
	s_waitcnt lgkmcnt(3)
	v_mfma_f32_16x16x32_bf16 v[46:49], v[130:133], v[178:181], v[46:49]
	v_mfma_f32_16x16x32_bf16 v[46:49], v[134:137], v[182:185], v[46:49]
	s_waitcnt lgkmcnt(1)
	v_mfma_f32_16x16x32_bf16 v[42:45], v[146:149], v[178:181], v[42:45]
	v_mfma_f32_16x16x32_bf16 v[42:45], v[150:153], v[182:185], v[42:45]
	v_mfma_f32_16x16x32_bf16 v[30:33], v[130:133], v[186:189], v[30:33]
	v_mfma_f32_16x16x32_bf16 v[30:33], v[134:137], v[190:193], v[30:33]
	v_mfma_f32_16x16x32_bf16 v[26:29], v[146:149], v[186:189], v[26:29]
	v_mfma_f32_16x16x32_bf16 v[26:29], v[150:153], v[190:193], v[26:29]
	v_mfma_f32_16x16x32_bf16 v[14:17], v[130:133], v[198:201], v[14:17]
	v_mfma_f32_16x16x32_bf16 v[14:17], v[134:137], v[202:205], v[14:17]
	s_waitcnt lgkmcnt(0)
	v_mfma_f32_16x16x32_bf16 v[10:13], v[146:149], v[198:201], v[10:13]
	v_mfma_f32_16x16x32_bf16 v[10:13], v[150:153], v[202:205], v[10:13]
	s_setprio 0
	s_setprio 1
	v_mfma_f32_16x16x32_bf16 v[50:53], v[154:157], v[170:173], v[50:53]
	v_mfma_f32_16x16x32_bf16 v[50:53], v[158:161], v[174:177], v[50:53]
	v_mfma_f32_16x16x32_bf16 v[54:57], v[162:165], v[170:173], v[54:57]
	v_mfma_f32_16x16x32_bf16 v[54:57], v[166:169], v[174:177], v[54:57]
	v_mfma_f32_16x16x32_bf16 v[34:37], v[154:157], v[178:181], v[34:37]
	v_mfma_f32_16x16x32_bf16 v[34:37], v[158:161], v[182:185], v[34:37]
	v_mfma_f32_16x16x32_bf16 v[38:41], v[162:165], v[178:181], v[38:41]
	v_mfma_f32_16x16x32_bf16 v[38:41], v[166:169], v[182:185], v[38:41]
	v_mfma_f32_16x16x32_bf16 v[18:21], v[154:157], v[186:189], v[18:21]
	v_mfma_f32_16x16x32_bf16 v[18:21], v[158:161], v[190:193], v[18:21]
	v_mfma_f32_16x16x32_bf16 v[22:25], v[162:165], v[186:189], v[22:25]
	v_mfma_f32_16x16x32_bf16 v[22:25], v[166:169], v[190:193], v[22:25]
	v_mfma_f32_16x16x32_bf16 v[2:5], v[154:157], v[198:201], v[2:5]
	v_mfma_f32_16x16x32_bf16 v[2:5], v[158:161], v[202:205], v[2:5]
	s_setprio 2
	s_barrier
	v_mfma_f32_16x16x32_bf16 v[6:9], v[162:165], v[198:201], v[6:9]
	v_mfma_f32_16x16x32_bf16 v[6:9], v[166:169], v[202:205], v[6:9]
	s_setprio 0
	s_nop 0
	s_add_i32 s77, s77, 2
	s_add_u32 s75, s75, 0x10000
	s_addc_u32 s76, s76, 0
	s_cmp_gt_u32 s77, 13
	s_mov_b64 s[26:27], s[24:25]
	s_cbranch_scc0 .LBB0_519
	s_and_b64 vcc, exec, s[10:11]
	s_cbranch_vccz .LBB0_522
	s_barrier
	s_setprio 1

.LBB0_635:
	s_add_u32 s28, s24, 0x10000
	s_addc_u32 s29, s25, 0
	s_and_b64 s[24:25], s[22:23], exec
	s_cselect_b32 s25, s29, s15
	s_cselect_b32 s24, s28, s33
	s_add_u32 s3, s52, s3
	s_addc_u32 s28, s53, 0
	s_add_u32 s3, s3, 0x10000
	s_waitcnt vmcnt(8)
	s_addc_u32 s28, s28, 0
	s_waitcnt lgkmcnt(0)
	s_and_b64 s[22:23], s[22:23], exec
	s_cselect_b32 s23, s28, s13
	s_cselect_b32 s22, s3, s70
	s_setprio 1
	s_barrier
	v_mfma_f32_16x16x32_bf16 v[126:129], v[146:149], v[186:189], v[126:129]
	v_mfma_f32_16x16x32_bf16 v[126:129], v[150:153], v[190:193], v[126:129]
	s_waitcnt lgkmcnt(5)
	v_mfma_f32_16x16x32_bf16 v[122:125], v[154:157], v[186:189], v[122:125]
	v_mfma_f32_16x16x32_bf16 v[122:125], v[158:161], v[190:193], v[122:125]
	s_waitcnt lgkmcnt(3)
	v_mfma_f32_16x16x32_bf16 v[118:121], v[146:149], v[178:181], v[118:121]
	v_mfma_f32_16x16x32_bf16 v[118:121], v[150:153], v[182:185], v[118:121]
	s_waitcnt lgkmcnt(1)
	v_mfma_f32_16x16x32_bf16 v[114:117], v[154:157], v[178:181], v[114:117]
	v_mfma_f32_16x16x32_bf16 v[114:117], v[158:161], v[182:185], v[114:117]
	v_mfma_f32_16x16x32_bf16 v[110:113], v[146:149], v[170:173], v[110:113]
	v_mfma_f32_16x16x32_bf16 v[110:113], v[150:153], v[174:177], v[110:113]
	v_mfma_f32_16x16x32_bf16 v[106:109], v[154:157], v[170:173], v[106:109]
	v_mfma_f32_16x16x32_bf16 v[106:109], v[158:161], v[174:177], v[106:109]
	v_mfma_f32_16x16x32_bf16 v[102:105], v[146:149], v[162:165], v[102:105]
	v_mfma_f32_16x16x32_bf16 v[102:105], v[150:153], v[166:169], v[102:105]
	s_waitcnt lgkmcnt(0)
	v_mfma_f32_16x16x32_bf16 v[98:101], v[154:157], v[162:165], v[98:101]
	v_mfma_f32_16x16x32_bf16 v[98:101], v[158:161], v[166:169], v[98:101]
	s_setprio 0
	s_setprio 1
	v_mfma_f32_16x16x32_bf16 v[94:97], v[130:133], v[186:189], v[94:97]
	v_mfma_f32_16x16x32_bf16 v[94:97], v[134:137], v[190:193], v[94:97]
	v_mfma_f32_16x16x32_bf16 v[90:93], v[138:141], v[186:189], v[90:93]
	v_mfma_f32_16x16x32_bf16 v[90:93], v[142:145], v[190:193], v[90:93]
	v_mfma_f32_16x16x32_bf16 v[86:89], v[130:133], v[178:181], v[86:89]
	v_mfma_f32_16x16x32_bf16 v[86:89], v[134:137], v[182:185], v[86:89]
	v_mfma_f32_16x16x32_bf16 v[82:85], v[138:141], v[178:181], v[82:85]
	v_mfma_f32_16x16x32_bf16 v[82:85], v[142:145], v[182:185], v[82:85]
	v_mfma_f32_16x16x32_bf16 v[78:81], v[130:133], v[170:173], v[78:81]
	v_mfma_f32_16x16x32_bf16 v[78:81], v[134:137], v[174:177], v[78:81]
	v_mfma_f32_16x16x32_bf16 v[74:77], v[138:141], v[170:173], v[74:77]
	v_mfma_f32_16x16x32_bf16 v[74:77], v[142:145], v[174:177], v[74:77]
	v_mfma_f32_16x16x32_bf16 v[70:73], v[130:133], v[162:165], v[70:73]
	v_mfma_f32_16x16x32_bf16 v[70:73], v[134:137], v[166:169], v[70:73]
	s_setprio 2
	s_barrier
	v_mfma_f32_16x16x32_bf16 v[66:69], v[138:141], v[162:165], v[66:69]
	v_mfma_f32_16x16x32_bf16 v[66:69], v[142:145], v[166:169], v[66:69]
	s_setprio 0
	s_nop 0
	ds_read_b128 v[186:189], v219 offset:16384
	ds_read_b128 v[190:193], v219 offset:17408
	ds_read_b128 v[178:181], v219 offset:18432
	ds_read_b128 v[182:185], v219 offset:19456
	ds_read_b128 v[170:173], v219 offset:20480
	ds_read_b128 v[174:177], v219 offset:21504
	ds_read_b128 v[162:165], v219 offset:22528
	ds_read_b128 v[166:169], v219 offset:23552
	s_mov_b32 m0, s89
	s_nop 0
	global_load_lds_dwordx4 v195, s[22:23]
	s_add_u32 m0, s89, 0x2000
	s_nop 0
	global_load_lds_dwordx4 v213, s[22:23]
	s_add_u32 s28, s22, 0x4000
	s_addc_u32 s29, s23, 0
	s_mov_b32 m0, s54
	s_nop 0
	global_load_lds_dwordx4 v195, s[28:29]
	s_add_u32 m0, s54, 0x2000
	s_nop 0
	global_load_lds_dwordx4 v213, s[28:29]
	s_andn2_b64 vcc, exec, s[26:27]
	s_mov_b32 m0, s39
	s_nop 0
	global_load_lds_dwordx4 v195, s[24:25]
	s_add_u32 m0, s39, 0x2000
	s_nop 0
	global_load_lds_dwordx4 v213, s[24:25]
	s_cbranch_vccnz .LBB0_637
	v_mov_b32_e32 v2, 0
	v_mov_b32_e32 v3, v2
	v_mov_b32_e32 v4, v2
	v_mov_b32_e32 v5, v2
	v_mov_b32_e32 v6, v2
	v_mov_b32_e32 v7, v2
	v_mov_b32_e32 v8, v2
	v_mov_b32_e32 v9, v2
	v_mov_b32_e32 v10, v2
	v_mov_b32_e32 v11, v2
	v_mov_b32_e32 v12, v2
	v_mov_b32_e32 v13, v2
	v_mov_b32_e32 v14, v2
	v_mov_b32_e32 v15, v2
	v_mov_b32_e32 v16, v2
	v_mov_b32_e32 v17, v2
	v_mov_b32_e32 v18, v2
	v_mov_b32_e32 v19, v2
	v_mov_b32_e32 v20, v2
	v_mov_b32_e32 v21, v2
	v_mov_b32_e32 v22, v2
	v_mov_b32_e32 v23, v2
	v_mov_b32_e32 v24, v2
	v_mov_b32_e32 v25, v2
	v_mov_b32_e32 v26, v2
	v_mov_b32_e32 v27, v2
	v_mov_b32_e32 v28, v2
	v_mov_b32_e32 v29, v2
	v_mov_b32_e32 v30, v2
	v_mov_b32_e32 v31, v2
	v_mov_b32_e32 v32, v2
	v_mov_b32_e32 v33, v2
	v_mov_b32_e32 v34, v2
	v_mov_b32_e32 v35, v2
	v_mov_b32_e32 v36, v2
	v_mov_b32_e32 v37, v2
	v_mov_b32_e32 v38, v2
	v_mov_b32_e32 v39, v2
	v_mov_b32_e32 v40, v2
	v_mov_b32_e32 v41, v2
	v_mov_b32_e32 v42, v2
	v_mov_b32_e32 v43, v2
	v_mov_b32_e32 v44, v2
	v_mov_b32_e32 v45, v2
	v_mov_b32_e32 v46, v2
	v_mov_b32_e32 v47, v2
	v_mov_b32_e32 v48, v2
	v_mov_b32_e32 v49, v2
	v_mov_b32_e32 v50, v2
	v_mov_b32_e32 v51, v2
	v_mov_b32_e32 v52, v2
	v_mov_b32_e32 v53, v2
	v_mov_b32_e32 v54, v2
	v_mov_b32_e32 v55, v2
	v_mov_b32_e32 v56, v2
	v_mov_b32_e32 v57, v2
	v_mov_b32_e32 v58, v2
	v_mov_b32_e32 v59, v2
	v_mov_b32_e32 v60, v2
	v_mov_b32_e32 v61, v2
	v_mov_b32_e32 v62, v2
	v_mov_b32_e32 v63, v2
	v_mov_b32_e32 v64, v2
	v_mov_b32_e32 v65, v2
.LBB0_637:
	s_waitcnt vmcnt(8)
	s_add_u32 s26, s24, 0x8000
	s_waitcnt lgkmcnt(0)
	s_addc_u32 s27, s25, 0
	s_add_u32 s28, s22, 0x8000
	s_addc_u32 s29, s23, 0
	s_setprio 1
	s_barrier
	v_mfma_f32_16x16x32_bf16 v[62:65], v[146:149], v[186:189], v[62:65]
	v_mfma_f32_16x16x32_bf16 v[62:65], v[150:153], v[190:193], v[62:65]
	s_waitcnt lgkmcnt(5)
	v_mfma_f32_16x16x32_bf16 v[58:61], v[154:157], v[186:189], v[58:61]
	v_mfma_f32_16x16x32_bf16 v[58:61], v[158:161], v[190:193], v[58:61]
	s_waitcnt lgkmcnt(3)
	v_mfma_f32_16x16x32_bf16 v[54:57], v[146:149], v[178:181], v[54:57]
	v_mfma_f32_16x16x32_bf16 v[54:57], v[150:153], v[182:185], v[54:57]
	s_waitcnt lgkmcnt(1)
	v_mfma_f32_16x16x32_bf16 v[50:53], v[154:157], v[178:181], v[50:53]
	v_mfma_f32_16x16x32_bf16 v[50:53], v[158:161], v[182:185], v[50:53]
	v_mfma_f32_16x16x32_bf16 v[46:49], v[146:149], v[170:173], v[46:49]
	v_mfma_f32_16x16x32_bf16 v[46:49], v[150:153], v[174:177], v[46:49]
	v_mfma_f32_16x16x32_bf16 v[42:45], v[154:157], v[170:173], v[42:45]
	v_mfma_f32_16x16x32_bf16 v[42:45], v[158:161], v[174:177], v[42:45]
	v_mfma_f32_16x16x32_bf16 v[38:41], v[146:149], v[162:165], v[38:41]
	v_mfma_f32_16x16x32_bf16 v[38:41], v[150:153], v[166:169], v[38:41]
	s_waitcnt lgkmcnt(0)
	v_mfma_f32_16x16x32_bf16 v[34:37], v[154:157], v[162:165], v[34:37]
	v_mfma_f32_16x16x32_bf16 v[34:37], v[158:161], v[166:169], v[34:37]
	s_setprio 0
	s_setprio 1
	v_mfma_f32_16x16x32_bf16 v[30:33], v[130:133], v[186:189], v[30:33]
	v_mfma_f32_16x16x32_bf16 v[30:33], v[134:137], v[190:193], v[30:33]
	v_mfma_f32_16x16x32_bf16 v[26:29], v[138:141], v[186:189], v[26:29]
	v_mfma_f32_16x16x32_bf16 v[26:29], v[142:145], v[190:193], v[26:29]
	v_mfma_f32_16x16x32_bf16 v[22:25], v[130:133], v[178:181], v[22:25]
	v_mfma_f32_16x16x32_bf16 v[22:25], v[134:137], v[182:185], v[22:25]
	v_mfma_f32_16x16x32_bf16 v[18:21], v[138:141], v[178:181], v[18:21]
	v_mfma_f32_16x16x32_bf16 v[18:21], v[142:145], v[182:185], v[18:21]
	v_mfma_f32_16x16x32_bf16 v[14:17], v[130:133], v[170:173], v[14:17]
	v_mfma_f32_16x16x32_bf16 v[14:17], v[134:137], v[174:177], v[14:17]
	v_mfma_f32_16x16x32_bf16 v[10:13], v[138:141], v[170:173], v[10:13]
	v_mfma_f32_16x16x32_bf16 v[10:13], v[142:145], v[174:177], v[10:13]
	v_mfma_f32_16x16x32_bf16 v[6:9], v[130:133], v[162:165], v[6:9]
	v_mfma_f32_16x16x32_bf16 v[6:9], v[134:137], v[166:169], v[6:9]
	s_setprio 2
	s_barrier
	v_mfma_f32_16x16x32_bf16 v[2:5], v[138:141], v[162:165], v[2:5]
	v_mfma_f32_16x16x32_bf16 v[2:5], v[142:145], v[166:169], v[2:5]
	s_setprio 0
	s_nop 0
	v_add_u32_e32 v142, 0x18000, v218
	v_add_u32_e32 v158, 0x1c000, v218
	ds_read_b128 v[130:133], v142
	ds_read_b128 v[134:137], v142 offset:1024
	ds_read_b128 v[138:141], v142 offset:2048
	ds_read_b128 v[142:145], v142 offset:3072
	ds_read_b128 v[146:149], v158
	ds_read_b128 v[150:153], v158 offset:1024
	ds_read_b128 v[154:157], v158 offset:2048
	ds_read_b128 v[158:161], v158 offset:3072
	ds_read_b128 v[162:165], v219 offset:32768
	ds_read_b128 v[166:169], v219 offset:33792
	ds_read_b128 v[170:173], v219 offset:34816
	ds_read_b128 v[174:177], v219 offset:35840
	ds_read_b128 v[178:181], v219 offset:36864
	ds_read_b128 v[182:185], v219 offset:37888
	ds_read_b128 v[186:189], v219 offset:38912
	ds_read_b128 v[190:193], v219 offset:39936
	s_add_u32 s24, s24, 0x4000
	s_addc_u32 s25, s25, 0
	s_mov_b32 m0, s55
	s_nop 0
	global_load_lds_dwordx4 v195, s[24:25]
	s_add_u32 m0, s55, 0x2000
	s_nop 0
	global_load_lds_dwordx4 v213, s[24:25]
	s_waitcnt vmcnt(8)
	s_waitcnt lgkmcnt(0)
	s_setprio 1
	s_barrier
	v_mfma_f32_16x16x32_bf16 v[126:129], v[130:133], v[162:165], v[126:129]
	v_mfma_f32_16x16x32_bf16 v[126:129], v[134:137], v[166:169], v[126:129]
	s_waitcnt lgkmcnt(5)
	v_mfma_f32_16x16x32_bf16 v[122:125], v[138:141], v[162:165], v[122:125]
	v_mfma_f32_16x16x32_bf16 v[122:125], v[142:145], v[166:169], v[122:125]
	s_waitcnt lgkmcnt(3)
	v_mfma_f32_16x16x32_bf16 v[118:121], v[130:133], v[170:173], v[118:121]
	v_mfma_f32_16x16x32_bf16 v[118:121], v[134:137], v[174:177], v[118:121]
	s_waitcnt lgkmcnt(1)
	v_mfma_f32_16x16x32_bf16 v[114:117], v[138:141], v[170:173], v[114:117]
	v_mfma_f32_16x16x32_bf16 v[114:117], v[142:145], v[174:177], v[114:117]
	v_mfma_f32_16x16x32_bf16 v[110:113], v[130:133], v[178:181], v[110:113]
	v_mfma_f32_16x16x32_bf16 v[110:113], v[134:137], v[182:185], v[110:113]
	v_mfma_f32_16x16x32_bf16 v[106:109], v[138:141], v[178:181], v[106:109]
	v_mfma_f32_16x16x32_bf16 v[106:109], v[142:145], v[182:185], v[106:109]
	v_mfma_f32_16x16x32_bf16 v[102:105], v[130:133], v[186:189], v[102:105]
	v_mfma_f32_16x16x32_bf16 v[102:105], v[134:137], v[190:193], v[102:105]
	s_waitcnt lgkmcnt(0)
	v_mfma_f32_16x16x32_bf16 v[98:101], v[138:141], v[186:189], v[98:101]
	v_mfma_f32_16x16x32_bf16 v[98:101], v[142:145], v[190:193], v[98:101]
	s_setprio 0
	s_setprio 1
	v_mfma_f32_16x16x32_bf16 v[94:97], v[146:149], v[162:165], v[94:97]
	v_mfma_f32_16x16x32_bf16 v[94:97], v[150:153], v[166:169], v[94:97]
	v_mfma_f32_16x16x32_bf16 v[90:93], v[154:157], v[162:165], v[90:93]
	v_mfma_f32_16x16x32_bf16 v[90:93], v[158:161], v[166:169], v[90:93]
	v_mfma_f32_16x16x32_bf16 v[86:89], v[146:149], v[170:173], v[86:89]
	v_mfma_f32_16x16x32_bf16 v[86:89], v[150:153], v[174:177], v[86:89]
	v_mfma_f32_16x16x32_bf16 v[82:85], v[154:157], v[170:173], v[82:85]
	v_mfma_f32_16x16x32_bf16 v[82:85], v[158:161], v[174:177], v[82:85]
	v_mfma_f32_16x16x32_bf16 v[78:81], v[146:149], v[178:181], v[78:81]
	v_mfma_f32_16x16x32_bf16 v[78:81], v[150:153], v[182:185], v[78:81]
	v_mfma_f32_16x16x32_bf16 v[74:77], v[154:157], v[178:181], v[74:77]
	v_mfma_f32_16x16x32_bf16 v[74:77], v[158:161], v[182:185], v[74:77]
	v_mfma_f32_16x16x32_bf16 v[70:73], v[146:149], v[186:189], v[70:73]
	v_mfma_f32_16x16x32_bf16 v[70:73], v[150:153], v[190:193], v[70:73]
	s_setprio 2
	s_barrier
	v_mfma_f32_16x16x32_bf16 v[66:69], v[154:157], v[186:189], v[66:69]
	v_mfma_f32_16x16x32_bf16 v[66:69], v[158:161], v[190:193], v[66:69]
	s_setprio 0
	s_nop 0
	ds_read_b128 v[162:165], v219 offset:49152
	ds_read_b128 v[166:169], v219 offset:50176
	ds_read_b128 v[170:173], v219 offset:51200
	ds_read_b128 v[174:177], v219 offset:52224
	ds_read_b128 v[178:181], v219 offset:53248
	ds_read_b128 v[182:185], v219 offset:54272
	ds_read_b128 v[186:189], v219 offset:55296
	ds_read_b128 v[190:193], v219 offset:56320
	s_mov_b32 m0, s83
	s_nop 0
	global_load_lds_dwordx4 v195, s[28:29]
	s_add_u32 m0, s83, 0x2000
	s_nop 0
	global_load_lds_dwordx4 v213, s[28:29]
	s_add_u32 s22, s22, 0xc000
	s_addc_u32 s23, s23, 0
	s_mov_b32 m0, s91
	s_nop 0
	global_load_lds_dwordx4 v195, s[22:23]
	s_add_u32 m0, s91, 0x2000
	s_nop 0
	global_load_lds_dwordx4 v213, s[22:23]
	s_nop 0
	s_mov_b32 m0, s90
	s_nop 0
	global_load_lds_dwordx4 v195, s[26:27]
	s_add_u32 m0, s90, 0x2000
	s_nop 0
	global_load_lds_dwordx4 v213, s[26:27]
	s_waitcnt vmcnt(8)
	s_waitcnt lgkmcnt(0)
	s_setprio 1
	s_barrier
	v_mfma_f32_16x16x32_bf16 v[62:65], v[130:133], v[162:165], v[62:65]
	v_mfma_f32_16x16x32_bf16 v[62:65], v[134:137], v[166:169], v[62:65]
	s_waitcnt lgkmcnt(5)
	v_mfma_f32_16x16x32_bf16 v[58:61], v[138:141], v[162:165], v[58:61]
	v_mfma_f32_16x16x32_bf16 v[58:61], v[142:145], v[166:169], v[58:61]
	s_waitcnt lgkmcnt(3)
	v_mfma_f32_16x16x32_bf16 v[54:57], v[130:133], v[170:173], v[54:57]
	v_mfma_f32_16x16x32_bf16 v[54:57], v[134:137], v[174:177], v[54:57]
	s_waitcnt lgkmcnt(1)
	v_mfma_f32_16x16x32_bf16 v[50:53], v[138:141], v[170:173], v[50:53]
	v_mfma_f32_16x16x32_bf16 v[50:53], v[142:145], v[174:177], v[50:53]
	v_mfma_f32_16x16x32_bf16 v[46:49], v[130:133], v[178:181], v[46:49]
	v_mfma_f32_16x16x32_bf16 v[46:49], v[134:137], v[182:185], v[46:49]
	v_mfma_f32_16x16x32_bf16 v[42:45], v[138:141], v[178:181], v[42:45]
	v_mfma_f32_16x16x32_bf16 v[42:45], v[142:145], v[182:185], v[42:45]
	v_mfma_f32_16x16x32_bf16 v[38:41], v[130:133], v[186:189], v[38:41]
	v_mfma_f32_16x16x32_bf16 v[38:41], v[134:137], v[190:193], v[38:41]
	s_waitcnt lgkmcnt(0)
	v_mfma_f32_16x16x32_bf16 v[34:37], v[138:141], v[186:189], v[34:37]
	v_mfma_f32_16x16x32_bf16 v[34:37], v[142:145], v[190:193], v[34:37]
	s_setprio 0
	s_setprio 1
	v_mfma_f32_16x16x32_bf16 v[30:33], v[146:149], v[162:165], v[30:33]
	v_mfma_f32_16x16x32_bf16 v[30:33], v[150:153], v[166:169], v[30:33]
	v_mfma_f32_16x16x32_bf16 v[26:29], v[154:157], v[162:165], v[26:29]
	v_mfma_f32_16x16x32_bf16 v[26:29], v[158:161], v[166:169], v[26:29]
	v_mfma_f32_16x16x32_bf16 v[22:25], v[146:149], v[170:173], v[22:25]
	v_mfma_f32_16x16x32_bf16 v[22:25], v[150:153], v[174:177], v[22:25]
	v_mfma_f32_16x16x32_bf16 v[18:21], v[154:157], v[170:173], v[18:21]
	v_mfma_f32_16x16x32_bf16 v[18:21], v[158:161], v[174:177], v[18:21]
	v_mfma_f32_16x16x32_bf16 v[14:17], v[146:149], v[178:181], v[14:17]
	v_mfma_f32_16x16x32_bf16 v[14:17], v[150:153], v[182:185], v[14:17]
	v_mfma_f32_16x16x32_bf16 v[10:13], v[154:157], v[178:181], v[10:13]
	v_mfma_f32_16x16x32_bf16 v[10:13], v[158:161], v[182:185], v[10:13]
	v_mfma_f32_16x16x32_bf16 v[6:9], v[146:149], v[186:189], v[6:9]
	v_mfma_f32_16x16x32_bf16 v[6:9], v[150:153], v[190:193], v[6:9]
	s_setprio 2
	s_barrier
	v_mfma_f32_16x16x32_bf16 v[2:5], v[154:157], v[186:189], v[2:5]
	v_mfma_f32_16x16x32_bf16 v[2:5], v[158:161], v[190:193], v[2:5]
	s_setprio 0
	s_nop 0
	s_add_i32 s3, s71, 2
	s_cmp_gt_u32 s71, 13
	s_cbranch_scc1 .LBB0_639
	s_mov_b32 s71, s3
	s_branch .LBB0_616

.LBB0_1068:
	s_or_b64 exec, exec, s[62:63]
	s_add_u32 s88, s12, s0
	ds_read_b128 v[132:135], v214
	ds_read_b128 v[136:139], v214 offset:1024
	ds_read_b128 v[140:143], v214 offset:2048
	ds_read_b128 v[144:147], v214 offset:3072
	ds_read_b128 v[154:157], v215
	ds_read_b128 v[158:161], v215 offset:1024
	ds_read_b128 v[162:165], v215 offset:2048
	ds_read_b128 v[166:169], v215 offset:3072
	s_addc_u32 s89, s13, s1
	s_add_u32 s62, s88, 0x20000
	s_addc_u32 s63, s89, 0
	s_add_u32 s64, s94, s0
	s_addc_u32 s65, s96, s1
	s_cmp_eq_u32 s0, 0x60000
	s_cselect_b32 s68, s53, s62
	s_cselect_b32 s69, s33, s63
	s_cselect_b32 s63, s51, s65
	s_cselect_b32 s62, s95, s64
	s_add_u32 s64, s68, 0x8000
	s_addc_u32 s65, s69, 0
	s_add_u32 s66, s62, 0x8000
	s_addc_u32 s67, s63, 0
	ds_read_b128 v[170:173], v216
	ds_read_b128 v[174:177], v216 offset:1024
	ds_read_b128 v[178:181], v216 offset:2048
	ds_read_b128 v[182:185], v216 offset:3072
	ds_read_b128 v[186:189], v216 offset:4096
	ds_read_b128 v[190:193], v216 offset:5120
	ds_read_b128 v[198:201], v216 offset:6144
	ds_read_b128 v[202:205], v216 offset:7168
	s_add_u32 s88, s88, 0x1c000
	s_addc_u32 s89, s89, 0
	s_mov_b32 m0, s79
	s_nop 0
	global_load_lds_dwordx4 v195, s[88:89]
	s_add_u32 m0, s79, 0x2000
	s_nop 0
	global_load_lds_dwordx4 v212, s[88:89]
	s_waitcnt vmcnt(8)
	s_waitcnt lgkmcnt(0)
	s_setprio 1
	s_barrier
	v_mfma_f32_16x16x32_bf16 v[126:129], v[132:135], v[170:173], v[126:129]
	v_mfma_f32_16x16x32_bf16 v[126:129], v[136:139], v[174:177], v[126:129]
	s_waitcnt lgkmcnt(5)
	v_mfma_f32_16x16x32_bf16 v[122:125], v[140:143], v[170:173], v[122:125]
	v_mfma_f32_16x16x32_bf16 v[122:125], v[144:147], v[174:177], v[122:125]
	s_waitcnt lgkmcnt(3)
	v_mfma_f32_16x16x32_bf16 v[110:113], v[132:135], v[178:181], v[110:113]
	v_mfma_f32_16x16x32_bf16 v[110:113], v[136:139], v[182:185], v[110:113]
	s_waitcnt lgkmcnt(1)
	v_mfma_f32_16x16x32_bf16 v[106:109], v[140:143], v[178:181], v[106:109]
	v_mfma_f32_16x16x32_bf16 v[106:109], v[144:147], v[182:185], v[106:109]
	v_mfma_f32_16x16x32_bf16 v[94:97], v[132:135], v[186:189], v[94:97]
	v_mfma_f32_16x16x32_bf16 v[94:97], v[136:139], v[190:193], v[94:97]
	v_mfma_f32_16x16x32_bf16 v[90:93], v[140:143], v[186:189], v[90:93]
	v_mfma_f32_16x16x32_bf16 v[90:93], v[144:147], v[190:193], v[90:93]
	v_mfma_f32_16x16x32_bf16 v[78:81], v[132:135], v[198:201], v[78:81]
	v_mfma_f32_16x16x32_bf16 v[78:81], v[136:139], v[202:205], v[78:81]
	s_waitcnt lgkmcnt(0)
	v_mfma_f32_16x16x32_bf16 v[74:77], v[140:143], v[198:201], v[74:77]
	v_mfma_f32_16x16x32_bf16 v[74:77], v[144:147], v[202:205], v[74:77]
	s_setprio 0
	s_setprio 1
	v_mfma_f32_16x16x32_bf16 v[118:121], v[154:157], v[170:173], v[118:121]
	v_mfma_f32_16x16x32_bf16 v[118:121], v[158:161], v[174:177], v[118:121]
	v_mfma_f32_16x16x32_bf16 v[114:117], v[162:165], v[170:173], v[114:117]
	v_mfma_f32_16x16x32_bf16 v[114:117], v[166:169], v[174:177], v[114:117]
	v_mfma_f32_16x16x32_bf16 v[102:105], v[154:157], v[178:181], v[102:105]
	v_mfma_f32_16x16x32_bf16 v[102:105], v[158:161], v[182:185], v[102:105]
	v_mfma_f32_16x16x32_bf16 v[98:101], v[162:165], v[178:181], v[98:101]
	v_mfma_f32_16x16x32_bf16 v[98:101], v[166:169], v[182:185], v[98:101]
	v_mfma_f32_16x16x32_bf16 v[86:89], v[154:157], v[186:189], v[86:89]
	v_mfma_f32_16x16x32_bf16 v[86:89], v[158:161], v[190:193], v[86:89]
	v_mfma_f32_16x16x32_bf16 v[82:85], v[162:165], v[186:189], v[82:85]
	v_mfma_f32_16x16x32_bf16 v[82:85], v[166:169], v[190:193], v[82:85]
	v_mfma_f32_16x16x32_bf16 v[70:73], v[154:157], v[198:201], v[70:73]
	v_mfma_f32_16x16x32_bf16 v[70:73], v[158:161], v[202:205], v[70:73]
	s_setprio 2
	s_barrier
	v_mfma_f32_16x16x32_bf16 v[66:69], v[162:165], v[198:201], v[66:69]
	v_mfma_f32_16x16x32_bf16 v[66:69], v[166:169], v[202:205], v[66:69]
	s_setprio 0
	s_nop 0
	ds_read_b128 v[170:173], v216 offset:16384
	ds_read_b128 v[174:177], v216 offset:17408
	ds_read_b128 v[178:181], v216 offset:18432
	ds_read_b128 v[182:185], v216 offset:19456
	ds_read_b128 v[186:189], v216 offset:20480
	ds_read_b128 v[190:193], v216 offset:21504
	ds_read_b128 v[198:201], v216 offset:22528
	ds_read_b128 v[202:205], v216 offset:23552
	s_mov_b32 m0, s3
	s_nop 0
	global_load_lds_dwordx4 v195, s[62:63]
	s_add_u32 m0, s3, 0x2000
	s_nop 0
	global_load_lds_dwordx4 v212, s[62:63]
	s_add_u32 s88, s62, 0x4000
	s_addc_u32 s89, s63, 0
	s_mov_b32 m0, s71
	s_nop 0
	global_load_lds_dwordx4 v195, s[88:89]
	s_add_u32 m0, s71, 0x2000
	s_nop 0
	global_load_lds_dwordx4 v212, s[88:89]
	s_nop 0
	s_mov_b32 m0, s70
	s_nop 0
	global_load_lds_dwordx4 v195, s[68:69]
	s_add_u32 m0, s70, 0x2000
	s_nop 0
	global_load_lds_dwordx4 v212, s[68:69]
	s_waitcnt vmcnt(8)
	s_waitcnt lgkmcnt(0)
	s_setprio 1
	s_barrier
	v_mfma_f32_16x16x32_bf16 v[62:65], v[132:135], v[170:173], v[62:65]
	v_mfma_f32_16x16x32_bf16 v[62:65], v[136:139], v[174:177], v[62:65]
	s_waitcnt lgkmcnt(5)
	v_mfma_f32_16x16x32_bf16 v[58:61], v[140:143], v[170:173], v[58:61]
	v_mfma_f32_16x16x32_bf16 v[58:61], v[144:147], v[174:177], v[58:61]
	s_waitcnt lgkmcnt(3)
	v_mfma_f32_16x16x32_bf16 v[46:49], v[132:135], v[178:181], v[46:49]
	v_mfma_f32_16x16x32_bf16 v[46:49], v[136:139], v[182:185], v[46:49]
	s_waitcnt lgkmcnt(1)
	v_mfma_f32_16x16x32_bf16 v[42:45], v[140:143], v[178:181], v[42:45]
	v_mfma_f32_16x16x32_bf16 v[42:45], v[144:147], v[182:185], v[42:45]
	v_mfma_f32_16x16x32_bf16 v[30:33], v[132:135], v[186:189], v[30:33]
	v_mfma_f32_16x16x32_bf16 v[30:33], v[136:139], v[190:193], v[30:33]
	v_mfma_f32_16x16x32_bf16 v[26:29], v[140:143], v[186:189], v[26:29]
	v_mfma_f32_16x16x32_bf16 v[26:29], v[144:147], v[190:193], v[26:29]
	v_mfma_f32_16x16x32_bf16 v[14:17], v[132:135], v[198:201], v[14:17]
	v_mfma_f32_16x16x32_bf16 v[14:17], v[136:139], v[202:205], v[14:17]
	s_waitcnt lgkmcnt(0)
	v_mfma_f32_16x16x32_bf16 v[10:13], v[140:143], v[198:201], v[10:13]
	v_mfma_f32_16x16x32_bf16 v[10:13], v[144:147], v[202:205], v[10:13]
	s_setprio 0
	s_setprio 1
	v_mfma_f32_16x16x32_bf16 v[54:57], v[154:157], v[170:173], v[54:57]
	v_mfma_f32_16x16x32_bf16 v[54:57], v[158:161], v[174:177], v[54:57]
	v_mfma_f32_16x16x32_bf16 v[50:53], v[162:165], v[170:173], v[50:53]
	v_mfma_f32_16x16x32_bf16 v[50:53], v[166:169], v[174:177], v[50:53]
	v_mfma_f32_16x16x32_bf16 v[38:41], v[154:157], v[178:181], v[38:41]
	v_mfma_f32_16x16x32_bf16 v[38:41], v[158:161], v[182:185], v[38:41]
	v_mfma_f32_16x16x32_bf16 v[34:37], v[162:165], v[178:181], v[34:37]
	v_mfma_f32_16x16x32_bf16 v[34:37], v[166:169], v[182:185], v[34:37]
	v_mfma_f32_16x16x32_bf16 v[22:25], v[154:157], v[186:189], v[22:25]
	v_mfma_f32_16x16x32_bf16 v[22:25], v[158:161], v[190:193], v[22:25]
	v_mfma_f32_16x16x32_bf16 v[18:21], v[162:165], v[186:189], v[18:21]
	v_mfma_f32_16x16x32_bf16 v[18:21], v[166:169], v[190:193], v[18:21]
	v_mfma_f32_16x16x32_bf16 v[6:9], v[154:157], v[198:201], v[6:9]
	v_mfma_f32_16x16x32_bf16 v[6:9], v[158:161], v[202:205], v[6:9]
	s_setprio 2
	s_barrier
	v_mfma_f32_16x16x32_bf16 v[2:5], v[162:165], v[198:201], v[2:5]
	v_mfma_f32_16x16x32_bf16 v[2:5], v[166:169], v[202:205], v[2:5]
	s_setprio 0
	s_nop 0
	ds_read_b128 v[132:135], v217
	ds_read_b128 v[136:139], v217 offset:1024
	ds_read_b128 v[140:143], v217 offset:2048
	ds_read_b128 v[144:147], v217 offset:3072
	ds_read_b128 v[154:157], v218
	ds_read_b128 v[158:161], v218 offset:1024
	ds_read_b128 v[162:165], v218 offset:2048
	ds_read_b128 v[166:169], v218 offset:3072
	ds_read_b128 v[170:173], v216 offset:32768
	ds_read_b128 v[174:177], v216 offset:33792
	ds_read_b128 v[178:181], v216 offset:34816
	ds_read_b128 v[182:185], v216 offset:35840
	ds_read_b128 v[186:189], v216 offset:36864
	ds_read_b128 v[190:193], v216 offset:37888
	ds_read_b128 v[198:201], v216 offset:38912
	ds_read_b128 v[202:205], v216 offset:39936
	s_add_u32 s68, s68, 0x4000
	s_addc_u32 s69, s69, 0
	s_mov_b32 m0, s72
	s_nop 0
	global_load_lds_dwordx4 v195, s[68:69]
	s_add_u32 m0, s72, 0x2000
	s_nop 0
	global_load_lds_dwordx4 v212, s[68:69]
	s_waitcnt vmcnt(8)
	s_waitcnt lgkmcnt(0)
	s_setprio 1
	s_barrier
	v_mfma_f32_16x16x32_bf16 v[126:129], v[132:135], v[170:173], v[126:129]
	v_mfma_f32_16x16x32_bf16 v[126:129], v[136:139], v[174:177], v[126:129]
	s_waitcnt lgkmcnt(5)
	v_mfma_f32_16x16x32_bf16 v[122:125], v[140:143], v[170:173], v[122:125]
	v_mfma_f32_16x16x32_bf16 v[122:125], v[144:147], v[174:177], v[122:125]
	s_waitcnt lgkmcnt(3)
	v_mfma_f32_16x16x32_bf16 v[110:113], v[132:135], v[178:181], v[110:113]
	v_mfma_f32_16x16x32_bf16 v[110:113], v[136:139], v[182:185], v[110:113]
	s_waitcnt lgkmcnt(1)
	v_mfma_f32_16x16x32_bf16 v[106:109], v[140:143], v[178:181], v[106:109]
	v_mfma_f32_16x16x32_bf16 v[106:109], v[144:147], v[182:185], v[106:109]
	v_mfma_f32_16x16x32_bf16 v[94:97], v[132:135], v[186:189], v[94:97]
	v_mfma_f32_16x16x32_bf16 v[94:97], v[136:139], v[190:193], v[94:97]
	v_mfma_f32_16x16x32_bf16 v[90:93], v[140:143], v[186:189], v[90:93]
	v_mfma_f32_16x16x32_bf16 v[90:93], v[144:147], v[190:193], v[90:93]
	v_mfma_f32_16x16x32_bf16 v[78:81], v[132:135], v[198:201], v[78:81]
	v_mfma_f32_16x16x32_bf16 v[78:81], v[136:139], v[202:205], v[78:81]
	s_waitcnt lgkmcnt(0)
	v_mfma_f32_16x16x32_bf16 v[74:77], v[140:143], v[198:201], v[74:77]
	v_mfma_f32_16x16x32_bf16 v[74:77], v[144:147], v[202:205], v[74:77]
	s_setprio 0
	s_setprio 1
	v_mfma_f32_16x16x32_bf16 v[118:121], v[154:157], v[170:173], v[118:121]
	v_mfma_f32_16x16x32_bf16 v[118:121], v[158:161], v[174:177], v[118:121]
	v_mfma_f32_16x16x32_bf16 v[114:117], v[162:165], v[170:173], v[114:117]
	v_mfma_f32_16x16x32_bf16 v[114:117], v[166:169], v[174:177], v[114:117]
	v_mfma_f32_16x16x32_bf16 v[102:105], v[154:157], v[178:181], v[102:105]
	v_mfma_f32_16x16x32_bf16 v[102:105], v[158:161], v[182:185], v[102:105]
	v_mfma_f32_16x16x32_bf16 v[98:101], v[162:165], v[178:181], v[98:101]
	v_mfma_f32_16x16x32_bf16 v[98:101], v[166:169], v[182:185], v[98:101]
	v_mfma_f32_16x16x32_bf16 v[86:89], v[154:157], v[186:189], v[86:89]
	v_mfma_f32_16x16x32_bf16 v[86:89], v[158:161], v[190:193], v[86:89]
	v_mfma_f32_16x16x32_bf16 v[82:85], v[162:165], v[186:189], v[82:85]
	v_mfma_f32_16x16x32_bf16 v[82:85], v[166:169], v[190:193], v[82:85]
	v_mfma_f32_16x16x32_bf16 v[70:73], v[154:157], v[198:201], v[70:73]
	v_mfma_f32_16x16x32_bf16 v[70:73], v[158:161], v[202:205], v[70:73]
	s_setprio 2
	s_barrier
	v_mfma_f32_16x16x32_bf16 v[66:69], v[162:165], v[198:201], v[66:69]
	v_mfma_f32_16x16x32_bf16 v[66:69], v[166:169], v[202:205], v[66:69]
	s_setprio 0
	s_nop 0
	ds_read_b128 v[170:173], v216 offset:49152
	ds_read_b128 v[174:177], v216 offset:50176
	ds_read_b128 v[178:181], v216 offset:51200
	ds_read_b128 v[182:185], v216 offset:52224
	ds_read_b128 v[186:189], v216 offset:53248
	ds_read_b128 v[190:193], v216 offset:54272
	ds_read_b128 v[198:201], v216 offset:55296
	ds_read_b128 v[202:205], v216 offset:56320
	s_mov_b32 m0, s76
	s_nop 0
	global_load_lds_dwordx4 v195, s[66:67]
	s_add_u32 m0, s76, 0x2000
	s_nop 0
	global_load_lds_dwordx4 v212, s[66:67]
	s_add_u32 s62, s62, 0xc000
	s_addc_u32 s63, s63, 0
	s_mov_b32 m0, s78
	s_nop 0
	global_load_lds_dwordx4 v195, s[62:63]
	s_add_u32 m0, s78, 0x2000
	s_nop 0
	global_load_lds_dwordx4 v212, s[62:63]
	s_nop 0
	s_mov_b32 m0, s77
	s_nop 0
	global_load_lds_dwordx4 v195, s[64:65]
	s_add_u32 m0, s77, 0x2000
	s_nop 0
	global_load_lds_dwordx4 v212, s[64:65]
	s_waitcnt vmcnt(8)
	s_waitcnt lgkmcnt(0)
	s_setprio 1
	s_barrier
	v_mfma_f32_16x16x32_bf16 v[62:65], v[132:135], v[170:173], v[62:65]
	v_mfma_f32_16x16x32_bf16 v[62:65], v[136:139], v[174:177], v[62:65]
	s_waitcnt lgkmcnt(5)
	v_mfma_f32_16x16x32_bf16 v[58:61], v[140:143], v[170:173], v[58:61]
	v_mfma_f32_16x16x32_bf16 v[58:61], v[144:147], v[174:177], v[58:61]
	s_waitcnt lgkmcnt(3)
	v_mfma_f32_16x16x32_bf16 v[46:49], v[132:135], v[178:181], v[46:49]
	v_mfma_f32_16x16x32_bf16 v[46:49], v[136:139], v[182:185], v[46:49]
	s_waitcnt lgkmcnt(1)
	v_mfma_f32_16x16x32_bf16 v[42:45], v[140:143], v[178:181], v[42:45]
	v_mfma_f32_16x16x32_bf16 v[42:45], v[144:147], v[182:185], v[42:45]
	v_mfma_f32_16x16x32_bf16 v[30:33], v[132:135], v[186:189], v[30:33]
	v_mfma_f32_16x16x32_bf16 v[30:33], v[136:139], v[190:193], v[30:33]
	v_mfma_f32_16x16x32_bf16 v[26:29], v[140:143], v[186:189], v[26:29]
	v_mfma_f32_16x16x32_bf16 v[26:29], v[144:147], v[190:193], v[26:29]
	v_mfma_f32_16x16x32_bf16 v[14:17], v[132:135], v[198:201], v[14:17]
	v_mfma_f32_16x16x32_bf16 v[14:17], v[136:139], v[202:205], v[14:17]
	s_waitcnt lgkmcnt(0)
	v_mfma_f32_16x16x32_bf16 v[10:13], v[140:143], v[198:201], v[10:13]
	v_mfma_f32_16x16x32_bf16 v[10:13], v[144:147], v[202:205], v[10:13]
	s_setprio 0
	s_setprio 1
	v_mfma_f32_16x16x32_bf16 v[54:57], v[154:157], v[170:173], v[54:57]
	v_mfma_f32_16x16x32_bf16 v[54:57], v[158:161], v[174:177], v[54:57]
	v_mfma_f32_16x16x32_bf16 v[50:53], v[162:165], v[170:173], v[50:53]
	v_mfma_f32_16x16x32_bf16 v[50:53], v[166:169], v[174:177], v[50:53]
	v_mfma_f32_16x16x32_bf16 v[38:41], v[154:157], v[178:181], v[38:41]
	v_mfma_f32_16x16x32_bf16 v[38:41], v[158:161], v[182:185], v[38:41]
	v_mfma_f32_16x16x32_bf16 v[34:37], v[162:165], v[178:181], v[34:37]
	v_mfma_f32_16x16x32_bf16 v[34:37], v[166:169], v[182:185], v[34:37]
	v_mfma_f32_16x16x32_bf16 v[22:25], v[154:157], v[186:189], v[22:25]
	v_mfma_f32_16x16x32_bf16 v[22:25], v[158:161], v[190:193], v[22:25]
	v_mfma_f32_16x16x32_bf16 v[18:21], v[162:165], v[186:189], v[18:21]
	v_mfma_f32_16x16x32_bf16 v[18:21], v[166:169], v[190:193], v[18:21]
	v_mfma_f32_16x16x32_bf16 v[6:9], v[154:157], v[198:201], v[6:9]
	v_mfma_f32_16x16x32_bf16 v[6:9], v[158:161], v[202:205], v[6:9]
	s_setprio 2
	s_barrier
	v_mfma_f32_16x16x32_bf16 v[2:5], v[162:165], v[198:201], v[2:5]
	v_mfma_f32_16x16x32_bf16 v[2:5], v[166:169], v[202:205], v[2:5]
	s_setprio 0
	s_nop 0
	s_add_i32 s97, s97, 2
	s_add_u32 s0, s0, 0x10000
	s_addc_u32 s1, s1, 0
	s_cmp_gt_u32 s97, 13
	s_cbranch_scc1 .LBB0_1070
	v_mov_b32_e32 v131, v130
	s_branch .LBB0_1066

.LBB0_1336:
	s_add_u32 s50, s46, 0x10000
	s_addc_u32 s51, s47, 0
	s_and_b64 s[46:47], s[42:43], exec
	s_cselect_b32 s47, s51, s23
	s_cselect_b32 s46, s50, s75
	s_add_u32 s13, s16, s13
	s_addc_u32 s50, s17, 0
	s_add_u32 s13, s13, 0x10000
	s_waitcnt vmcnt(8)
	s_addc_u32 s50, s50, 0
	s_waitcnt lgkmcnt(0)
	s_and_b64 s[42:43], s[42:43], exec
	s_cselect_b32 s43, s50, s25
	s_cselect_b32 s42, s13, s76
	s_setprio 1
	s_barrier
	v_mfma_f32_16x16x32_bf16 v[126:129], v[146:149], v[186:189], v[126:129]
	v_mfma_f32_16x16x32_bf16 v[126:129], v[150:153], v[190:193], v[126:129]
	s_waitcnt lgkmcnt(5)
	v_mfma_f32_16x16x32_bf16 v[122:125], v[154:157], v[186:189], v[122:125]
	v_mfma_f32_16x16x32_bf16 v[122:125], v[158:161], v[190:193], v[122:125]
	s_waitcnt lgkmcnt(3)
	v_mfma_f32_16x16x32_bf16 v[118:121], v[146:149], v[178:181], v[118:121]
	v_mfma_f32_16x16x32_bf16 v[118:121], v[150:153], v[182:185], v[118:121]
	s_waitcnt lgkmcnt(1)
	v_mfma_f32_16x16x32_bf16 v[114:117], v[154:157], v[178:181], v[114:117]
	v_mfma_f32_16x16x32_bf16 v[114:117], v[158:161], v[182:185], v[114:117]
	v_mfma_f32_16x16x32_bf16 v[110:113], v[146:149], v[170:173], v[110:113]
	v_mfma_f32_16x16x32_bf16 v[110:113], v[150:153], v[174:177], v[110:113]
	v_mfma_f32_16x16x32_bf16 v[106:109], v[154:157], v[170:173], v[106:109]
	v_mfma_f32_16x16x32_bf16 v[106:109], v[158:161], v[174:177], v[106:109]
	v_mfma_f32_16x16x32_bf16 v[102:105], v[146:149], v[162:165], v[102:105]
	v_mfma_f32_16x16x32_bf16 v[102:105], v[150:153], v[166:169], v[102:105]
	s_waitcnt lgkmcnt(0)
	v_mfma_f32_16x16x32_bf16 v[98:101], v[154:157], v[162:165], v[98:101]
	v_mfma_f32_16x16x32_bf16 v[98:101], v[158:161], v[166:169], v[98:101]
	s_setprio 0
	s_setprio 1
	v_mfma_f32_16x16x32_bf16 v[94:97], v[130:133], v[186:189], v[94:97]
	v_mfma_f32_16x16x32_bf16 v[94:97], v[134:137], v[190:193], v[94:97]
	v_mfma_f32_16x16x32_bf16 v[90:93], v[138:141], v[186:189], v[90:93]
	v_mfma_f32_16x16x32_bf16 v[90:93], v[142:145], v[190:193], v[90:93]
	v_mfma_f32_16x16x32_bf16 v[86:89], v[130:133], v[178:181], v[86:89]
	v_mfma_f32_16x16x32_bf16 v[86:89], v[134:137], v[182:185], v[86:89]
	v_mfma_f32_16x16x32_bf16 v[82:85], v[138:141], v[178:181], v[82:85]
	v_mfma_f32_16x16x32_bf16 v[82:85], v[142:145], v[182:185], v[82:85]
	v_mfma_f32_16x16x32_bf16 v[78:81], v[130:133], v[170:173], v[78:81]
	v_mfma_f32_16x16x32_bf16 v[78:81], v[134:137], v[174:177], v[78:81]
	v_mfma_f32_16x16x32_bf16 v[74:77], v[138:141], v[170:173], v[74:77]
	v_mfma_f32_16x16x32_bf16 v[74:77], v[142:145], v[174:177], v[74:77]
	v_mfma_f32_16x16x32_bf16 v[70:73], v[130:133], v[162:165], v[70:73]
	v_mfma_f32_16x16x32_bf16 v[70:73], v[134:137], v[166:169], v[70:73]
	s_setprio 2
	s_barrier
	v_mfma_f32_16x16x32_bf16 v[66:69], v[138:141], v[162:165], v[66:69]
	v_mfma_f32_16x16x32_bf16 v[66:69], v[142:145], v[166:169], v[66:69]
	s_setprio 0
	s_nop 0
	ds_read_b128 v[186:189], v208 offset:16384
	ds_read_b128 v[190:193], v208 offset:17408
	ds_read_b128 v[178:181], v208 offset:18432
	ds_read_b128 v[182:185], v208 offset:19456
	ds_read_b128 v[170:173], v208 offset:20480
	ds_read_b128 v[174:177], v208 offset:21504
	ds_read_b128 v[162:165], v208 offset:22528
	ds_read_b128 v[166:169], v208 offset:23552
	s_mov_b32 m0, s58
	s_nop 0
	global_load_lds_dwordx4 v202, s[42:43]
	s_add_u32 m0, s58, 0x2000
	s_nop 0
	global_load_lds_dwordx4 v203, s[42:43]
	s_add_u32 s50, s42, 0x4000
	s_addc_u32 s51, s43, 0
	s_mov_b32 m0, s59
	s_nop 0
	global_load_lds_dwordx4 v202, s[50:51]
	s_add_u32 m0, s59, 0x2000
	s_nop 0
	global_load_lds_dwordx4 v203, s[50:51]
	s_andn2_b64 vcc, exec, s[48:49]
	s_mov_b32 m0, s7
	s_nop 0
	global_load_lds_dwordx4 v202, s[46:47]
	s_add_u32 m0, s7, 0x2000
	s_nop 0
	global_load_lds_dwordx4 v203, s[46:47]
	s_cbranch_vccnz .LBB0_1338
	v_mov_b32_e32 v2, 0
	v_mov_b32_e32 v3, v2
	v_mov_b32_e32 v4, v2
	v_mov_b32_e32 v5, v2
	v_mov_b32_e32 v6, v2
	v_mov_b32_e32 v7, v2
	v_mov_b32_e32 v8, v2
	v_mov_b32_e32 v9, v2
	v_mov_b32_e32 v10, v2
	v_mov_b32_e32 v11, v2
	v_mov_b32_e32 v12, v2
	v_mov_b32_e32 v13, v2
	v_mov_b32_e32 v14, v2
	v_mov_b32_e32 v15, v2
	v_mov_b32_e32 v16, v2
	v_mov_b32_e32 v17, v2
	v_mov_b32_e32 v18, v2
	v_mov_b32_e32 v19, v2
	v_mov_b32_e32 v20, v2
	v_mov_b32_e32 v21, v2
	v_mov_b32_e32 v22, v2
	v_mov_b32_e32 v23, v2
	v_mov_b32_e32 v24, v2
	v_mov_b32_e32 v25, v2
	v_mov_b32_e32 v26, v2
	v_mov_b32_e32 v27, v2
	v_mov_b32_e32 v28, v2
	v_mov_b32_e32 v29, v2
	v_mov_b32_e32 v30, v2
	v_mov_b32_e32 v31, v2
	v_mov_b32_e32 v32, v2
	v_mov_b32_e32 v33, v2
	v_mov_b32_e32 v34, v2
	v_mov_b32_e32 v35, v2
	v_mov_b32_e32 v36, v2
	v_mov_b32_e32 v37, v2
	v_mov_b32_e32 v38, v2
	v_mov_b32_e32 v39, v2
	v_mov_b32_e32 v40, v2
	v_mov_b32_e32 v41, v2
	v_mov_b32_e32 v42, v2
	v_mov_b32_e32 v43, v2
	v_mov_b32_e32 v44, v2
	v_mov_b32_e32 v45, v2
	v_mov_b32_e32 v46, v2
	v_mov_b32_e32 v47, v2
	v_mov_b32_e32 v48, v2
	v_mov_b32_e32 v49, v2
	v_mov_b32_e32 v50, v2
	v_mov_b32_e32 v51, v2
	v_mov_b32_e32 v52, v2
	v_mov_b32_e32 v53, v2
	v_mov_b32_e32 v54, v2
	v_mov_b32_e32 v55, v2
	v_mov_b32_e32 v56, v2
	v_mov_b32_e32 v57, v2
	v_mov_b32_e32 v58, v2
	v_mov_b32_e32 v59, v2
	v_mov_b32_e32 v60, v2
	v_mov_b32_e32 v61, v2
	v_mov_b32_e32 v62, v2
	v_mov_b32_e32 v63, v2
	v_mov_b32_e32 v64, v2
	v_mov_b32_e32 v65, v2
.LBB0_1338:
	s_waitcnt vmcnt(8)
	s_add_u32 s48, s46, 0x8000
	s_waitcnt lgkmcnt(0)
	s_addc_u32 s49, s47, 0
	s_add_u32 s50, s42, 0x8000
	s_addc_u32 s51, s43, 0
	s_setprio 1
	s_barrier
	v_mfma_f32_16x16x32_bf16 v[62:65], v[146:149], v[186:189], v[62:65]
	v_mfma_f32_16x16x32_bf16 v[62:65], v[150:153], v[190:193], v[62:65]
	s_waitcnt lgkmcnt(5)
	v_mfma_f32_16x16x32_bf16 v[58:61], v[154:157], v[186:189], v[58:61]
	v_mfma_f32_16x16x32_bf16 v[58:61], v[158:161], v[190:193], v[58:61]
	s_waitcnt lgkmcnt(3)
	v_mfma_f32_16x16x32_bf16 v[54:57], v[146:149], v[178:181], v[54:57]
	v_mfma_f32_16x16x32_bf16 v[54:57], v[150:153], v[182:185], v[54:57]
	s_waitcnt lgkmcnt(1)
	v_mfma_f32_16x16x32_bf16 v[50:53], v[154:157], v[178:181], v[50:53]
	v_mfma_f32_16x16x32_bf16 v[50:53], v[158:161], v[182:185], v[50:53]
	v_mfma_f32_16x16x32_bf16 v[46:49], v[146:149], v[170:173], v[46:49]
	v_mfma_f32_16x16x32_bf16 v[46:49], v[150:153], v[174:177], v[46:49]
	v_mfma_f32_16x16x32_bf16 v[42:45], v[154:157], v[170:173], v[42:45]
	v_mfma_f32_16x16x32_bf16 v[42:45], v[158:161], v[174:177], v[42:45]
	v_mfma_f32_16x16x32_bf16 v[38:41], v[146:149], v[162:165], v[38:41]
	v_mfma_f32_16x16x32_bf16 v[38:41], v[150:153], v[166:169], v[38:41]
	s_waitcnt lgkmcnt(0)
	v_mfma_f32_16x16x32_bf16 v[34:37], v[154:157], v[162:165], v[34:37]
	v_mfma_f32_16x16x32_bf16 v[34:37], v[158:161], v[166:169], v[34:37]
	s_setprio 0
	s_setprio 1
	v_mfma_f32_16x16x32_bf16 v[30:33], v[130:133], v[186:189], v[30:33]
	v_mfma_f32_16x16x32_bf16 v[30:33], v[134:137], v[190:193], v[30:33]
	v_mfma_f32_16x16x32_bf16 v[26:29], v[138:141], v[186:189], v[26:29]
	v_mfma_f32_16x16x32_bf16 v[26:29], v[142:145], v[190:193], v[26:29]
	v_mfma_f32_16x16x32_bf16 v[22:25], v[130:133], v[178:181], v[22:25]
	v_mfma_f32_16x16x32_bf16 v[22:25], v[134:137], v[182:185], v[22:25]
	v_mfma_f32_16x16x32_bf16 v[18:21], v[138:141], v[178:181], v[18:21]
	v_mfma_f32_16x16x32_bf16 v[18:21], v[142:145], v[182:185], v[18:21]
	v_mfma_f32_16x16x32_bf16 v[14:17], v[130:133], v[170:173], v[14:17]
	v_mfma_f32_16x16x32_bf16 v[14:17], v[134:137], v[174:177], v[14:17]
	v_mfma_f32_16x16x32_bf16 v[10:13], v[138:141], v[170:173], v[10:13]
	v_mfma_f32_16x16x32_bf16 v[10:13], v[142:145], v[174:177], v[10:13]
	v_mfma_f32_16x16x32_bf16 v[6:9], v[130:133], v[162:165], v[6:9]
	v_mfma_f32_16x16x32_bf16 v[6:9], v[134:137], v[166:169], v[6:9]
	s_setprio 2
	s_barrier
	v_mfma_f32_16x16x32_bf16 v[2:5], v[138:141], v[162:165], v[2:5]
	v_mfma_f32_16x16x32_bf16 v[2:5], v[142:145], v[166:169], v[2:5]
	s_setprio 0
	s_nop 0
	v_add_u32_e32 v142, 0x18000, v207
	v_add_u32_e32 v158, 0x1c000, v207
	ds_read_b128 v[130:133], v142
	ds_read_b128 v[134:137], v142 offset:1024
	ds_read_b128 v[138:141], v142 offset:2048
	ds_read_b128 v[142:145], v142 offset:3072
	ds_read_b128 v[146:149], v158
	ds_read_b128 v[150:153], v158 offset:1024
	ds_read_b128 v[154:157], v158 offset:2048
	ds_read_b128 v[158:161], v158 offset:3072
	ds_read_b128 v[162:165], v208 offset:32768
	ds_read_b128 v[166:169], v208 offset:33792
	ds_read_b128 v[170:173], v208 offset:34816
	ds_read_b128 v[174:177], v208 offset:35840
	ds_read_b128 v[178:181], v208 offset:36864
	ds_read_b128 v[182:185], v208 offset:37888
	ds_read_b128 v[186:189], v208 offset:38912
	ds_read_b128 v[190:193], v208 offset:39936
	s_add_u32 s46, s46, 0x4000
	s_addc_u32 s47, s47, 0
	s_mov_b32 m0, s60
	s_nop 0
	global_load_lds_dwordx4 v202, s[46:47]
	s_add_u32 m0, s60, 0x2000
	s_nop 0
	global_load_lds_dwordx4 v203, s[46:47]
	s_waitcnt vmcnt(8)
	s_waitcnt lgkmcnt(0)
	s_setprio 1
	s_barrier
	v_mfma_f32_16x16x32_bf16 v[126:129], v[130:133], v[162:165], v[126:129]
	v_mfma_f32_16x16x32_bf16 v[126:129], v[134:137], v[166:169], v[126:129]
	s_waitcnt lgkmcnt(5)
	v_mfma_f32_16x16x32_bf16 v[122:125], v[138:141], v[162:165], v[122:125]
	v_mfma_f32_16x16x32_bf16 v[122:125], v[142:145], v[166:169], v[122:125]
	s_waitcnt lgkmcnt(3)
	v_mfma_f32_16x16x32_bf16 v[118:121], v[130:133], v[170:173], v[118:121]
	v_mfma_f32_16x16x32_bf16 v[118:121], v[134:137], v[174:177], v[118:121]
	s_waitcnt lgkmcnt(1)
	v_mfma_f32_16x16x32_bf16 v[114:117], v[138:141], v[170:173], v[114:117]
	v_mfma_f32_16x16x32_bf16 v[114:117], v[142:145], v[174:177], v[114:117]
	v_mfma_f32_16x16x32_bf16 v[110:113], v[130:133], v[178:181], v[110:113]
	v_mfma_f32_16x16x32_bf16 v[110:113], v[134:137], v[182:185], v[110:113]
	v_mfma_f32_16x16x32_bf16 v[106:109], v[138:141], v[178:181], v[106:109]
	v_mfma_f32_16x16x32_bf16 v[106:109], v[142:145], v[182:185], v[106:109]
	v_mfma_f32_16x16x32_bf16 v[102:105], v[130:133], v[186:189], v[102:105]
	v_mfma_f32_16x16x32_bf16 v[102:105], v[134:137], v[190:193], v[102:105]
	s_waitcnt lgkmcnt(0)
	v_mfma_f32_16x16x32_bf16 v[98:101], v[138:141], v[186:189], v[98:101]
	v_mfma_f32_16x16x32_bf16 v[98:101], v[142:145], v[190:193], v[98:101]
	s_setprio 0
	s_setprio 1
	v_mfma_f32_16x16x32_bf16 v[94:97], v[146:149], v[162:165], v[94:97]
	v_mfma_f32_16x16x32_bf16 v[94:97], v[150:153], v[166:169], v[94:97]
	v_mfma_f32_16x16x32_bf16 v[90:93], v[154:157], v[162:165], v[90:93]
	v_mfma_f32_16x16x32_bf16 v[90:93], v[158:161], v[166:169], v[90:93]
	v_mfma_f32_16x16x32_bf16 v[86:89], v[146:149], v[170:173], v[86:89]
	v_mfma_f32_16x16x32_bf16 v[86:89], v[150:153], v[174:177], v[86:89]
	v_mfma_f32_16x16x32_bf16 v[82:85], v[154:157], v[170:173], v[82:85]
	v_mfma_f32_16x16x32_bf16 v[82:85], v[158:161], v[174:177], v[82:85]
	v_mfma_f32_16x16x32_bf16 v[78:81], v[146:149], v[178:181], v[78:81]
	v_mfma_f32_16x16x32_bf16 v[78:81], v[150:153], v[182:185], v[78:81]
	v_mfma_f32_16x16x32_bf16 v[74:77], v[154:157], v[178:181], v[74:77]
	v_mfma_f32_16x16x32_bf16 v[74:77], v[158:161], v[182:185], v[74:77]
	v_mfma_f32_16x16x32_bf16 v[70:73], v[146:149], v[186:189], v[70:73]
	v_mfma_f32_16x16x32_bf16 v[70:73], v[150:153], v[190:193], v[70:73]
	s_setprio 2
	s_barrier
	v_mfma_f32_16x16x32_bf16 v[66:69], v[154:157], v[186:189], v[66:69]
	v_mfma_f32_16x16x32_bf16 v[66:69], v[158:161], v[190:193], v[66:69]
	s_setprio 0
	s_nop 0
	ds_read_b128 v[162:165], v208 offset:49152
	ds_read_b128 v[166:169], v208 offset:50176
	ds_read_b128 v[170:173], v208 offset:51200
	ds_read_b128 v[174:177], v208 offset:52224
	ds_read_b128 v[178:181], v208 offset:53248
	ds_read_b128 v[182:185], v208 offset:54272
	ds_read_b128 v[186:189], v208 offset:55296
	ds_read_b128 v[190:193], v208 offset:56320
	s_mov_b32 m0, s64
	s_nop 0
	global_load_lds_dwordx4 v202, s[50:51]
	s_add_u32 m0, s64, 0x2000
	s_nop 0
	global_load_lds_dwordx4 v203, s[50:51]
	s_add_u32 s42, s42, 0xc000
	s_addc_u32 s43, s43, 0
	s_mov_b32 m0, s66
	s_nop 0
	global_load_lds_dwordx4 v202, s[42:43]
	s_add_u32 m0, s66, 0x2000
	s_nop 0
	global_load_lds_dwordx4 v203, s[42:43]
	s_nop 0
	s_mov_b32 m0, s65
	s_nop 0
	global_load_lds_dwordx4 v202, s[48:49]
	s_add_u32 m0, s65, 0x2000
	s_nop 0
	global_load_lds_dwordx4 v203, s[48:49]
	s_waitcnt vmcnt(8)
	s_waitcnt lgkmcnt(0)
	s_setprio 1
	s_barrier
	v_mfma_f32_16x16x32_bf16 v[62:65], v[130:133], v[162:165], v[62:65]
	v_mfma_f32_16x16x32_bf16 v[62:65], v[134:137], v[166:169], v[62:65]
	s_waitcnt lgkmcnt(5)
	v_mfma_f32_16x16x32_bf16 v[58:61], v[138:141], v[162:165], v[58:61]
	v_mfma_f32_16x16x32_bf16 v[58:61], v[142:145], v[166:169], v[58:61]
	s_waitcnt lgkmcnt(3)
	v_mfma_f32_16x16x32_bf16 v[54:57], v[130:133], v[170:173], v[54:57]
	v_mfma_f32_16x16x32_bf16 v[54:57], v[134:137], v[174:177], v[54:57]
	s_waitcnt lgkmcnt(1)
	v_mfma_f32_16x16x32_bf16 v[50:53], v[138:141], v[170:173], v[50:53]
	v_mfma_f32_16x16x32_bf16 v[50:53], v[142:145], v[174:177], v[50:53]
	v_mfma_f32_16x16x32_bf16 v[46:49], v[130:133], v[178:181], v[46:49]
	v_mfma_f32_16x16x32_bf16 v[46:49], v[134:137], v[182:185], v[46:49]
	v_mfma_f32_16x16x32_bf16 v[42:45], v[138:141], v[178:181], v[42:45]
	v_mfma_f32_16x16x32_bf16 v[42:45], v[142:145], v[182:185], v[42:45]
	v_mfma_f32_16x16x32_bf16 v[38:41], v[130:133], v[186:189], v[38:41]
	v_mfma_f32_16x16x32_bf16 v[38:41], v[134:137], v[190:193], v[38:41]
	s_waitcnt lgkmcnt(0)
	v_mfma_f32_16x16x32_bf16 v[34:37], v[138:141], v[186:189], v[34:37]
	v_mfma_f32_16x16x32_bf16 v[34:37], v[142:145], v[190:193], v[34:37]
	s_setprio 0
	s_setprio 1
	v_mfma_f32_16x16x32_bf16 v[30:33], v[146:149], v[162:165], v[30:33]
	v_mfma_f32_16x16x32_bf16 v[30:33], v[150:153], v[166:169], v[30:33]
	v_mfma_f32_16x16x32_bf16 v[26:29], v[154:157], v[162:165], v[26:29]
	v_mfma_f32_16x16x32_bf16 v[26:29], v[158:161], v[166:169], v[26:29]
	v_mfma_f32_16x16x32_bf16 v[22:25], v[146:149], v[170:173], v[22:25]
	v_mfma_f32_16x16x32_bf16 v[22:25], v[150:153], v[174:177], v[22:25]
	v_mfma_f32_16x16x32_bf16 v[18:21], v[154:157], v[170:173], v[18:21]
	v_mfma_f32_16x16x32_bf16 v[18:21], v[158:161], v[174:177], v[18:21]
	v_mfma_f32_16x16x32_bf16 v[14:17], v[146:149], v[178:181], v[14:17]
	v_mfma_f32_16x16x32_bf16 v[14:17], v[150:153], v[182:185], v[14:17]
	v_mfma_f32_16x16x32_bf16 v[10:13], v[154:157], v[178:181], v[10:13]
	v_mfma_f32_16x16x32_bf16 v[10:13], v[158:161], v[182:185], v[10:13]
	v_mfma_f32_16x16x32_bf16 v[6:9], v[146:149], v[186:189], v[6:9]
	v_mfma_f32_16x16x32_bf16 v[6:9], v[150:153], v[190:193], v[6:9]
	s_setprio 2
	s_barrier
	v_mfma_f32_16x16x32_bf16 v[2:5], v[154:157], v[186:189], v[2:5]
	v_mfma_f32_16x16x32_bf16 v[2:5], v[158:161], v[190:193], v[2:5]
	s_setprio 0
	s_nop 0
	s_add_i32 s13, s77, 2
	s_cmp_gt_u32 s77, 5
	s_cbranch_scc1 .LBB0_1340
	s_mov_b32 s77, s13
	s_branch .LBB0_1317

.LBB0_1374:
	s_or_b64 exec, exec, s[40:41]
	s_add_u32 s76, s16, s6
	ds_read_b128 v[132:135], v168
	ds_read_b128 v[136:139], v168 offset:1024
	ds_read_b128 v[140:143], v168 offset:2048
	ds_read_b128 v[144:147], v168 offset:3072
	ds_read_b128 v[148:151], v169
	ds_read_b128 v[158:161], v169 offset:1024
	ds_read_b128 v[162:165], v169 offset:2048
	ds_read_b128 v[174:177], v169 offset:3072
	s_addc_u32 s77, s17, s7
	s_add_u32 s40, s76, 0x20000
	s_addc_u32 s41, s77, 0
	s_add_u32 s42, s71, s6
	s_addc_u32 s43, s72, s7
	s_cmp_eq_u32 s6, 0x20000
	s_cselect_b32 s48, s73, s40
	s_cselect_b32 s49, s27, s41
	s_cselect_b32 s41, s25, s43
	s_cselect_b32 s40, s74, s42
	s_add_u32 s42, s48, 0x8000
	s_addc_u32 s43, s49, 0
	s_add_u32 s46, s40, 0x8000
	s_addc_u32 s47, s41, 0
	ds_read_b128 v[178:181], v170
	ds_read_b128 v[182:185], v170 offset:1024
	ds_read_b128 v[186:189], v170 offset:2048
	ds_read_b128 v[190:193], v170 offset:3072
	ds_read_b128 v[198:201], v170 offset:4096
	ds_read_b128 v[204:207], v170 offset:5120
	ds_read_b128 v[212:215], v170 offset:6144
	ds_read_b128 v[216:219], v170 offset:7168
	s_add_u32 s76, s76, 0x1c000
	s_addc_u32 s77, s77, 0
	s_mov_b32 m0, s63
	s_nop 0
	global_load_lds_dwordx4 v202, s[76:77]
	s_add_u32 m0, s63, 0x2000
	s_nop 0
	global_load_lds_dwordx4 v203, s[76:77]
	s_waitcnt vmcnt(8)
	s_waitcnt lgkmcnt(0)
	s_setprio 1
	s_barrier
	v_mfma_f32_16x16x32_bf16 v[126:129], v[132:135], v[178:181], v[126:129]
	v_mfma_f32_16x16x32_bf16 v[126:129], v[136:139], v[182:185], v[126:129]
	s_waitcnt lgkmcnt(5)
	v_mfma_f32_16x16x32_bf16 v[122:125], v[140:143], v[178:181], v[122:125]
	v_mfma_f32_16x16x32_bf16 v[122:125], v[144:147], v[182:185], v[122:125]
	s_waitcnt lgkmcnt(3)
	v_mfma_f32_16x16x32_bf16 v[110:113], v[132:135], v[186:189], v[110:113]
	v_mfma_f32_16x16x32_bf16 v[110:113], v[136:139], v[190:193], v[110:113]
	s_waitcnt lgkmcnt(1)
	v_mfma_f32_16x16x32_bf16 v[106:109], v[140:143], v[186:189], v[106:109]
	v_mfma_f32_16x16x32_bf16 v[106:109], v[144:147], v[190:193], v[106:109]
	v_mfma_f32_16x16x32_bf16 v[94:97], v[132:135], v[198:201], v[94:97]
	v_mfma_f32_16x16x32_bf16 v[94:97], v[136:139], v[204:207], v[94:97]
	v_mfma_f32_16x16x32_bf16 v[90:93], v[140:143], v[198:201], v[90:93]
	v_mfma_f32_16x16x32_bf16 v[90:93], v[144:147], v[204:207], v[90:93]
	v_mfma_f32_16x16x32_bf16 v[78:81], v[132:135], v[212:215], v[78:81]
	v_mfma_f32_16x16x32_bf16 v[78:81], v[136:139], v[216:219], v[78:81]
	s_waitcnt lgkmcnt(0)
	v_mfma_f32_16x16x32_bf16 v[74:77], v[140:143], v[212:215], v[74:77]
	v_mfma_f32_16x16x32_bf16 v[74:77], v[144:147], v[216:219], v[74:77]
	s_setprio 0
	s_setprio 1
	v_mfma_f32_16x16x32_bf16 v[118:121], v[148:151], v[178:181], v[118:121]
	v_mfma_f32_16x16x32_bf16 v[118:121], v[158:161], v[182:185], v[118:121]
	v_mfma_f32_16x16x32_bf16 v[114:117], v[162:165], v[178:181], v[114:117]
	v_mfma_f32_16x16x32_bf16 v[114:117], v[174:177], v[182:185], v[114:117]
	v_mfma_f32_16x16x32_bf16 v[102:105], v[148:151], v[186:189], v[102:105]
	v_mfma_f32_16x16x32_bf16 v[102:105], v[158:161], v[190:193], v[102:105]
	v_mfma_f32_16x16x32_bf16 v[98:101], v[162:165], v[186:189], v[98:101]
	v_mfma_f32_16x16x32_bf16 v[98:101], v[174:177], v[190:193], v[98:101]
	v_mfma_f32_16x16x32_bf16 v[86:89], v[148:151], v[198:201], v[86:89]
	v_mfma_f32_16x16x32_bf16 v[86:89], v[158:161], v[204:207], v[86:89]
	v_mfma_f32_16x16x32_bf16 v[82:85], v[162:165], v[198:201], v[82:85]
	v_mfma_f32_16x16x32_bf16 v[82:85], v[174:177], v[204:207], v[82:85]
	v_mfma_f32_16x16x32_bf16 v[70:73], v[148:151], v[212:215], v[70:73]
	v_mfma_f32_16x16x32_bf16 v[70:73], v[158:161], v[216:219], v[70:73]
	s_setprio 2
	s_barrier
	v_mfma_f32_16x16x32_bf16 v[66:69], v[162:165], v[212:215], v[66:69]
	v_mfma_f32_16x16x32_bf16 v[66:69], v[174:177], v[216:219], v[66:69]
	s_setprio 0
	s_nop 0
	ds_read_b128 v[178:181], v170 offset:16384
	ds_read_b128 v[182:185], v170 offset:17408
	ds_read_b128 v[186:189], v170 offset:18432
	ds_read_b128 v[190:193], v170 offset:19456
	ds_read_b128 v[198:201], v170 offset:20480
	ds_read_b128 v[204:207], v170 offset:21504
	ds_read_b128 v[212:215], v170 offset:22528
	ds_read_b128 v[216:219], v170 offset:23552
	s_mov_b32 m0, s13
	s_nop 0
	global_load_lds_dwordx4 v202, s[40:41]
	s_add_u32 m0, s13, 0x2000
	s_nop 0
	global_load_lds_dwordx4 v203, s[40:41]
	s_add_u32 s76, s40, 0x4000
	s_addc_u32 s77, s41, 0
	s_mov_b32 m0, s55
	s_nop 0
	global_load_lds_dwordx4 v202, s[76:77]
	s_add_u32 m0, s55, 0x2000
	s_nop 0
	global_load_lds_dwordx4 v203, s[76:77]
	s_nop 0
	s_mov_b32 m0, s54
	s_nop 0
	global_load_lds_dwordx4 v202, s[48:49]
	s_add_u32 m0, s54, 0x2000
	s_nop 0
	global_load_lds_dwordx4 v203, s[48:49]
	s_waitcnt vmcnt(8)
	s_waitcnt lgkmcnt(0)
	s_setprio 1
	s_barrier
	v_mfma_f32_16x16x32_bf16 v[62:65], v[132:135], v[178:181], v[62:65]
	v_mfma_f32_16x16x32_bf16 v[62:65], v[136:139], v[182:185], v[62:65]
	s_waitcnt lgkmcnt(5)
	v_mfma_f32_16x16x32_bf16 v[58:61], v[140:143], v[178:181], v[58:61]
	v_mfma_f32_16x16x32_bf16 v[58:61], v[144:147], v[182:185], v[58:61]
	s_waitcnt lgkmcnt(3)
	v_mfma_f32_16x16x32_bf16 v[46:49], v[132:135], v[186:189], v[46:49]
	v_mfma_f32_16x16x32_bf16 v[46:49], v[136:139], v[190:193], v[46:49]
	s_waitcnt lgkmcnt(1)
	v_mfma_f32_16x16x32_bf16 v[42:45], v[140:143], v[186:189], v[42:45]
	v_mfma_f32_16x16x32_bf16 v[42:45], v[144:147], v[190:193], v[42:45]
	v_mfma_f32_16x16x32_bf16 v[30:33], v[132:135], v[198:201], v[30:33]
	v_mfma_f32_16x16x32_bf16 v[30:33], v[136:139], v[204:207], v[30:33]
	v_mfma_f32_16x16x32_bf16 v[26:29], v[140:143], v[198:201], v[26:29]
	v_mfma_f32_16x16x32_bf16 v[26:29], v[144:147], v[204:207], v[26:29]
	v_mfma_f32_16x16x32_bf16 v[14:17], v[132:135], v[212:215], v[14:17]
	v_mfma_f32_16x16x32_bf16 v[14:17], v[136:139], v[216:219], v[14:17]
	s_waitcnt lgkmcnt(0)
	v_mfma_f32_16x16x32_bf16 v[10:13], v[140:143], v[212:215], v[10:13]
	v_mfma_f32_16x16x32_bf16 v[10:13], v[144:147], v[216:219], v[10:13]
	s_setprio 0
	s_setprio 1
	v_mfma_f32_16x16x32_bf16 v[54:57], v[148:151], v[178:181], v[54:57]
	v_mfma_f32_16x16x32_bf16 v[54:57], v[158:161], v[182:185], v[54:57]
	v_mfma_f32_16x16x32_bf16 v[50:53], v[162:165], v[178:181], v[50:53]
	v_mfma_f32_16x16x32_bf16 v[50:53], v[174:177], v[182:185], v[50:53]
	v_mfma_f32_16x16x32_bf16 v[38:41], v[148:151], v[186:189], v[38:41]
	v_mfma_f32_16x16x32_bf16 v[38:41], v[158:161], v[190:193], v[38:41]
	v_mfma_f32_16x16x32_bf16 v[34:37], v[162:165], v[186:189], v[34:37]
	v_mfma_f32_16x16x32_bf16 v[34:37], v[174:177], v[190:193], v[34:37]
	v_mfma_f32_16x16x32_bf16 v[22:25], v[148:151], v[198:201], v[22:25]
	v_mfma_f32_16x16x32_bf16 v[22:25], v[158:161], v[204:207], v[22:25]
	v_mfma_f32_16x16x32_bf16 v[18:21], v[162:165], v[198:201], v[18:21]
	v_mfma_f32_16x16x32_bf16 v[18:21], v[174:177], v[204:207], v[18:21]
	v_mfma_f32_16x16x32_bf16 v[6:9], v[148:151], v[212:215], v[6:9]
	v_mfma_f32_16x16x32_bf16 v[6:9], v[158:161], v[216:219], v[6:9]
	s_setprio 2
	s_barrier
	v_mfma_f32_16x16x32_bf16 v[2:5], v[162:165], v[212:215], v[2:5]
	v_mfma_f32_16x16x32_bf16 v[2:5], v[174:177], v[216:219], v[2:5]
	s_setprio 0
	s_nop 0
	ds_read_b128 v[132:135], v171
	ds_read_b128 v[136:139], v171 offset:1024
	ds_read_b128 v[140:143], v171 offset:2048
	ds_read_b128 v[144:147], v171 offset:3072
	ds_read_b128 v[148:151], v172
	ds_read_b128 v[158:161], v172 offset:1024
	ds_read_b128 v[162:165], v172 offset:2048
	ds_read_b128 v[174:177], v172 offset:3072
	ds_read_b128 v[178:181], v170 offset:32768
	ds_read_b128 v[182:185], v170 offset:33792
	ds_read_b128 v[186:189], v170 offset:34816
	ds_read_b128 v[190:193], v170 offset:35840
	ds_read_b128 v[198:201], v170 offset:36864
	ds_read_b128 v[204:207], v170 offset:37888
	ds_read_b128 v[212:215], v170 offset:38912
	ds_read_b128 v[216:219], v170 offset:39936
	s_add_u32 s48, s48, 0x4000
	s_addc_u32 s49, s49, 0
	s_mov_b32 m0, s56
	s_nop 0
	global_load_lds_dwordx4 v202, s[48:49]
	s_add_u32 m0, s56, 0x2000
	s_nop 0
	global_load_lds_dwordx4 v203, s[48:49]
	s_waitcnt vmcnt(8)
	s_waitcnt lgkmcnt(0)
	s_setprio 1
	s_barrier
	v_mfma_f32_16x16x32_bf16 v[126:129], v[132:135], v[178:181], v[126:129]
	v_mfma_f32_16x16x32_bf16 v[126:129], v[136:139], v[182:185], v[126:129]
	s_waitcnt lgkmcnt(5)
	v_mfma_f32_16x16x32_bf16 v[122:125], v[140:143], v[178:181], v[122:125]
	v_mfma_f32_16x16x32_bf16 v[122:125], v[144:147], v[182:185], v[122:125]
	s_waitcnt lgkmcnt(3)
	v_mfma_f32_16x16x32_bf16 v[110:113], v[132:135], v[186:189], v[110:113]
	v_mfma_f32_16x16x32_bf16 v[110:113], v[136:139], v[190:193], v[110:113]
	s_waitcnt lgkmcnt(1)
	v_mfma_f32_16x16x32_bf16 v[106:109], v[140:143], v[186:189], v[106:109]
	v_mfma_f32_16x16x32_bf16 v[106:109], v[144:147], v[190:193], v[106:109]
	v_mfma_f32_16x16x32_bf16 v[94:97], v[132:135], v[198:201], v[94:97]
	v_mfma_f32_16x16x32_bf16 v[94:97], v[136:139], v[204:207], v[94:97]
	v_mfma_f32_16x16x32_bf16 v[90:93], v[140:143], v[198:201], v[90:93]
	v_mfma_f32_16x16x32_bf16 v[90:93], v[144:147], v[204:207], v[90:93]
	v_mfma_f32_16x16x32_bf16 v[78:81], v[132:135], v[212:215], v[78:81]
	v_mfma_f32_16x16x32_bf16 v[78:81], v[136:139], v[216:219], v[78:81]
	s_waitcnt lgkmcnt(0)
	v_mfma_f32_16x16x32_bf16 v[74:77], v[140:143], v[212:215], v[74:77]
	v_mfma_f32_16x16x32_bf16 v[74:77], v[144:147], v[216:219], v[74:77]
	s_setprio 0
	s_setprio 1
	v_mfma_f32_16x16x32_bf16 v[118:121], v[148:151], v[178:181], v[118:121]
	v_mfma_f32_16x16x32_bf16 v[118:121], v[158:161], v[182:185], v[118:121]
	v_mfma_f32_16x16x32_bf16 v[114:117], v[162:165], v[178:181], v[114:117]
	v_mfma_f32_16x16x32_bf16 v[114:117], v[174:177], v[182:185], v[114:117]
	v_mfma_f32_16x16x32_bf16 v[102:105], v[148:151], v[186:189], v[102:105]
	v_mfma_f32_16x16x32_bf16 v[102:105], v[158:161], v[190:193], v[102:105]
	v_mfma_f32_16x16x32_bf16 v[98:101], v[162:165], v[186:189], v[98:101]
	v_mfma_f32_16x16x32_bf16 v[98:101], v[174:177], v[190:193], v[98:101]
	v_mfma_f32_16x16x32_bf16 v[86:89], v[148:151], v[198:201], v[86:89]
	v_mfma_f32_16x16x32_bf16 v[86:89], v[158:161], v[204:207], v[86:89]
	v_mfma_f32_16x16x32_bf16 v[82:85], v[162:165], v[198:201], v[82:85]
	v_mfma_f32_16x16x32_bf16 v[82:85], v[174:177], v[204:207], v[82:85]
	v_mfma_f32_16x16x32_bf16 v[70:73], v[148:151], v[212:215], v[70:73]
	v_mfma_f32_16x16x32_bf16 v[70:73], v[158:161], v[216:219], v[70:73]
	s_setprio 2
	s_barrier
	v_mfma_f32_16x16x32_bf16 v[66:69], v[162:165], v[212:215], v[66:69]
	v_mfma_f32_16x16x32_bf16 v[66:69], v[174:177], v[216:219], v[66:69]
	s_setprio 0
	s_nop 0
	ds_read_b128 v[178:181], v170 offset:49152
	ds_read_b128 v[182:185], v170 offset:50176
	ds_read_b128 v[186:189], v170 offset:51200
	ds_read_b128 v[190:193], v170 offset:52224
	ds_read_b128 v[198:201], v170 offset:53248
	ds_read_b128 v[204:207], v170 offset:54272
	ds_read_b128 v[212:215], v170 offset:55296
	ds_read_b128 v[216:219], v170 offset:56320
	s_mov_b32 m0, s59
	s_nop 0
	global_load_lds_dwordx4 v202, s[46:47]
	s_add_u32 m0, s59, 0x2000
	s_nop 0
	global_load_lds_dwordx4 v203, s[46:47]
	s_add_u32 s40, s40, 0xc000
	s_addc_u32 s41, s41, 0
	s_mov_b32 m0, s62
	s_nop 0
	global_load_lds_dwordx4 v202, s[40:41]
	s_add_u32 m0, s62, 0x2000
	s_nop 0
	global_load_lds_dwordx4 v203, s[40:41]
	s_nop 0
	s_mov_b32 m0, s61
	s_nop 0
	global_load_lds_dwordx4 v202, s[42:43]
	s_add_u32 m0, s61, 0x2000
	s_nop 0
	global_load_lds_dwordx4 v203, s[42:43]
	s_waitcnt vmcnt(8)
	s_waitcnt lgkmcnt(0)
	s_setprio 1
	s_barrier
	v_mfma_f32_16x16x32_bf16 v[62:65], v[132:135], v[178:181], v[62:65]
	v_mfma_f32_16x16x32_bf16 v[62:65], v[136:139], v[182:185], v[62:65]
	s_waitcnt lgkmcnt(5)
	v_mfma_f32_16x16x32_bf16 v[58:61], v[140:143], v[178:181], v[58:61]
	v_mfma_f32_16x16x32_bf16 v[58:61], v[144:147], v[182:185], v[58:61]
	s_waitcnt lgkmcnt(3)
	v_mfma_f32_16x16x32_bf16 v[46:49], v[132:135], v[186:189], v[46:49]
	v_mfma_f32_16x16x32_bf16 v[46:49], v[136:139], v[190:193], v[46:49]
	s_waitcnt lgkmcnt(1)
	v_mfma_f32_16x16x32_bf16 v[42:45], v[140:143], v[186:189], v[42:45]
	v_mfma_f32_16x16x32_bf16 v[42:45], v[144:147], v[190:193], v[42:45]
	v_mfma_f32_16x16x32_bf16 v[30:33], v[132:135], v[198:201], v[30:33]
	v_mfma_f32_16x16x32_bf16 v[30:33], v[136:139], v[204:207], v[30:33]
	v_mfma_f32_16x16x32_bf16 v[26:29], v[140:143], v[198:201], v[26:29]
	v_mfma_f32_16x16x32_bf16 v[26:29], v[144:147], v[204:207], v[26:29]
	v_mfma_f32_16x16x32_bf16 v[14:17], v[132:135], v[212:215], v[14:17]
	v_mfma_f32_16x16x32_bf16 v[14:17], v[136:139], v[216:219], v[14:17]
	s_waitcnt lgkmcnt(0)
	v_mfma_f32_16x16x32_bf16 v[10:13], v[140:143], v[212:215], v[10:13]
	v_mfma_f32_16x16x32_bf16 v[10:13], v[144:147], v[216:219], v[10:13]
	s_setprio 0
	s_setprio 1
	v_mfma_f32_16x16x32_bf16 v[54:57], v[148:151], v[178:181], v[54:57]
	v_mfma_f32_16x16x32_bf16 v[54:57], v[158:161], v[182:185], v[54:57]
	v_mfma_f32_16x16x32_bf16 v[50:53], v[162:165], v[178:181], v[50:53]
	v_mfma_f32_16x16x32_bf16 v[50:53], v[174:177], v[182:185], v[50:53]
	v_mfma_f32_16x16x32_bf16 v[38:41], v[148:151], v[186:189], v[38:41]
	v_mfma_f32_16x16x32_bf16 v[38:41], v[158:161], v[190:193], v[38:41]
	v_mfma_f32_16x16x32_bf16 v[34:37], v[162:165], v[186:189], v[34:37]
	v_mfma_f32_16x16x32_bf16 v[34:37], v[174:177], v[190:193], v[34:37]
	v_mfma_f32_16x16x32_bf16 v[22:25], v[148:151], v[198:201], v[22:25]
	v_mfma_f32_16x16x32_bf16 v[22:25], v[158:161], v[204:207], v[22:25]
	v_mfma_f32_16x16x32_bf16 v[18:21], v[162:165], v[198:201], v[18:21]
	v_mfma_f32_16x16x32_bf16 v[18:21], v[174:177], v[204:207], v[18:21]
	v_mfma_f32_16x16x32_bf16 v[6:9], v[148:151], v[212:215], v[6:9]
	v_mfma_f32_16x16x32_bf16 v[6:9], v[158:161], v[216:219], v[6:9]
	s_setprio 2
	s_barrier
	v_mfma_f32_16x16x32_bf16 v[2:5], v[162:165], v[212:215], v[2:5]
	v_mfma_f32_16x16x32_bf16 v[2:5], v[174:177], v[216:219], v[2:5]
	s_setprio 0
	s_nop 0
	s_add_i32 s75, s75, 2
	s_add_u32 s6, s6, 0x10000
	s_addc_u32 s7, s7, 0
	s_cmp_gt_u32 s75, 5
	s_cbranch_scc1 .LBB0_1376
	v_mov_b32_e32 v131, v130
	s_branch .LBB0_1372

.LBB0_1519:
	s_add_i32 s26, s58, 2
	s_lshl_b64 s[54:55], s[26:27], 15
	s_add_u32 s17, s18, s54
	s_addc_u32 s59, s19, s55
	s_and_b64 s[50:51], s[12:13], exec
	s_cselect_b32 s51, s59, s41
	s_cselect_b32 s50, s17, s56
	s_add_u32 s17, s20, s54
	s_waitcnt vmcnt(8)
	s_addc_u32 s54, s21, s55
	s_waitcnt lgkmcnt(0)
	s_and_b64 s[12:13], s[12:13], exec
	s_cselect_b32 s13, s54, s39
	s_cselect_b32 s12, s17, s57
	s_setprio 1
	s_barrier
	v_mfma_f32_16x16x32_bf16 v[126:129], v[146:149], v[186:189], v[126:129]
	v_mfma_f32_16x16x32_bf16 v[126:129], v[150:153], v[190:193], v[126:129]
	s_waitcnt lgkmcnt(5)
	v_mfma_f32_16x16x32_bf16 v[122:125], v[154:157], v[186:189], v[122:125]
	v_mfma_f32_16x16x32_bf16 v[122:125], v[158:161], v[190:193], v[122:125]
	s_waitcnt lgkmcnt(3)
	v_mfma_f32_16x16x32_bf16 v[118:121], v[146:149], v[178:181], v[118:121]
	v_mfma_f32_16x16x32_bf16 v[118:121], v[150:153], v[182:185], v[118:121]
	s_waitcnt lgkmcnt(1)
	v_mfma_f32_16x16x32_bf16 v[114:117], v[154:157], v[178:181], v[114:117]
	v_mfma_f32_16x16x32_bf16 v[114:117], v[158:161], v[182:185], v[114:117]
	v_mfma_f32_16x16x32_bf16 v[110:113], v[146:149], v[170:173], v[110:113]
	v_mfma_f32_16x16x32_bf16 v[110:113], v[150:153], v[174:177], v[110:113]
	v_mfma_f32_16x16x32_bf16 v[106:109], v[154:157], v[170:173], v[106:109]
	v_mfma_f32_16x16x32_bf16 v[106:109], v[158:161], v[174:177], v[106:109]
	v_mfma_f32_16x16x32_bf16 v[102:105], v[146:149], v[162:165], v[102:105]
	v_mfma_f32_16x16x32_bf16 v[102:105], v[150:153], v[166:169], v[102:105]
	s_waitcnt lgkmcnt(0)
	v_mfma_f32_16x16x32_bf16 v[98:101], v[154:157], v[162:165], v[98:101]
	v_mfma_f32_16x16x32_bf16 v[98:101], v[158:161], v[166:169], v[98:101]
	s_setprio 0
	s_setprio 1
	v_mfma_f32_16x16x32_bf16 v[94:97], v[130:133], v[186:189], v[94:97]
	v_mfma_f32_16x16x32_bf16 v[94:97], v[134:137], v[190:193], v[94:97]
	v_mfma_f32_16x16x32_bf16 v[90:93], v[138:141], v[186:189], v[90:93]
	v_mfma_f32_16x16x32_bf16 v[90:93], v[142:145], v[190:193], v[90:93]
	v_mfma_f32_16x16x32_bf16 v[86:89], v[130:133], v[178:181], v[86:89]
	v_mfma_f32_16x16x32_bf16 v[86:89], v[134:137], v[182:185], v[86:89]
	v_mfma_f32_16x16x32_bf16 v[82:85], v[138:141], v[178:181], v[82:85]
	v_mfma_f32_16x16x32_bf16 v[82:85], v[142:145], v[182:185], v[82:85]
	v_mfma_f32_16x16x32_bf16 v[78:81], v[130:133], v[170:173], v[78:81]
	v_mfma_f32_16x16x32_bf16 v[78:81], v[134:137], v[174:177], v[78:81]
	v_mfma_f32_16x16x32_bf16 v[74:77], v[138:141], v[170:173], v[74:77]
	v_mfma_f32_16x16x32_bf16 v[74:77], v[142:145], v[174:177], v[74:77]
	v_mfma_f32_16x16x32_bf16 v[70:73], v[130:133], v[162:165], v[70:73]
	v_mfma_f32_16x16x32_bf16 v[70:73], v[134:137], v[166:169], v[70:73]
	s_setprio 2
	s_barrier
	v_mfma_f32_16x16x32_bf16 v[66:69], v[138:141], v[162:165], v[66:69]
	v_mfma_f32_16x16x32_bf16 v[66:69], v[142:145], v[166:169], v[66:69]
	s_setprio 0
	s_nop 0
	ds_read_b128 v[186:189], v217 offset:16384
	ds_read_b128 v[190:193], v217 offset:17408
	ds_read_b128 v[178:181], v217 offset:18432
	ds_read_b128 v[182:185], v217 offset:19456
	ds_read_b128 v[170:173], v217 offset:20480
	ds_read_b128 v[174:177], v217 offset:21504
	ds_read_b128 v[162:165], v217 offset:22528
	ds_read_b128 v[166:169], v217 offset:23552
	s_mov_b32 m0, s66
	s_nop 0
	global_load_lds_dwordx4 v195, s[12:13]
	s_add_u32 m0, s66, 0x2000
	s_nop 0
	global_load_lds_dwordx4 v212, s[12:13]
	s_add_u32 s54, s12, 0x4000
	s_addc_u32 s55, s13, 0
	s_mov_b32 m0, s67
	s_nop 0
	global_load_lds_dwordx4 v195, s[54:55]
	s_add_u32 m0, s67, 0x2000
	s_nop 0
	global_load_lds_dwordx4 v212, s[54:55]
	s_andn2_b64 vcc, exec, s[52:53]
	s_mov_b32 m0, s15
	s_nop 0
	global_load_lds_dwordx4 v195, s[50:51]
	s_add_u32 m0, s15, 0x2000
	s_nop 0
	global_load_lds_dwordx4 v212, s[50:51]
	s_cbranch_vccnz .LBB0_1521
	v_mov_b32_e32 v2, 0
	v_mov_b32_e32 v3, v2
	v_mov_b32_e32 v4, v2
	v_mov_b32_e32 v5, v2
	v_mov_b32_e32 v6, v2
	v_mov_b32_e32 v7, v2
	v_mov_b32_e32 v8, v2
	v_mov_b32_e32 v9, v2
	v_mov_b32_e32 v10, v2
	v_mov_b32_e32 v11, v2
	v_mov_b32_e32 v12, v2
	v_mov_b32_e32 v13, v2
	v_mov_b32_e32 v14, v2
	v_mov_b32_e32 v15, v2
	v_mov_b32_e32 v16, v2
	v_mov_b32_e32 v17, v2
	v_mov_b32_e32 v18, v2
	v_mov_b32_e32 v19, v2
	v_mov_b32_e32 v20, v2
	v_mov_b32_e32 v21, v2
	v_mov_b32_e32 v22, v2
	v_mov_b32_e32 v23, v2
	v_mov_b32_e32 v24, v2
	v_mov_b32_e32 v25, v2
	v_mov_b32_e32 v26, v2
	v_mov_b32_e32 v27, v2
	v_mov_b32_e32 v28, v2
	v_mov_b32_e32 v29, v2
	v_mov_b32_e32 v30, v2
	v_mov_b32_e32 v31, v2
	v_mov_b32_e32 v32, v2
	v_mov_b32_e32 v33, v2
	v_mov_b32_e32 v34, v2
	v_mov_b32_e32 v35, v2
	v_mov_b32_e32 v36, v2
	v_mov_b32_e32 v37, v2
	v_mov_b32_e32 v38, v2
	v_mov_b32_e32 v39, v2
	v_mov_b32_e32 v40, v2
	v_mov_b32_e32 v41, v2
	v_mov_b32_e32 v42, v2
	v_mov_b32_e32 v43, v2
	v_mov_b32_e32 v44, v2
	v_mov_b32_e32 v45, v2
	v_mov_b32_e32 v46, v2
	v_mov_b32_e32 v47, v2
	v_mov_b32_e32 v48, v2
	v_mov_b32_e32 v49, v2
	v_mov_b32_e32 v50, v2
	v_mov_b32_e32 v51, v2
	v_mov_b32_e32 v52, v2
	v_mov_b32_e32 v53, v2
	v_mov_b32_e32 v54, v2
	v_mov_b32_e32 v55, v2
	v_mov_b32_e32 v56, v2
	v_mov_b32_e32 v57, v2
	v_mov_b32_e32 v58, v2
	v_mov_b32_e32 v59, v2
	v_mov_b32_e32 v60, v2
	v_mov_b32_e32 v61, v2
	v_mov_b32_e32 v62, v2
	v_mov_b32_e32 v63, v2
	v_mov_b32_e32 v64, v2
	v_mov_b32_e32 v65, v2
.LBB0_1521:
	s_waitcnt vmcnt(8)
	s_add_u32 s52, s50, 0x8000
	s_waitcnt lgkmcnt(0)
	s_addc_u32 s53, s51, 0
	s_add_u32 s54, s12, 0x8000
	s_addc_u32 s55, s13, 0
	s_setprio 1
	s_barrier
	v_mfma_f32_16x16x32_bf16 v[62:65], v[146:149], v[186:189], v[62:65]
	v_mfma_f32_16x16x32_bf16 v[62:65], v[150:153], v[190:193], v[62:65]
	s_waitcnt lgkmcnt(5)
	v_mfma_f32_16x16x32_bf16 v[58:61], v[154:157], v[186:189], v[58:61]
	v_mfma_f32_16x16x32_bf16 v[58:61], v[158:161], v[190:193], v[58:61]
	s_waitcnt lgkmcnt(3)
	v_mfma_f32_16x16x32_bf16 v[54:57], v[146:149], v[178:181], v[54:57]
	v_mfma_f32_16x16x32_bf16 v[54:57], v[150:153], v[182:185], v[54:57]
	s_waitcnt lgkmcnt(1)
	v_mfma_f32_16x16x32_bf16 v[50:53], v[154:157], v[178:181], v[50:53]
	v_mfma_f32_16x16x32_bf16 v[50:53], v[158:161], v[182:185], v[50:53]
	v_mfma_f32_16x16x32_bf16 v[46:49], v[146:149], v[170:173], v[46:49]
	v_mfma_f32_16x16x32_bf16 v[46:49], v[150:153], v[174:177], v[46:49]
	v_mfma_f32_16x16x32_bf16 v[42:45], v[154:157], v[170:173], v[42:45]
	v_mfma_f32_16x16x32_bf16 v[42:45], v[158:161], v[174:177], v[42:45]
	v_mfma_f32_16x16x32_bf16 v[38:41], v[146:149], v[162:165], v[38:41]
	v_mfma_f32_16x16x32_bf16 v[38:41], v[150:153], v[166:169], v[38:41]
	s_waitcnt lgkmcnt(0)
	v_mfma_f32_16x16x32_bf16 v[34:37], v[154:157], v[162:165], v[34:37]
	v_mfma_f32_16x16x32_bf16 v[34:37], v[158:161], v[166:169], v[34:37]
	s_setprio 0
	s_setprio 1
	v_mfma_f32_16x16x32_bf16 v[30:33], v[130:133], v[186:189], v[30:33]
	v_mfma_f32_16x16x32_bf16 v[30:33], v[134:137], v[190:193], v[30:33]
	v_mfma_f32_16x16x32_bf16 v[26:29], v[138:141], v[186:189], v[26:29]
	v_mfma_f32_16x16x32_bf16 v[26:29], v[142:145], v[190:193], v[26:29]
	v_mfma_f32_16x16x32_bf16 v[22:25], v[130:133], v[178:181], v[22:25]
	v_mfma_f32_16x16x32_bf16 v[22:25], v[134:137], v[182:185], v[22:25]
	v_mfma_f32_16x16x32_bf16 v[18:21], v[138:141], v[178:181], v[18:21]
	v_mfma_f32_16x16x32_bf16 v[18:21], v[142:145], v[182:185], v[18:21]
	v_mfma_f32_16x16x32_bf16 v[14:17], v[130:133], v[170:173], v[14:17]
	v_mfma_f32_16x16x32_bf16 v[14:17], v[134:137], v[174:177], v[14:17]
	v_mfma_f32_16x16x32_bf16 v[10:13], v[138:141], v[170:173], v[10:13]
	v_mfma_f32_16x16x32_bf16 v[10:13], v[142:145], v[174:177], v[10:13]
	v_mfma_f32_16x16x32_bf16 v[6:9], v[130:133], v[162:165], v[6:9]
	v_mfma_f32_16x16x32_bf16 v[6:9], v[134:137], v[166:169], v[6:9]
	s_setprio 2
	s_barrier
	v_mfma_f32_16x16x32_bf16 v[2:5], v[138:141], v[162:165], v[2:5]
	v_mfma_f32_16x16x32_bf16 v[2:5], v[142:145], v[166:169], v[2:5]
	s_setprio 0
	s_nop 0
	v_add_u32_e32 v142, 0x18000, v216
	v_add_u32_e32 v158, 0x1c000, v216
	ds_read_b128 v[130:133], v142
	ds_read_b128 v[134:137], v142 offset:1024
	ds_read_b128 v[138:141], v142 offset:2048
	ds_read_b128 v[142:145], v142 offset:3072
	ds_read_b128 v[146:149], v158
	ds_read_b128 v[150:153], v158 offset:1024
	ds_read_b128 v[154:157], v158 offset:2048
	ds_read_b128 v[158:161], v158 offset:3072
	ds_read_b128 v[162:165], v217 offset:32768
	ds_read_b128 v[166:169], v217 offset:33792
	ds_read_b128 v[170:173], v217 offset:34816
	ds_read_b128 v[174:177], v217 offset:35840
	ds_read_b128 v[178:181], v217 offset:36864
	ds_read_b128 v[182:185], v217 offset:37888
	ds_read_b128 v[186:189], v217 offset:38912
	ds_read_b128 v[190:193], v217 offset:39936
	s_add_u32 s50, s50, 0x4000
	s_addc_u32 s51, s51, 0
	s_mov_b32 m0, s68
	s_nop 0
	global_load_lds_dwordx4 v195, s[50:51]
	s_add_u32 m0, s68, 0x2000
	s_nop 0
	global_load_lds_dwordx4 v212, s[50:51]
	s_waitcnt vmcnt(8)
	s_waitcnt lgkmcnt(0)
	s_setprio 1
	s_barrier
	v_mfma_f32_16x16x32_bf16 v[126:129], v[130:133], v[162:165], v[126:129]
	v_mfma_f32_16x16x32_bf16 v[126:129], v[134:137], v[166:169], v[126:129]
	s_waitcnt lgkmcnt(5)
	v_mfma_f32_16x16x32_bf16 v[122:125], v[138:141], v[162:165], v[122:125]
	v_mfma_f32_16x16x32_bf16 v[122:125], v[142:145], v[166:169], v[122:125]
	s_waitcnt lgkmcnt(3)
	v_mfma_f32_16x16x32_bf16 v[118:121], v[130:133], v[170:173], v[118:121]
	v_mfma_f32_16x16x32_bf16 v[118:121], v[134:137], v[174:177], v[118:121]
	s_waitcnt lgkmcnt(1)
	v_mfma_f32_16x16x32_bf16 v[114:117], v[138:141], v[170:173], v[114:117]
	v_mfma_f32_16x16x32_bf16 v[114:117], v[142:145], v[174:177], v[114:117]
	v_mfma_f32_16x16x32_bf16 v[110:113], v[130:133], v[178:181], v[110:113]
	v_mfma_f32_16x16x32_bf16 v[110:113], v[134:137], v[182:185], v[110:113]
	v_mfma_f32_16x16x32_bf16 v[106:109], v[138:141], v[178:181], v[106:109]
	v_mfma_f32_16x16x32_bf16 v[106:109], v[142:145], v[182:185], v[106:109]
	v_mfma_f32_16x16x32_bf16 v[102:105], v[130:133], v[186:189], v[102:105]
	v_mfma_f32_16x16x32_bf16 v[102:105], v[134:137], v[190:193], v[102:105]
	s_waitcnt lgkmcnt(0)
	v_mfma_f32_16x16x32_bf16 v[98:101], v[138:141], v[186:189], v[98:101]
	v_mfma_f32_16x16x32_bf16 v[98:101], v[142:145], v[190:193], v[98:101]
	s_setprio 0
	s_setprio 1
	v_mfma_f32_16x16x32_bf16 v[94:97], v[146:149], v[162:165], v[94:97]
	v_mfma_f32_16x16x32_bf16 v[94:97], v[150:153], v[166:169], v[94:97]
	v_mfma_f32_16x16x32_bf16 v[90:93], v[154:157], v[162:165], v[90:93]
	v_mfma_f32_16x16x32_bf16 v[90:93], v[158:161], v[166:169], v[90:93]
	v_mfma_f32_16x16x32_bf16 v[86:89], v[146:149], v[170:173], v[86:89]
	v_mfma_f32_16x16x32_bf16 v[86:89], v[150:153], v[174:177], v[86:89]
	v_mfma_f32_16x16x32_bf16 v[82:85], v[154:157], v[170:173], v[82:85]
	v_mfma_f32_16x16x32_bf16 v[82:85], v[158:161], v[174:177], v[82:85]
	v_mfma_f32_16x16x32_bf16 v[78:81], v[146:149], v[178:181], v[78:81]
	v_mfma_f32_16x16x32_bf16 v[78:81], v[150:153], v[182:185], v[78:81]
	v_mfma_f32_16x16x32_bf16 v[74:77], v[154:157], v[178:181], v[74:77]
	v_mfma_f32_16x16x32_bf16 v[74:77], v[158:161], v[182:185], v[74:77]
	v_mfma_f32_16x16x32_bf16 v[70:73], v[146:149], v[186:189], v[70:73]
	v_mfma_f32_16x16x32_bf16 v[70:73], v[150:153], v[190:193], v[70:73]
	s_setprio 2
	s_barrier
	v_mfma_f32_16x16x32_bf16 v[66:69], v[154:157], v[186:189], v[66:69]
	v_mfma_f32_16x16x32_bf16 v[66:69], v[158:161], v[190:193], v[66:69]
	s_setprio 0
	s_nop 0
	ds_read_b128 v[162:165], v217 offset:49152
	ds_read_b128 v[166:169], v217 offset:50176
	ds_read_b128 v[170:173], v217 offset:51200
	ds_read_b128 v[174:177], v217 offset:52224
	ds_read_b128 v[178:181], v217 offset:53248
	ds_read_b128 v[182:185], v217 offset:54272
	ds_read_b128 v[186:189], v217 offset:55296
	ds_read_b128 v[190:193], v217 offset:56320
	s_mov_b32 m0, s72
	s_nop 0
	global_load_lds_dwordx4 v195, s[54:55]
	s_add_u32 m0, s72, 0x2000
	s_nop 0
	global_load_lds_dwordx4 v212, s[54:55]
	s_add_u32 s12, s12, 0xc000
	s_addc_u32 s13, s13, 0
	s_mov_b32 m0, s74
	s_nop 0
	global_load_lds_dwordx4 v195, s[12:13]
	s_add_u32 m0, s74, 0x2000
	s_nop 0
	global_load_lds_dwordx4 v212, s[12:13]
	s_nop 0
	s_mov_b32 m0, s73
	s_nop 0
	global_load_lds_dwordx4 v195, s[52:53]
	s_add_u32 m0, s73, 0x2000
	s_nop 0
	global_load_lds_dwordx4 v212, s[52:53]
	s_waitcnt vmcnt(8)
	s_waitcnt lgkmcnt(0)
	s_setprio 1
	s_barrier
	v_mfma_f32_16x16x32_bf16 v[62:65], v[130:133], v[162:165], v[62:65]
	v_mfma_f32_16x16x32_bf16 v[62:65], v[134:137], v[166:169], v[62:65]
	s_waitcnt lgkmcnt(5)
	v_mfma_f32_16x16x32_bf16 v[58:61], v[138:141], v[162:165], v[58:61]
	v_mfma_f32_16x16x32_bf16 v[58:61], v[142:145], v[166:169], v[58:61]
	s_waitcnt lgkmcnt(3)
	v_mfma_f32_16x16x32_bf16 v[54:57], v[130:133], v[170:173], v[54:57]
	v_mfma_f32_16x16x32_bf16 v[54:57], v[134:137], v[174:177], v[54:57]
	s_waitcnt lgkmcnt(1)
	v_mfma_f32_16x16x32_bf16 v[50:53], v[138:141], v[170:173], v[50:53]
	v_mfma_f32_16x16x32_bf16 v[50:53], v[142:145], v[174:177], v[50:53]
	v_mfma_f32_16x16x32_bf16 v[46:49], v[130:133], v[178:181], v[46:49]
	v_mfma_f32_16x16x32_bf16 v[46:49], v[134:137], v[182:185], v[46:49]
	v_mfma_f32_16x16x32_bf16 v[42:45], v[138:141], v[178:181], v[42:45]
	v_mfma_f32_16x16x32_bf16 v[42:45], v[142:145], v[182:185], v[42:45]
	v_mfma_f32_16x16x32_bf16 v[38:41], v[130:133], v[186:189], v[38:41]
	v_mfma_f32_16x16x32_bf16 v[38:41], v[134:137], v[190:193], v[38:41]
	s_waitcnt lgkmcnt(0)
	v_mfma_f32_16x16x32_bf16 v[34:37], v[138:141], v[186:189], v[34:37]
	v_mfma_f32_16x16x32_bf16 v[34:37], v[142:145], v[190:193], v[34:37]
	s_setprio 0
	s_setprio 1
	v_mfma_f32_16x16x32_bf16 v[30:33], v[146:149], v[162:165], v[30:33]
	v_mfma_f32_16x16x32_bf16 v[30:33], v[150:153], v[166:169], v[30:33]
	v_mfma_f32_16x16x32_bf16 v[26:29], v[154:157], v[162:165], v[26:29]
	v_mfma_f32_16x16x32_bf16 v[26:29], v[158:161], v[166:169], v[26:29]
	v_mfma_f32_16x16x32_bf16 v[22:25], v[146:149], v[170:173], v[22:25]
	v_mfma_f32_16x16x32_bf16 v[22:25], v[150:153], v[174:177], v[22:25]
	v_mfma_f32_16x16x32_bf16 v[18:21], v[154:157], v[170:173], v[18:21]
	v_mfma_f32_16x16x32_bf16 v[18:21], v[158:161], v[174:177], v[18:21]
	v_mfma_f32_16x16x32_bf16 v[14:17], v[146:149], v[178:181], v[14:17]
	v_mfma_f32_16x16x32_bf16 v[14:17], v[150:153], v[182:185], v[14:17]
	v_mfma_f32_16x16x32_bf16 v[10:13], v[154:157], v[178:181], v[10:13]
	v_mfma_f32_16x16x32_bf16 v[10:13], v[158:161], v[182:185], v[10:13]
	v_mfma_f32_16x16x32_bf16 v[6:9], v[146:149], v[186:189], v[6:9]
	v_mfma_f32_16x16x32_bf16 v[6:9], v[150:153], v[190:193], v[6:9]
	s_setprio 2
	s_barrier
	v_mfma_f32_16x16x32_bf16 v[2:5], v[154:157], v[186:189], v[2:5]
	v_mfma_f32_16x16x32_bf16 v[2:5], v[158:161], v[190:193], v[2:5]
	s_setprio 0
	s_nop 0
	s_cmp_gt_u32 s58, 13
	s_cbranch_scc1 .LBB0_1523
	v_mov_b32_e32 v130, v198
	s_mov_b32 s58, s26
	s_branch .LBB0_1498

.LBB0_1712:
	s_add_u32 s52, s48, 0x10000
	s_addc_u32 s53, s49, 0
	s_and_b64 s[48:49], s[46:47], exec
	s_cselect_b32 s49, s53, s25
	s_cselect_b32 s48, s52, s75
	s_add_u32 s13, s16, s13
	s_addc_u32 s52, s17, 0
	s_add_u32 s13, s13, 0x10000
	s_waitcnt vmcnt(8)
	s_addc_u32 s52, s52, 0
	s_waitcnt lgkmcnt(0)
	s_and_b64 s[46:47], s[46:47], exec
	s_cselect_b32 s47, s52, s27
	s_cselect_b32 s46, s13, s76
	s_setprio 1
	s_barrier
	v_mfma_f32_16x16x32_bf16 v[126:129], v[146:149], v[186:189], v[126:129]
	v_mfma_f32_16x16x32_bf16 v[126:129], v[150:153], v[190:193], v[126:129]
	s_waitcnt lgkmcnt(5)
	v_mfma_f32_16x16x32_bf16 v[122:125], v[154:157], v[186:189], v[122:125]
	v_mfma_f32_16x16x32_bf16 v[122:125], v[158:161], v[190:193], v[122:125]
	s_waitcnt lgkmcnt(3)
	v_mfma_f32_16x16x32_bf16 v[118:121], v[146:149], v[178:181], v[118:121]
	v_mfma_f32_16x16x32_bf16 v[118:121], v[150:153], v[182:185], v[118:121]
	s_waitcnt lgkmcnt(1)
	v_mfma_f32_16x16x32_bf16 v[114:117], v[154:157], v[178:181], v[114:117]
	v_mfma_f32_16x16x32_bf16 v[114:117], v[158:161], v[182:185], v[114:117]
	v_mfma_f32_16x16x32_bf16 v[110:113], v[146:149], v[170:173], v[110:113]
	v_mfma_f32_16x16x32_bf16 v[110:113], v[150:153], v[174:177], v[110:113]
	v_mfma_f32_16x16x32_bf16 v[106:109], v[154:157], v[170:173], v[106:109]
	v_mfma_f32_16x16x32_bf16 v[106:109], v[158:161], v[174:177], v[106:109]
	v_mfma_f32_16x16x32_bf16 v[102:105], v[146:149], v[162:165], v[102:105]
	v_mfma_f32_16x16x32_bf16 v[102:105], v[150:153], v[166:169], v[102:105]
	s_waitcnt lgkmcnt(0)
	v_mfma_f32_16x16x32_bf16 v[98:101], v[154:157], v[162:165], v[98:101]
	v_mfma_f32_16x16x32_bf16 v[98:101], v[158:161], v[166:169], v[98:101]
	s_setprio 0
	s_setprio 1
	v_mfma_f32_16x16x32_bf16 v[94:97], v[130:133], v[186:189], v[94:97]
	v_mfma_f32_16x16x32_bf16 v[94:97], v[134:137], v[190:193], v[94:97]
	v_mfma_f32_16x16x32_bf16 v[90:93], v[138:141], v[186:189], v[90:93]
	v_mfma_f32_16x16x32_bf16 v[90:93], v[142:145], v[190:193], v[90:93]
	v_mfma_f32_16x16x32_bf16 v[86:89], v[130:133], v[178:181], v[86:89]
	v_mfma_f32_16x16x32_bf16 v[86:89], v[134:137], v[182:185], v[86:89]
	v_mfma_f32_16x16x32_bf16 v[82:85], v[138:141], v[178:181], v[82:85]
	v_mfma_f32_16x16x32_bf16 v[82:85], v[142:145], v[182:185], v[82:85]
	v_mfma_f32_16x16x32_bf16 v[78:81], v[130:133], v[170:173], v[78:81]
	v_mfma_f32_16x16x32_bf16 v[78:81], v[134:137], v[174:177], v[78:81]
	v_mfma_f32_16x16x32_bf16 v[74:77], v[138:141], v[170:173], v[74:77]
	v_mfma_f32_16x16x32_bf16 v[74:77], v[142:145], v[174:177], v[74:77]
	v_mfma_f32_16x16x32_bf16 v[70:73], v[130:133], v[162:165], v[70:73]
	v_mfma_f32_16x16x32_bf16 v[70:73], v[134:137], v[166:169], v[70:73]
	s_setprio 2
	s_barrier
	v_mfma_f32_16x16x32_bf16 v[66:69], v[138:141], v[162:165], v[66:69]
	v_mfma_f32_16x16x32_bf16 v[66:69], v[142:145], v[166:169], v[66:69]
	s_setprio 0
	s_nop 0
	ds_read_b128 v[186:189], v209 offset:16384
	ds_read_b128 v[190:193], v209 offset:17408
	ds_read_b128 v[178:181], v209 offset:18432
	ds_read_b128 v[182:185], v209 offset:19456
	ds_read_b128 v[170:173], v209 offset:20480
	ds_read_b128 v[174:177], v209 offset:21504
	ds_read_b128 v[162:165], v209 offset:22528
	ds_read_b128 v[166:169], v209 offset:23552
	s_mov_b32 m0, s58
	s_nop 0
	global_load_lds_dwordx4 v195, s[46:47]
	s_add_u32 m0, s58, 0x2000
	s_nop 0
	global_load_lds_dwordx4 v203, s[46:47]
	s_add_u32 s52, s46, 0x4000
	s_addc_u32 s53, s47, 0
	s_mov_b32 m0, s59
	s_nop 0
	global_load_lds_dwordx4 v195, s[52:53]
	s_add_u32 m0, s59, 0x2000
	s_nop 0
	global_load_lds_dwordx4 v203, s[52:53]
	s_andn2_b64 vcc, exec, s[50:51]
	s_mov_b32 m0, s11
	s_nop 0
	global_load_lds_dwordx4 v195, s[48:49]
	s_add_u32 m0, s11, 0x2000
	s_nop 0
	global_load_lds_dwordx4 v203, s[48:49]
	s_cbranch_vccnz .LBB0_1714
	v_mov_b32_e32 v2, 0
	v_mov_b32_e32 v3, v2
	v_mov_b32_e32 v4, v2
	v_mov_b32_e32 v5, v2
	v_mov_b32_e32 v6, v2
	v_mov_b32_e32 v7, v2
	v_mov_b32_e32 v8, v2
	v_mov_b32_e32 v9, v2
	v_mov_b32_e32 v10, v2
	v_mov_b32_e32 v11, v2
	v_mov_b32_e32 v12, v2
	v_mov_b32_e32 v13, v2
	v_mov_b32_e32 v14, v2
	v_mov_b32_e32 v15, v2
	v_mov_b32_e32 v16, v2
	v_mov_b32_e32 v17, v2
	v_mov_b32_e32 v18, v2
	v_mov_b32_e32 v19, v2
	v_mov_b32_e32 v20, v2
	v_mov_b32_e32 v21, v2
	v_mov_b32_e32 v22, v2
	v_mov_b32_e32 v23, v2
	v_mov_b32_e32 v24, v2
	v_mov_b32_e32 v25, v2
	v_mov_b32_e32 v26, v2
	v_mov_b32_e32 v27, v2
	v_mov_b32_e32 v28, v2
	v_mov_b32_e32 v29, v2
	v_mov_b32_e32 v30, v2
	v_mov_b32_e32 v31, v2
	v_mov_b32_e32 v32, v2
	v_mov_b32_e32 v33, v2
	v_mov_b32_e32 v34, v2
	v_mov_b32_e32 v35, v2
	v_mov_b32_e32 v36, v2
	v_mov_b32_e32 v37, v2
	v_mov_b32_e32 v38, v2
	v_mov_b32_e32 v39, v2
	v_mov_b32_e32 v40, v2
	v_mov_b32_e32 v41, v2
	v_mov_b32_e32 v42, v2
	v_mov_b32_e32 v43, v2
	v_mov_b32_e32 v44, v2
	v_mov_b32_e32 v45, v2
	v_mov_b32_e32 v46, v2
	v_mov_b32_e32 v47, v2
	v_mov_b32_e32 v48, v2
	v_mov_b32_e32 v49, v2
	v_mov_b32_e32 v50, v2
	v_mov_b32_e32 v51, v2
	v_mov_b32_e32 v52, v2
	v_mov_b32_e32 v53, v2
	v_mov_b32_e32 v54, v2
	v_mov_b32_e32 v55, v2
	v_mov_b32_e32 v56, v2
	v_mov_b32_e32 v57, v2
	v_mov_b32_e32 v58, v2
	v_mov_b32_e32 v59, v2
	v_mov_b32_e32 v60, v2
	v_mov_b32_e32 v61, v2
	v_mov_b32_e32 v62, v2
	v_mov_b32_e32 v63, v2
	v_mov_b32_e32 v64, v2
	v_mov_b32_e32 v65, v2
.LBB0_1714:
	s_waitcnt vmcnt(8)
	s_add_u32 s50, s48, 0x8000
	s_waitcnt lgkmcnt(0)
	s_addc_u32 s51, s49, 0
	s_add_u32 s52, s46, 0x8000
	s_addc_u32 s53, s47, 0
	s_setprio 1
	s_barrier
	v_mfma_f32_16x16x32_bf16 v[62:65], v[146:149], v[186:189], v[62:65]
	v_mfma_f32_16x16x32_bf16 v[62:65], v[150:153], v[190:193], v[62:65]
	s_waitcnt lgkmcnt(5)
	v_mfma_f32_16x16x32_bf16 v[58:61], v[154:157], v[186:189], v[58:61]
	v_mfma_f32_16x16x32_bf16 v[58:61], v[158:161], v[190:193], v[58:61]
	s_waitcnt lgkmcnt(3)
	v_mfma_f32_16x16x32_bf16 v[54:57], v[146:149], v[178:181], v[54:57]
	v_mfma_f32_16x16x32_bf16 v[54:57], v[150:153], v[182:185], v[54:57]
	s_waitcnt lgkmcnt(1)
	v_mfma_f32_16x16x32_bf16 v[50:53], v[154:157], v[178:181], v[50:53]
	v_mfma_f32_16x16x32_bf16 v[50:53], v[158:161], v[182:185], v[50:53]
	v_mfma_f32_16x16x32_bf16 v[46:49], v[146:149], v[170:173], v[46:49]
	v_mfma_f32_16x16x32_bf16 v[46:49], v[150:153], v[174:177], v[46:49]
	v_mfma_f32_16x16x32_bf16 v[42:45], v[154:157], v[170:173], v[42:45]
	v_mfma_f32_16x16x32_bf16 v[42:45], v[158:161], v[174:177], v[42:45]
	v_mfma_f32_16x16x32_bf16 v[38:41], v[146:149], v[162:165], v[38:41]
	v_mfma_f32_16x16x32_bf16 v[38:41], v[150:153], v[166:169], v[38:41]
	s_waitcnt lgkmcnt(0)
	v_mfma_f32_16x16x32_bf16 v[34:37], v[154:157], v[162:165], v[34:37]
	v_mfma_f32_16x16x32_bf16 v[34:37], v[158:161], v[166:169], v[34:37]
	s_setprio 0
	s_setprio 1
	v_mfma_f32_16x16x32_bf16 v[30:33], v[130:133], v[186:189], v[30:33]
	v_mfma_f32_16x16x32_bf16 v[30:33], v[134:137], v[190:193], v[30:33]
	v_mfma_f32_16x16x32_bf16 v[26:29], v[138:141], v[186:189], v[26:29]
	v_mfma_f32_16x16x32_bf16 v[26:29], v[142:145], v[190:193], v[26:29]
	v_mfma_f32_16x16x32_bf16 v[22:25], v[130:133], v[178:181], v[22:25]
	v_mfma_f32_16x16x32_bf16 v[22:25], v[134:137], v[182:185], v[22:25]
	v_mfma_f32_16x16x32_bf16 v[18:21], v[138:141], v[178:181], v[18:21]
	v_mfma_f32_16x16x32_bf16 v[18:21], v[142:145], v[182:185], v[18:21]
	v_mfma_f32_16x16x32_bf16 v[14:17], v[130:133], v[170:173], v[14:17]
	v_mfma_f32_16x16x32_bf16 v[14:17], v[134:137], v[174:177], v[14:17]
	v_mfma_f32_16x16x32_bf16 v[10:13], v[138:141], v[170:173], v[10:13]
	v_mfma_f32_16x16x32_bf16 v[10:13], v[142:145], v[174:177], v[10:13]
	v_mfma_f32_16x16x32_bf16 v[6:9], v[130:133], v[162:165], v[6:9]
	v_mfma_f32_16x16x32_bf16 v[6:9], v[134:137], v[166:169], v[6:9]
	s_setprio 2
	s_barrier
	v_mfma_f32_16x16x32_bf16 v[2:5], v[138:141], v[162:165], v[2:5]
	v_mfma_f32_16x16x32_bf16 v[2:5], v[142:145], v[166:169], v[2:5]
	s_setprio 0
	s_nop 0
	v_add_u32_e32 v142, 0x18000, v208
	v_add_u32_e32 v158, 0x1c000, v208
	ds_read_b128 v[130:133], v142
	ds_read_b128 v[134:137], v142 offset:1024
	ds_read_b128 v[138:141], v142 offset:2048
	ds_read_b128 v[142:145], v142 offset:3072
	ds_read_b128 v[146:149], v158
	ds_read_b128 v[150:153], v158 offset:1024
	ds_read_b128 v[154:157], v158 offset:2048
	ds_read_b128 v[158:161], v158 offset:3072
	ds_read_b128 v[162:165], v209 offset:32768
	ds_read_b128 v[166:169], v209 offset:33792
	ds_read_b128 v[170:173], v209 offset:34816
	ds_read_b128 v[174:177], v209 offset:35840
	ds_read_b128 v[178:181], v209 offset:36864
	ds_read_b128 v[182:185], v209 offset:37888
	ds_read_b128 v[186:189], v209 offset:38912
	ds_read_b128 v[190:193], v209 offset:39936
	s_add_u32 s48, s48, 0x4000
	s_addc_u32 s49, s49, 0
	s_mov_b32 m0, s60
	s_nop 0
	global_load_lds_dwordx4 v195, s[48:49]
	s_add_u32 m0, s60, 0x2000
	s_nop 0
	global_load_lds_dwordx4 v203, s[48:49]
	s_waitcnt vmcnt(8)
	s_waitcnt lgkmcnt(0)
	s_setprio 1
	s_barrier
	v_mfma_f32_16x16x32_bf16 v[126:129], v[130:133], v[162:165], v[126:129]
	v_mfma_f32_16x16x32_bf16 v[126:129], v[134:137], v[166:169], v[126:129]
	s_waitcnt lgkmcnt(5)
	v_mfma_f32_16x16x32_bf16 v[122:125], v[138:141], v[162:165], v[122:125]
	v_mfma_f32_16x16x32_bf16 v[122:125], v[142:145], v[166:169], v[122:125]
	s_waitcnt lgkmcnt(3)
	v_mfma_f32_16x16x32_bf16 v[118:121], v[130:133], v[170:173], v[118:121]
	v_mfma_f32_16x16x32_bf16 v[118:121], v[134:137], v[174:177], v[118:121]
	s_waitcnt lgkmcnt(1)
	v_mfma_f32_16x16x32_bf16 v[114:117], v[138:141], v[170:173], v[114:117]
	v_mfma_f32_16x16x32_bf16 v[114:117], v[142:145], v[174:177], v[114:117]
	v_mfma_f32_16x16x32_bf16 v[110:113], v[130:133], v[178:181], v[110:113]
	v_mfma_f32_16x16x32_bf16 v[110:113], v[134:137], v[182:185], v[110:113]
	v_mfma_f32_16x16x32_bf16 v[106:109], v[138:141], v[178:181], v[106:109]
	v_mfma_f32_16x16x32_bf16 v[106:109], v[142:145], v[182:185], v[106:109]
	v_mfma_f32_16x16x32_bf16 v[102:105], v[130:133], v[186:189], v[102:105]
	v_mfma_f32_16x16x32_bf16 v[102:105], v[134:137], v[190:193], v[102:105]
	s_waitcnt lgkmcnt(0)
	v_mfma_f32_16x16x32_bf16 v[98:101], v[138:141], v[186:189], v[98:101]
	v_mfma_f32_16x16x32_bf16 v[98:101], v[142:145], v[190:193], v[98:101]
	s_setprio 0
	s_setprio 1
	v_mfma_f32_16x16x32_bf16 v[94:97], v[146:149], v[162:165], v[94:97]
	v_mfma_f32_16x16x32_bf16 v[94:97], v[150:153], v[166:169], v[94:97]
	v_mfma_f32_16x16x32_bf16 v[90:93], v[154:157], v[162:165], v[90:93]
	v_mfma_f32_16x16x32_bf16 v[90:93], v[158:161], v[166:169], v[90:93]
	v_mfma_f32_16x16x32_bf16 v[86:89], v[146:149], v[170:173], v[86:89]
	v_mfma_f32_16x16x32_bf16 v[86:89], v[150:153], v[174:177], v[86:89]
	v_mfma_f32_16x16x32_bf16 v[82:85], v[154:157], v[170:173], v[82:85]
	v_mfma_f32_16x16x32_bf16 v[82:85], v[158:161], v[174:177], v[82:85]
	v_mfma_f32_16x16x32_bf16 v[78:81], v[146:149], v[178:181], v[78:81]
	v_mfma_f32_16x16x32_bf16 v[78:81], v[150:153], v[182:185], v[78:81]
	v_mfma_f32_16x16x32_bf16 v[74:77], v[154:157], v[178:181], v[74:77]
	v_mfma_f32_16x16x32_bf16 v[74:77], v[158:161], v[182:185], v[74:77]
	v_mfma_f32_16x16x32_bf16 v[70:73], v[146:149], v[186:189], v[70:73]
	v_mfma_f32_16x16x32_bf16 v[70:73], v[150:153], v[190:193], v[70:73]
	s_setprio 2
	s_barrier
	v_mfma_f32_16x16x32_bf16 v[66:69], v[154:157], v[186:189], v[66:69]
	v_mfma_f32_16x16x32_bf16 v[66:69], v[158:161], v[190:193], v[66:69]
	s_setprio 0
	s_nop 0
	ds_read_b128 v[162:165], v209 offset:49152
	ds_read_b128 v[166:169], v209 offset:50176
	ds_read_b128 v[170:173], v209 offset:51200
	ds_read_b128 v[174:177], v209 offset:52224
	ds_read_b128 v[178:181], v209 offset:53248
	ds_read_b128 v[182:185], v209 offset:54272
	ds_read_b128 v[186:189], v209 offset:55296
	ds_read_b128 v[190:193], v209 offset:56320
	s_mov_b32 m0, s64
	s_nop 0
	global_load_lds_dwordx4 v195, s[52:53]
	s_add_u32 m0, s64, 0x2000
	s_nop 0
	global_load_lds_dwordx4 v203, s[52:53]
	s_add_u32 s46, s46, 0xc000
	s_addc_u32 s47, s47, 0
	s_mov_b32 m0, s66
	s_nop 0
	global_load_lds_dwordx4 v195, s[46:47]
	s_add_u32 m0, s66, 0x2000
	s_nop 0
	global_load_lds_dwordx4 v203, s[46:47]
	s_nop 0
	s_mov_b32 m0, s65
	s_nop 0
	global_load_lds_dwordx4 v195, s[50:51]
	s_add_u32 m0, s65, 0x2000
	s_nop 0
	global_load_lds_dwordx4 v203, s[50:51]
	s_waitcnt vmcnt(8)
	s_waitcnt lgkmcnt(0)
	s_setprio 1
	s_barrier
	v_mfma_f32_16x16x32_bf16 v[62:65], v[130:133], v[162:165], v[62:65]
	v_mfma_f32_16x16x32_bf16 v[62:65], v[134:137], v[166:169], v[62:65]
	s_waitcnt lgkmcnt(5)
	v_mfma_f32_16x16x32_bf16 v[58:61], v[138:141], v[162:165], v[58:61]
	v_mfma_f32_16x16x32_bf16 v[58:61], v[142:145], v[166:169], v[58:61]
	s_waitcnt lgkmcnt(3)
	v_mfma_f32_16x16x32_bf16 v[54:57], v[130:133], v[170:173], v[54:57]
	v_mfma_f32_16x16x32_bf16 v[54:57], v[134:137], v[174:177], v[54:57]
	s_waitcnt lgkmcnt(1)
	v_mfma_f32_16x16x32_bf16 v[50:53], v[138:141], v[170:173], v[50:53]
	v_mfma_f32_16x16x32_bf16 v[50:53], v[142:145], v[174:177], v[50:53]
	v_mfma_f32_16x16x32_bf16 v[46:49], v[130:133], v[178:181], v[46:49]
	v_mfma_f32_16x16x32_bf16 v[46:49], v[134:137], v[182:185], v[46:49]
	v_mfma_f32_16x16x32_bf16 v[42:45], v[138:141], v[178:181], v[42:45]
	v_mfma_f32_16x16x32_bf16 v[42:45], v[142:145], v[182:185], v[42:45]
	v_mfma_f32_16x16x32_bf16 v[38:41], v[130:133], v[186:189], v[38:41]
	v_mfma_f32_16x16x32_bf16 v[38:41], v[134:137], v[190:193], v[38:41]
	s_waitcnt lgkmcnt(0)
	v_mfma_f32_16x16x32_bf16 v[34:37], v[138:141], v[186:189], v[34:37]
	v_mfma_f32_16x16x32_bf16 v[34:37], v[142:145], v[190:193], v[34:37]
	s_setprio 0
	s_setprio 1
	v_mfma_f32_16x16x32_bf16 v[30:33], v[146:149], v[162:165], v[30:33]
	v_mfma_f32_16x16x32_bf16 v[30:33], v[150:153], v[166:169], v[30:33]
	v_mfma_f32_16x16x32_bf16 v[26:29], v[154:157], v[162:165], v[26:29]
	v_mfma_f32_16x16x32_bf16 v[26:29], v[158:161], v[166:169], v[26:29]
	v_mfma_f32_16x16x32_bf16 v[22:25], v[146:149], v[170:173], v[22:25]
	v_mfma_f32_16x16x32_bf16 v[22:25], v[150:153], v[174:177], v[22:25]
	v_mfma_f32_16x16x32_bf16 v[18:21], v[154:157], v[170:173], v[18:21]
	v_mfma_f32_16x16x32_bf16 v[18:21], v[158:161], v[174:177], v[18:21]
	v_mfma_f32_16x16x32_bf16 v[14:17], v[146:149], v[178:181], v[14:17]
	v_mfma_f32_16x16x32_bf16 v[14:17], v[150:153], v[182:185], v[14:17]
	v_mfma_f32_16x16x32_bf16 v[10:13], v[154:157], v[178:181], v[10:13]
	v_mfma_f32_16x16x32_bf16 v[10:13], v[158:161], v[182:185], v[10:13]
	v_mfma_f32_16x16x32_bf16 v[6:9], v[146:149], v[186:189], v[6:9]
	v_mfma_f32_16x16x32_bf16 v[6:9], v[150:153], v[190:193], v[6:9]
	s_setprio 2
	s_barrier
	v_mfma_f32_16x16x32_bf16 v[2:5], v[154:157], v[186:189], v[2:5]
	v_mfma_f32_16x16x32_bf16 v[2:5], v[158:161], v[190:193], v[2:5]
	s_setprio 0
	s_nop 0
	s_add_i32 s13, s77, 2
	s_cmp_gt_u32 s77, 13
	s_cbranch_scc1 .LBB0_1716
	s_mov_b32 s77, s13
	s_branch .LBB0_1693

.LBB0_1919:
	s_or_b64 exec, exec, s[10:11]
	s_add_u32 s50, s16, s6
	ds_read_b128 v[134:137], v201
	ds_read_b128 v[138:141], v201 offset:1024
	ds_read_b128 v[142:145], v201 offset:2048
	ds_read_b128 v[146:149], v201 offset:3072
	ds_read_b128 v[150:153], v202
	ds_read_b128 v[154:157], v202 offset:1024
	ds_read_b128 v[162:165], v202 offset:2048
	ds_read_b128 v[166:169], v202 offset:3072
	s_addc_u32 s51, s17, s7
	s_add_u32 s10, s50, 0x20000
	s_addc_u32 s11, s51, 0
	s_add_u32 s42, s75, s6
	s_addc_u32 s43, s76, s7
	s_cmp_eq_u32 s6, 0x60000
	s_cselect_b32 s46, s29, s10
	s_cselect_b32 s47, s20, s11
	s_cselect_b32 s11, s27, s43
	s_cselect_b32 s10, s48, s42
	s_add_u32 s42, s46, 0x8000
	s_addc_u32 s43, s47, 0
	s_add_u32 s44, s10, 0x8000
	s_addc_u32 s45, s11, 0
	ds_read_b128 v[170:173], v203
	ds_read_b128 v[174:177], v203 offset:1024
	ds_read_b128 v[178:181], v203 offset:2048
	ds_read_b128 v[182:185], v203 offset:3072
	ds_read_b128 v[186:189], v203 offset:4096
	ds_read_b128 v[190:193], v203 offset:5120
	ds_read_b128 v[212:215], v203 offset:6144
	ds_read_b128 v[216:219], v203 offset:7168
	s_add_u32 s50, s50, 0x1c000
	s_addc_u32 s51, s51, 0
	s_mov_b32 m0, s65
	s_nop 0
	global_load_lds_dwordx4 v195, s[50:51]
	s_add_u32 m0, s65, 0x2000
	s_nop 0
	global_load_lds_dwordx4 v197, s[50:51]
	s_waitcnt vmcnt(8)
	s_waitcnt lgkmcnt(0)
	s_setprio 1
	s_barrier
	v_mfma_f32_16x16x32_bf16 v[130:133], v[134:137], v[170:173], v[130:133]
	v_mfma_f32_16x16x32_bf16 v[126:129], v[142:145], v[170:173], v[126:129]
	s_waitcnt lgkmcnt(5)
	v_mfma_f32_16x16x32_bf16 v[110:113], v[134:137], v[178:181], v[110:113]
	v_mfma_f32_16x16x32_bf16 v[106:109], v[142:145], v[178:181], v[106:109]
	s_waitcnt lgkmcnt(3)
	v_mfma_f32_16x16x32_bf16 v[94:97], v[134:137], v[186:189], v[94:97]
	v_mfma_f32_16x16x32_bf16 v[90:93], v[142:145], v[186:189], v[90:93]
	s_waitcnt lgkmcnt(1)
	v_mfma_f32_16x16x32_bf16 v[78:81], v[134:137], v[212:215], v[78:81]
	v_mfma_f32_16x16x32_bf16 v[74:77], v[142:145], v[212:215], v[74:77]
	v_mfma_f32_16x16x32_bf16 v[130:133], v[138:141], v[174:177], v[130:133]
	v_mfma_f32_16x16x32_bf16 v[126:129], v[146:149], v[174:177], v[126:129]
	v_mfma_f32_16x16x32_bf16 v[110:113], v[138:141], v[182:185], v[110:113]
	v_mfma_f32_16x16x32_bf16 v[106:109], v[146:149], v[182:185], v[106:109]
	v_mfma_f32_16x16x32_bf16 v[94:97], v[138:141], v[190:193], v[94:97]
	v_mfma_f32_16x16x32_bf16 v[90:93], v[146:149], v[190:193], v[90:93]
	s_waitcnt lgkmcnt(0)
	v_mfma_f32_16x16x32_bf16 v[78:81], v[138:141], v[216:219], v[78:81]
	v_mfma_f32_16x16x32_bf16 v[74:77], v[146:149], v[216:219], v[74:77]
	s_setprio 0
	s_setprio 1
	v_mfma_f32_16x16x32_bf16 v[122:125], v[150:153], v[170:173], v[122:125]
	v_mfma_f32_16x16x32_bf16 v[116:119], v[162:165], v[170:173], v[118:121]
	v_mfma_f32_16x16x32_bf16 v[102:105], v[150:153], v[178:181], v[102:105]
	v_mfma_f32_16x16x32_bf16 v[98:101], v[162:165], v[178:181], v[98:101]
	v_mfma_f32_16x16x32_bf16 v[86:89], v[150:153], v[186:189], v[86:89]
	v_mfma_f32_16x16x32_bf16 v[82:85], v[162:165], v[186:189], v[82:85]
	v_mfma_f32_16x16x32_bf16 v[70:73], v[150:153], v[212:215], v[70:73]
	v_mfma_f32_16x16x32_bf16 v[66:69], v[162:165], v[212:215], v[66:69]
	v_mfma_f32_16x16x32_bf16 v[122:125], v[154:157], v[174:177], v[122:125]
	v_mfma_f32_16x16x32_bf16 v[116:119], v[166:169], v[174:177], v[116:119]
	v_mfma_f32_16x16x32_bf16 v[102:105], v[154:157], v[182:185], v[102:105]
	v_mfma_f32_16x16x32_bf16 v[98:101], v[166:169], v[182:185], v[98:101]
	v_mfma_f32_16x16x32_bf16 v[86:89], v[154:157], v[190:193], v[86:89]
	v_mfma_f32_16x16x32_bf16 v[82:85], v[166:169], v[190:193], v[82:85]
	s_setprio 2
	s_barrier
	v_mfma_f32_16x16x32_bf16 v[70:73], v[154:157], v[216:219], v[70:73]
	v_mfma_f32_16x16x32_bf16 v[66:69], v[166:169], v[216:219], v[66:69]
	s_setprio 0
	s_nop 0
	ds_read_b128 v[170:173], v203 offset:16384
	ds_read_b128 v[174:177], v203 offset:17408
	ds_read_b128 v[178:181], v203 offset:18432
	ds_read_b128 v[182:185], v203 offset:19456
	ds_read_b128 v[186:189], v203 offset:20480
	ds_read_b128 v[190:193], v203 offset:21504
	ds_read_b128 v[212:215], v203 offset:22528
	ds_read_b128 v[216:219], v203 offset:23552
	s_mov_b32 m0, s13
	s_nop 0
	global_load_lds_dwordx4 v195, s[10:11]
	s_add_u32 m0, s13, 0x2000
	s_nop 0
	global_load_lds_dwordx4 v197, s[10:11]
	s_add_u32 s50, s10, 0x4000
	s_addc_u32 s51, s11, 0
	s_mov_b32 m0, s57
	s_nop 0
	global_load_lds_dwordx4 v195, s[50:51]
	s_add_u32 m0, s57, 0x2000
	s_nop 0
	global_load_lds_dwordx4 v197, s[50:51]
	s_nop 0
	s_mov_b32 m0, s56
	s_nop 0
	global_load_lds_dwordx4 v195, s[46:47]
	s_add_u32 m0, s56, 0x2000
	s_nop 0
	global_load_lds_dwordx4 v197, s[46:47]
	s_waitcnt vmcnt(8)
	s_waitcnt lgkmcnt(0)
	s_setprio 1
	s_barrier
	v_mfma_f32_16x16x32_bf16 v[62:65], v[134:137], v[170:173], v[62:65]
	v_mfma_f32_16x16x32_bf16 v[62:65], v[138:141], v[174:177], v[62:65]
	s_waitcnt lgkmcnt(5)
	v_mfma_f32_16x16x32_bf16 v[58:61], v[142:145], v[170:173], v[58:61]
	v_mfma_f32_16x16x32_bf16 v[58:61], v[146:149], v[174:177], v[58:61]
	s_waitcnt lgkmcnt(3)
	v_mfma_f32_16x16x32_bf16 v[46:49], v[134:137], v[178:181], v[46:49]
	v_mfma_f32_16x16x32_bf16 v[46:49], v[138:141], v[182:185], v[46:49]
	s_waitcnt lgkmcnt(1)
	v_mfma_f32_16x16x32_bf16 v[42:45], v[142:145], v[178:181], v[42:45]
	v_mfma_f32_16x16x32_bf16 v[42:45], v[146:149], v[182:185], v[42:45]
	v_mfma_f32_16x16x32_bf16 v[30:33], v[134:137], v[186:189], v[30:33]
	v_mfma_f32_16x16x32_bf16 v[30:33], v[138:141], v[190:193], v[30:33]
	v_mfma_f32_16x16x32_bf16 v[26:29], v[142:145], v[186:189], v[26:29]
	v_mfma_f32_16x16x32_bf16 v[26:29], v[146:149], v[190:193], v[26:29]
	v_mfma_f32_16x16x32_bf16 v[14:17], v[134:137], v[212:215], v[14:17]
	v_mfma_f32_16x16x32_bf16 v[14:17], v[138:141], v[216:219], v[14:17]
	s_waitcnt lgkmcnt(0)
	v_mfma_f32_16x16x32_bf16 v[10:13], v[142:145], v[212:215], v[10:13]
	v_mfma_f32_16x16x32_bf16 v[10:13], v[146:149], v[216:219], v[10:13]
	s_setprio 0
	s_setprio 1
	v_mfma_f32_16x16x32_bf16 v[54:57], v[150:153], v[170:173], v[54:57]
	v_mfma_f32_16x16x32_bf16 v[54:57], v[154:157], v[174:177], v[54:57]
	v_mfma_f32_16x16x32_bf16 v[50:53], v[162:165], v[170:173], v[50:53]
	v_mfma_f32_16x16x32_bf16 v[50:53], v[166:169], v[174:177], v[50:53]
	v_mfma_f32_16x16x32_bf16 v[38:41], v[150:153], v[178:181], v[38:41]
	v_mfma_f32_16x16x32_bf16 v[38:41], v[154:157], v[182:185], v[38:41]
	v_mfma_f32_16x16x32_bf16 v[34:37], v[162:165], v[178:181], v[34:37]
	v_mfma_f32_16x16x32_bf16 v[34:37], v[166:169], v[182:185], v[34:37]
	v_mfma_f32_16x16x32_bf16 v[22:25], v[150:153], v[186:189], v[22:25]
	v_mfma_f32_16x16x32_bf16 v[22:25], v[154:157], v[190:193], v[22:25]
	v_mfma_f32_16x16x32_bf16 v[18:21], v[162:165], v[186:189], v[18:21]
	v_mfma_f32_16x16x32_bf16 v[18:21], v[166:169], v[190:193], v[18:21]
	v_mfma_f32_16x16x32_bf16 v[6:9], v[150:153], v[212:215], v[6:9]
	v_mfma_f32_16x16x32_bf16 v[6:9], v[154:157], v[216:219], v[6:9]
	s_setprio 2
	s_barrier
	v_mfma_f32_16x16x32_bf16 v[2:5], v[162:165], v[212:215], v[2:5]
	v_mfma_f32_16x16x32_bf16 v[2:5], v[166:169], v[216:219], v[2:5]
	s_setprio 0
	s_nop 0
	ds_read_b128 v[134:137], v204
	ds_read_b128 v[138:141], v204 offset:1024
	ds_read_b128 v[142:145], v204 offset:2048
	ds_read_b128 v[146:149], v204 offset:3072
	ds_read_b128 v[150:153], v205
	ds_read_b128 v[154:157], v205 offset:1024
	ds_read_b128 v[162:165], v205 offset:2048
	ds_read_b128 v[166:169], v205 offset:3072
	ds_read_b128 v[170:173], v203 offset:32768
	ds_read_b128 v[174:177], v203 offset:33792
	ds_read_b128 v[178:181], v203 offset:34816
	ds_read_b128 v[182:185], v203 offset:35840
	ds_read_b128 v[186:189], v203 offset:36864
	ds_read_b128 v[190:193], v203 offset:37888
	ds_read_b128 v[212:215], v203 offset:38912
	ds_read_b128 v[216:219], v203 offset:39936
	s_add_u32 s46, s46, 0x4000
	s_addc_u32 s47, s47, 0
	s_mov_b32 m0, s58
	s_nop 0
	global_load_lds_dwordx4 v195, s[46:47]
	s_add_u32 m0, s58, 0x2000
	s_nop 0
	global_load_lds_dwordx4 v197, s[46:47]
	s_waitcnt vmcnt(8)
	s_waitcnt lgkmcnt(0)
	s_setprio 1
	s_barrier
	v_mfma_f32_16x16x32_bf16 v[130:133], v[134:137], v[170:173], v[130:133]
	v_mfma_f32_16x16x32_bf16 v[126:129], v[142:145], v[170:173], v[126:129]
	s_waitcnt lgkmcnt(5)
	v_mfma_f32_16x16x32_bf16 v[110:113], v[134:137], v[178:181], v[110:113]
	v_mfma_f32_16x16x32_bf16 v[106:109], v[142:145], v[178:181], v[106:109]
	s_waitcnt lgkmcnt(3)
	v_mfma_f32_16x16x32_bf16 v[94:97], v[134:137], v[186:189], v[94:97]
	v_mfma_f32_16x16x32_bf16 v[90:93], v[142:145], v[186:189], v[90:93]
	s_waitcnt lgkmcnt(1)
	v_mfma_f32_16x16x32_bf16 v[78:81], v[134:137], v[212:215], v[78:81]
	v_mfma_f32_16x16x32_bf16 v[74:77], v[142:145], v[212:215], v[74:77]
	v_mfma_f32_16x16x32_bf16 v[130:133], v[138:141], v[174:177], v[130:133]
	v_mfma_f32_16x16x32_bf16 v[126:129], v[146:149], v[174:177], v[126:129]
	v_mfma_f32_16x16x32_bf16 v[110:113], v[138:141], v[182:185], v[110:113]
	v_mfma_f32_16x16x32_bf16 v[106:109], v[146:149], v[182:185], v[106:109]
	v_mfma_f32_16x16x32_bf16 v[94:97], v[138:141], v[190:193], v[94:97]
	v_mfma_f32_16x16x32_bf16 v[90:93], v[146:149], v[190:193], v[90:93]
	s_waitcnt lgkmcnt(0)
	v_mfma_f32_16x16x32_bf16 v[78:81], v[138:141], v[216:219], v[78:81]
	v_mfma_f32_16x16x32_bf16 v[74:77], v[146:149], v[216:219], v[74:77]
	s_setprio 0
	s_setprio 1
	v_mfma_f32_16x16x32_bf16 v[120:123], v[150:153], v[170:173], v[122:125]
	v_mfma_f32_16x16x32_bf16 v[116:119], v[162:165], v[170:173], v[116:119]
	v_mfma_f32_16x16x32_bf16 v[102:105], v[150:153], v[178:181], v[102:105]
	v_mfma_f32_16x16x32_bf16 v[98:101], v[162:165], v[178:181], v[98:101]
	v_mfma_f32_16x16x32_bf16 v[86:89], v[150:153], v[186:189], v[86:89]
	v_mfma_f32_16x16x32_bf16 v[82:85], v[162:165], v[186:189], v[82:85]
	v_mfma_f32_16x16x32_bf16 v[70:73], v[150:153], v[212:215], v[70:73]
	v_mfma_f32_16x16x32_bf16 v[66:69], v[162:165], v[212:215], v[66:69]
	v_mfma_f32_16x16x32_bf16 v[122:125], v[154:157], v[174:177], v[120:123]
	v_mfma_f32_16x16x32_bf16 v[118:121], v[166:169], v[174:177], v[116:119]
	v_mfma_f32_16x16x32_bf16 v[102:105], v[154:157], v[182:185], v[102:105]
	v_mfma_f32_16x16x32_bf16 v[98:101], v[166:169], v[182:185], v[98:101]
	v_mfma_f32_16x16x32_bf16 v[86:89], v[154:157], v[190:193], v[86:89]
	v_mfma_f32_16x16x32_bf16 v[82:85], v[166:169], v[190:193], v[82:85]
	s_setprio 2
	s_barrier
	v_mfma_f32_16x16x32_bf16 v[70:73], v[154:157], v[216:219], v[70:73]
	v_mfma_f32_16x16x32_bf16 v[66:69], v[166:169], v[216:219], v[66:69]
	s_setprio 0
	s_nop 0
	ds_read_b128 v[170:173], v203 offset:49152
	ds_read_b128 v[174:177], v203 offset:50176
	ds_read_b128 v[178:181], v203 offset:51200
	ds_read_b128 v[182:185], v203 offset:52224
	ds_read_b128 v[186:189], v203 offset:53248
	ds_read_b128 v[190:193], v203 offset:54272
	ds_read_b128 v[212:215], v203 offset:55296
	ds_read_b128 v[216:219], v203 offset:56320
	s_mov_b32 m0, s62
	s_nop 0
	global_load_lds_dwordx4 v195, s[44:45]
	s_add_u32 m0, s62, 0x2000
	s_nop 0
	global_load_lds_dwordx4 v197, s[44:45]
	s_add_u32 s10, s10, 0xc000
	s_addc_u32 s11, s11, 0
	s_mov_b32 m0, s64
	s_nop 0
	global_load_lds_dwordx4 v195, s[10:11]
	s_add_u32 m0, s64, 0x2000
	s_nop 0
	global_load_lds_dwordx4 v197, s[10:11]
	s_nop 0
	s_mov_b32 m0, s63
	s_nop 0
	global_load_lds_dwordx4 v195, s[42:43]
	s_add_u32 m0, s63, 0x2000
	s_nop 0
	global_load_lds_dwordx4 v197, s[42:43]
	s_waitcnt vmcnt(8)
	s_waitcnt lgkmcnt(0)
	s_setprio 1
	s_barrier
	v_mfma_f32_16x16x32_bf16 v[62:65], v[134:137], v[170:173], v[62:65]
	v_mfma_f32_16x16x32_bf16 v[62:65], v[138:141], v[174:177], v[62:65]
	s_waitcnt lgkmcnt(5)
	v_mfma_f32_16x16x32_bf16 v[58:61], v[142:145], v[170:173], v[58:61]
	v_mfma_f32_16x16x32_bf16 v[58:61], v[146:149], v[174:177], v[58:61]
	s_waitcnt lgkmcnt(3)
	v_mfma_f32_16x16x32_bf16 v[46:49], v[134:137], v[178:181], v[46:49]
	v_mfma_f32_16x16x32_bf16 v[46:49], v[138:141], v[182:185], v[46:49]
	s_waitcnt lgkmcnt(1)
	v_mfma_f32_16x16x32_bf16 v[42:45], v[142:145], v[178:181], v[42:45]
	v_mfma_f32_16x16x32_bf16 v[42:45], v[146:149], v[182:185], v[42:45]
	v_mfma_f32_16x16x32_bf16 v[30:33], v[134:137], v[186:189], v[30:33]
	v_mfma_f32_16x16x32_bf16 v[30:33], v[138:141], v[190:193], v[30:33]
	v_mfma_f32_16x16x32_bf16 v[26:29], v[142:145], v[186:189], v[26:29]
	v_mfma_f32_16x16x32_bf16 v[26:29], v[146:149], v[190:193], v[26:29]
	v_mfma_f32_16x16x32_bf16 v[14:17], v[134:137], v[212:215], v[14:17]
	v_mfma_f32_16x16x32_bf16 v[14:17], v[138:141], v[216:219], v[14:17]
	s_waitcnt lgkmcnt(0)
	v_mfma_f32_16x16x32_bf16 v[10:13], v[142:145], v[212:215], v[10:13]
	v_mfma_f32_16x16x32_bf16 v[10:13], v[146:149], v[216:219], v[10:13]
	s_setprio 0
	s_setprio 1
	v_mfma_f32_16x16x32_bf16 v[54:57], v[150:153], v[170:173], v[54:57]
	v_mfma_f32_16x16x32_bf16 v[54:57], v[154:157], v[174:177], v[54:57]
	v_mfma_f32_16x16x32_bf16 v[50:53], v[162:165], v[170:173], v[50:53]
	v_mfma_f32_16x16x32_bf16 v[50:53], v[166:169], v[174:177], v[50:53]
	v_mfma_f32_16x16x32_bf16 v[38:41], v[150:153], v[178:181], v[38:41]
	v_mfma_f32_16x16x32_bf16 v[38:41], v[154:157], v[182:185], v[38:41]
	v_mfma_f32_16x16x32_bf16 v[34:37], v[162:165], v[178:181], v[34:37]
	v_mfma_f32_16x16x32_bf16 v[34:37], v[166:169], v[182:185], v[34:37]
	v_mfma_f32_16x16x32_bf16 v[22:25], v[150:153], v[186:189], v[22:25]
	v_mfma_f32_16x16x32_bf16 v[22:25], v[154:157], v[190:193], v[22:25]
	v_mfma_f32_16x16x32_bf16 v[18:21], v[162:165], v[186:189], v[18:21]
	v_mfma_f32_16x16x32_bf16 v[18:21], v[166:169], v[190:193], v[18:21]
	v_mfma_f32_16x16x32_bf16 v[6:9], v[150:153], v[212:215], v[6:9]
	v_mfma_f32_16x16x32_bf16 v[6:9], v[154:157], v[216:219], v[6:9]
	s_setprio 2
	s_barrier
	v_mfma_f32_16x16x32_bf16 v[2:5], v[162:165], v[212:215], v[2:5]
	v_mfma_f32_16x16x32_bf16 v[2:5], v[166:169], v[216:219], v[2:5]
	s_setprio 0
	s_nop 0
	s_add_i32 s49, s49, 2
	s_add_u32 s6, s6, 0x10000
	s_addc_u32 s7, s7, 0
	s_cmp_gt_u32 s49, 13
	v_mov_b32_e32 v115, v114
	s_cbranch_scc1 .LBB0_1922

.LBB0_2120:
	s_add_u32 s56, s52, 0x10000
	s_addc_u32 s57, s53, 0
	s_and_b64 s[52:53], s[50:51], exec
	s_cselect_b32 s53, s57, s43
	s_cselect_b32 s52, s56, s88
	s_add_u32 s15, s18, s15
	s_addc_u32 s56, s19, 0
	s_add_u32 s15, s15, 0x10000
	s_waitcnt vmcnt(8)
	s_addc_u32 s56, s56, 0
	s_waitcnt lgkmcnt(0)
	s_and_b64 s[50:51], s[50:51], exec
	s_cselect_b32 s51, s56, s41
	s_cselect_b32 s50, s15, s89
	s_setprio 1
	s_barrier
	v_mfma_f32_16x16x32_bf16 v[126:129], v[146:149], v[186:189], v[126:129]
	v_mfma_f32_16x16x32_bf16 v[126:129], v[150:153], v[190:193], v[126:129]
	s_waitcnt lgkmcnt(5)
	v_mfma_f32_16x16x32_bf16 v[122:125], v[154:157], v[186:189], v[122:125]
	v_mfma_f32_16x16x32_bf16 v[122:125], v[158:161], v[190:193], v[122:125]
	s_waitcnt lgkmcnt(3)
	v_mfma_f32_16x16x32_bf16 v[118:121], v[146:149], v[178:181], v[118:121]
	v_mfma_f32_16x16x32_bf16 v[118:121], v[150:153], v[182:185], v[118:121]
	s_waitcnt lgkmcnt(1)
	v_mfma_f32_16x16x32_bf16 v[114:117], v[154:157], v[178:181], v[114:117]
	v_mfma_f32_16x16x32_bf16 v[114:117], v[158:161], v[182:185], v[114:117]
	v_mfma_f32_16x16x32_bf16 v[110:113], v[146:149], v[170:173], v[110:113]
	v_mfma_f32_16x16x32_bf16 v[110:113], v[150:153], v[174:177], v[110:113]
	v_mfma_f32_16x16x32_bf16 v[106:109], v[154:157], v[170:173], v[106:109]
	v_mfma_f32_16x16x32_bf16 v[106:109], v[158:161], v[174:177], v[106:109]
	v_mfma_f32_16x16x32_bf16 v[102:105], v[146:149], v[162:165], v[102:105]
	v_mfma_f32_16x16x32_bf16 v[102:105], v[150:153], v[166:169], v[102:105]
	s_waitcnt lgkmcnt(0)
	v_mfma_f32_16x16x32_bf16 v[98:101], v[154:157], v[162:165], v[98:101]
	v_mfma_f32_16x16x32_bf16 v[98:101], v[158:161], v[166:169], v[98:101]
	s_setprio 0
	s_setprio 1
	v_mfma_f32_16x16x32_bf16 v[94:97], v[130:133], v[186:189], v[94:97]
	v_mfma_f32_16x16x32_bf16 v[94:97], v[134:137], v[190:193], v[94:97]
	v_mfma_f32_16x16x32_bf16 v[90:93], v[138:141], v[186:189], v[90:93]
	v_mfma_f32_16x16x32_bf16 v[90:93], v[142:145], v[190:193], v[90:93]
	v_mfma_f32_16x16x32_bf16 v[86:89], v[130:133], v[178:181], v[86:89]
	v_mfma_f32_16x16x32_bf16 v[86:89], v[134:137], v[182:185], v[86:89]
	v_mfma_f32_16x16x32_bf16 v[82:85], v[138:141], v[178:181], v[82:85]
	v_mfma_f32_16x16x32_bf16 v[82:85], v[142:145], v[182:185], v[82:85]
	v_mfma_f32_16x16x32_bf16 v[78:81], v[130:133], v[170:173], v[78:81]
	v_mfma_f32_16x16x32_bf16 v[78:81], v[134:137], v[174:177], v[78:81]
	v_mfma_f32_16x16x32_bf16 v[74:77], v[138:141], v[170:173], v[74:77]
	v_mfma_f32_16x16x32_bf16 v[74:77], v[142:145], v[174:177], v[74:77]
	v_mfma_f32_16x16x32_bf16 v[70:73], v[130:133], v[162:165], v[70:73]
	v_mfma_f32_16x16x32_bf16 v[70:73], v[134:137], v[166:169], v[70:73]
	s_setprio 2
	s_barrier
	v_mfma_f32_16x16x32_bf16 v[66:69], v[138:141], v[162:165], v[66:69]
	v_mfma_f32_16x16x32_bf16 v[66:69], v[142:145], v[166:169], v[66:69]
	s_setprio 0
	s_nop 0
	ds_read_b128 v[186:189], v207 offset:16384
	ds_read_b128 v[190:193], v207 offset:17408
	ds_read_b128 v[178:181], v207 offset:18432
	ds_read_b128 v[182:185], v207 offset:19456
	ds_read_b128 v[170:173], v207 offset:20480
	ds_read_b128 v[174:177], v207 offset:21504
	ds_read_b128 v[162:165], v207 offset:22528
	ds_read_b128 v[166:169], v207 offset:23552
	s_mov_b32 m0, s62
	s_nop 0
	global_load_lds_dwordx4 v195, s[50:51]
	s_add_u32 m0, s62, 0x2000
	s_nop 0
	global_load_lds_dwordx4 v197, s[50:51]
	s_add_u32 s56, s50, 0x4000
	s_addc_u32 s57, s51, 0
	s_mov_b32 m0, s63
	s_nop 0
	global_load_lds_dwordx4 v195, s[56:57]
	s_add_u32 m0, s63, 0x2000
	s_nop 0
	global_load_lds_dwordx4 v197, s[56:57]
	s_andn2_b64 vcc, exec, s[54:55]
	s_mov_b32 m0, s61
	s_nop 0
	global_load_lds_dwordx4 v195, s[52:53]
	s_add_u32 m0, s61, 0x2000
	s_nop 0
	global_load_lds_dwordx4 v197, s[52:53]
	s_cbranch_vccnz .LBB0_2122
	v_mov_b32_e32 v2, 0
	v_mov_b32_e32 v3, v2
	v_mov_b32_e32 v4, v2
	v_mov_b32_e32 v5, v2
	v_mov_b32_e32 v6, v2
	v_mov_b32_e32 v7, v2
	v_mov_b32_e32 v8, v2
	v_mov_b32_e32 v9, v2
	v_mov_b32_e32 v10, v2
	v_mov_b32_e32 v11, v2
	v_mov_b32_e32 v12, v2
	v_mov_b32_e32 v13, v2
	v_mov_b32_e32 v14, v2
	v_mov_b32_e32 v15, v2
	v_mov_b32_e32 v16, v2
	v_mov_b32_e32 v17, v2
	v_mov_b32_e32 v18, v2
	v_mov_b32_e32 v19, v2
	v_mov_b32_e32 v20, v2
	v_mov_b32_e32 v21, v2
	v_mov_b32_e32 v22, v2
	v_mov_b32_e32 v23, v2
	v_mov_b32_e32 v24, v2
	v_mov_b32_e32 v25, v2
	v_mov_b32_e32 v26, v2
	v_mov_b32_e32 v27, v2
	v_mov_b32_e32 v28, v2
	v_mov_b32_e32 v29, v2
	v_mov_b32_e32 v30, v2
	v_mov_b32_e32 v31, v2
	v_mov_b32_e32 v32, v2
	v_mov_b32_e32 v33, v2
	v_mov_b32_e32 v34, v2
	v_mov_b32_e32 v35, v2
	v_mov_b32_e32 v36, v2
	v_mov_b32_e32 v37, v2
	v_mov_b32_e32 v38, v2
	v_mov_b32_e32 v39, v2
	v_mov_b32_e32 v40, v2
	v_mov_b32_e32 v41, v2
	v_mov_b32_e32 v42, v2
	v_mov_b32_e32 v43, v2
	v_mov_b32_e32 v44, v2
	v_mov_b32_e32 v45, v2
	v_mov_b32_e32 v46, v2
	v_mov_b32_e32 v47, v2
	v_mov_b32_e32 v48, v2
	v_mov_b32_e32 v49, v2
	v_mov_b32_e32 v50, v2
	v_mov_b32_e32 v51, v2
	v_mov_b32_e32 v52, v2
	v_mov_b32_e32 v53, v2
	v_mov_b32_e32 v54, v2
	v_mov_b32_e32 v55, v2
	v_mov_b32_e32 v56, v2
	v_mov_b32_e32 v57, v2
	v_mov_b32_e32 v58, v2
	v_mov_b32_e32 v59, v2
	v_mov_b32_e32 v60, v2
	v_mov_b32_e32 v61, v2
	v_mov_b32_e32 v62, v2
	v_mov_b32_e32 v63, v2
	v_mov_b32_e32 v64, v2
	v_mov_b32_e32 v65, v2
.LBB0_2122:
	s_waitcnt vmcnt(8)
	s_add_u32 s54, s52, 0x8000
	s_waitcnt lgkmcnt(0)
	s_addc_u32 s55, s53, 0
	s_add_u32 s56, s50, 0x8000
	s_addc_u32 s57, s51, 0
	s_setprio 1
	s_barrier
	v_mfma_f32_16x16x32_bf16 v[62:65], v[146:149], v[186:189], v[62:65]
	v_mfma_f32_16x16x32_bf16 v[62:65], v[150:153], v[190:193], v[62:65]
	s_waitcnt lgkmcnt(5)
	v_mfma_f32_16x16x32_bf16 v[58:61], v[154:157], v[186:189], v[58:61]
	v_mfma_f32_16x16x32_bf16 v[58:61], v[158:161], v[190:193], v[58:61]
	s_waitcnt lgkmcnt(3)
	v_mfma_f32_16x16x32_bf16 v[54:57], v[146:149], v[178:181], v[54:57]
	v_mfma_f32_16x16x32_bf16 v[54:57], v[150:153], v[182:185], v[54:57]
	s_waitcnt lgkmcnt(1)
	v_mfma_f32_16x16x32_bf16 v[50:53], v[154:157], v[178:181], v[50:53]
	v_mfma_f32_16x16x32_bf16 v[50:53], v[158:161], v[182:185], v[50:53]
	v_mfma_f32_16x16x32_bf16 v[46:49], v[146:149], v[170:173], v[46:49]
	v_mfma_f32_16x16x32_bf16 v[46:49], v[150:153], v[174:177], v[46:49]
	v_mfma_f32_16x16x32_bf16 v[42:45], v[154:157], v[170:173], v[42:45]
	v_mfma_f32_16x16x32_bf16 v[42:45], v[158:161], v[174:177], v[42:45]
	v_mfma_f32_16x16x32_bf16 v[38:41], v[146:149], v[162:165], v[38:41]
	v_mfma_f32_16x16x32_bf16 v[38:41], v[150:153], v[166:169], v[38:41]
	s_waitcnt lgkmcnt(0)
	v_mfma_f32_16x16x32_bf16 v[34:37], v[154:157], v[162:165], v[34:37]
	v_mfma_f32_16x16x32_bf16 v[34:37], v[158:161], v[166:169], v[34:37]
	s_setprio 0
	s_setprio 1
	v_mfma_f32_16x16x32_bf16 v[30:33], v[130:133], v[186:189], v[30:33]
	v_mfma_f32_16x16x32_bf16 v[30:33], v[134:137], v[190:193], v[30:33]
	v_mfma_f32_16x16x32_bf16 v[26:29], v[138:141], v[186:189], v[26:29]
	v_mfma_f32_16x16x32_bf16 v[26:29], v[142:145], v[190:193], v[26:29]
	v_mfma_f32_16x16x32_bf16 v[22:25], v[130:133], v[178:181], v[22:25]
	v_mfma_f32_16x16x32_bf16 v[22:25], v[134:137], v[182:185], v[22:25]
	v_mfma_f32_16x16x32_bf16 v[18:21], v[138:141], v[178:181], v[18:21]
	v_mfma_f32_16x16x32_bf16 v[18:21], v[142:145], v[182:185], v[18:21]
	v_mfma_f32_16x16x32_bf16 v[14:17], v[130:133], v[170:173], v[14:17]
	v_mfma_f32_16x16x32_bf16 v[14:17], v[134:137], v[174:177], v[14:17]
	v_mfma_f32_16x16x32_bf16 v[10:13], v[138:141], v[170:173], v[10:13]
	v_mfma_f32_16x16x32_bf16 v[10:13], v[142:145], v[174:177], v[10:13]
	v_mfma_f32_16x16x32_bf16 v[6:9], v[130:133], v[162:165], v[6:9]
	v_mfma_f32_16x16x32_bf16 v[6:9], v[134:137], v[166:169], v[6:9]
	s_setprio 2
	s_barrier
	v_mfma_f32_16x16x32_bf16 v[2:5], v[138:141], v[162:165], v[2:5]
	v_mfma_f32_16x16x32_bf16 v[2:5], v[142:145], v[166:169], v[2:5]
	s_setprio 0
	s_nop 0
	v_add_u32_e32 v142, 0x18000, v206
	v_add_u32_e32 v158, 0x1c000, v206
	ds_read_b128 v[130:133], v142
	ds_read_b128 v[134:137], v142 offset:1024
	ds_read_b128 v[138:141], v142 offset:2048
	ds_read_b128 v[142:145], v142 offset:3072
	ds_read_b128 v[146:149], v158
	ds_read_b128 v[150:153], v158 offset:1024
	ds_read_b128 v[154:157], v158 offset:2048
	ds_read_b128 v[158:161], v158 offset:3072
	ds_read_b128 v[162:165], v207 offset:32768
	ds_read_b128 v[166:169], v207 offset:33792
	ds_read_b128 v[170:173], v207 offset:34816
	ds_read_b128 v[174:177], v207 offset:35840
	ds_read_b128 v[178:181], v207 offset:36864
	ds_read_b128 v[182:185], v207 offset:37888
	ds_read_b128 v[186:189], v207 offset:38912
	ds_read_b128 v[190:193], v207 offset:39936
	s_add_u32 s52, s52, 0x4000
	s_addc_u32 s53, s53, 0
	s_mov_b32 m0, s64
	s_nop 0
	global_load_lds_dwordx4 v195, s[52:53]
	s_add_u32 m0, s64, 0x2000
	s_nop 0
	global_load_lds_dwordx4 v197, s[52:53]
	s_waitcnt vmcnt(8)
	s_waitcnt lgkmcnt(0)
	s_setprio 1
	s_barrier
	v_mfma_f32_16x16x32_bf16 v[126:129], v[130:133], v[162:165], v[126:129]
	v_mfma_f32_16x16x32_bf16 v[126:129], v[134:137], v[166:169], v[126:129]
	s_waitcnt lgkmcnt(5)
	v_mfma_f32_16x16x32_bf16 v[122:125], v[138:141], v[162:165], v[122:125]
	v_mfma_f32_16x16x32_bf16 v[122:125], v[142:145], v[166:169], v[122:125]
	s_waitcnt lgkmcnt(3)
	v_mfma_f32_16x16x32_bf16 v[118:121], v[130:133], v[170:173], v[118:121]
	v_mfma_f32_16x16x32_bf16 v[118:121], v[134:137], v[174:177], v[118:121]
	s_waitcnt lgkmcnt(1)
	v_mfma_f32_16x16x32_bf16 v[114:117], v[138:141], v[170:173], v[114:117]
	v_mfma_f32_16x16x32_bf16 v[114:117], v[142:145], v[174:177], v[114:117]
	v_mfma_f32_16x16x32_bf16 v[110:113], v[130:133], v[178:181], v[110:113]
	v_mfma_f32_16x16x32_bf16 v[110:113], v[134:137], v[182:185], v[110:113]
	v_mfma_f32_16x16x32_bf16 v[106:109], v[138:141], v[178:181], v[106:109]
	v_mfma_f32_16x16x32_bf16 v[106:109], v[142:145], v[182:185], v[106:109]
	v_mfma_f32_16x16x32_bf16 v[102:105], v[130:133], v[186:189], v[102:105]
	v_mfma_f32_16x16x32_bf16 v[102:105], v[134:137], v[190:193], v[102:105]
	s_waitcnt lgkmcnt(0)
	v_mfma_f32_16x16x32_bf16 v[98:101], v[138:141], v[186:189], v[98:101]
	v_mfma_f32_16x16x32_bf16 v[98:101], v[142:145], v[190:193], v[98:101]
	s_setprio 0
	s_setprio 1
	v_mfma_f32_16x16x32_bf16 v[94:97], v[146:149], v[162:165], v[94:97]
	v_mfma_f32_16x16x32_bf16 v[94:97], v[150:153], v[166:169], v[94:97]
	v_mfma_f32_16x16x32_bf16 v[90:93], v[154:157], v[162:165], v[90:93]
	v_mfma_f32_16x16x32_bf16 v[90:93], v[158:161], v[166:169], v[90:93]
	v_mfma_f32_16x16x32_bf16 v[86:89], v[146:149], v[170:173], v[86:89]
	v_mfma_f32_16x16x32_bf16 v[86:89], v[150:153], v[174:177], v[86:89]
	v_mfma_f32_16x16x32_bf16 v[82:85], v[154:157], v[170:173], v[82:85]
	v_mfma_f32_16x16x32_bf16 v[82:85], v[158:161], v[174:177], v[82:85]
	v_mfma_f32_16x16x32_bf16 v[78:81], v[146:149], v[178:181], v[78:81]
	v_mfma_f32_16x16x32_bf16 v[78:81], v[150:153], v[182:185], v[78:81]
	v_mfma_f32_16x16x32_bf16 v[74:77], v[154:157], v[178:181], v[74:77]
	v_mfma_f32_16x16x32_bf16 v[74:77], v[158:161], v[182:185], v[74:77]
	v_mfma_f32_16x16x32_bf16 v[70:73], v[146:149], v[186:189], v[70:73]
	v_mfma_f32_16x16x32_bf16 v[70:73], v[150:153], v[190:193], v[70:73]
	s_setprio 2
	s_barrier
	v_mfma_f32_16x16x32_bf16 v[66:69], v[154:157], v[186:189], v[66:69]
	v_mfma_f32_16x16x32_bf16 v[66:69], v[158:161], v[190:193], v[66:69]
	s_setprio 0
	s_nop 0
	ds_read_b128 v[162:165], v207 offset:49152
	ds_read_b128 v[166:169], v207 offset:50176
	ds_read_b128 v[170:173], v207 offset:51200
	ds_read_b128 v[174:177], v207 offset:52224
	ds_read_b128 v[178:181], v207 offset:53248
	ds_read_b128 v[182:185], v207 offset:54272
	ds_read_b128 v[186:189], v207 offset:55296
	ds_read_b128 v[190:193], v207 offset:56320
	s_mov_b32 m0, s70
	s_nop 0
	global_load_lds_dwordx4 v195, s[56:57]
	s_add_u32 m0, s70, 0x2000
	s_nop 0
	global_load_lds_dwordx4 v197, s[56:57]
	s_add_u32 s50, s50, 0xc000
	s_addc_u32 s51, s51, 0
	s_mov_b32 m0, s72
	s_nop 0
	global_load_lds_dwordx4 v195, s[50:51]
	s_add_u32 m0, s72, 0x2000
	s_nop 0
	global_load_lds_dwordx4 v197, s[50:51]
	s_nop 0
	s_mov_b32 m0, s71
	s_nop 0
	global_load_lds_dwordx4 v195, s[54:55]
	s_add_u32 m0, s71, 0x2000
	s_nop 0
	global_load_lds_dwordx4 v197, s[54:55]
	s_waitcnt vmcnt(8)
	s_waitcnt lgkmcnt(0)
	s_setprio 1
	s_barrier
	v_mfma_f32_16x16x32_bf16 v[62:65], v[130:133], v[162:165], v[62:65]
	v_mfma_f32_16x16x32_bf16 v[62:65], v[134:137], v[166:169], v[62:65]
	s_waitcnt lgkmcnt(5)
	v_mfma_f32_16x16x32_bf16 v[58:61], v[138:141], v[162:165], v[58:61]
	v_mfma_f32_16x16x32_bf16 v[58:61], v[142:145], v[166:169], v[58:61]
	s_waitcnt lgkmcnt(3)
	v_mfma_f32_16x16x32_bf16 v[54:57], v[130:133], v[170:173], v[54:57]
	v_mfma_f32_16x16x32_bf16 v[54:57], v[134:137], v[174:177], v[54:57]
	s_waitcnt lgkmcnt(1)
	v_mfma_f32_16x16x32_bf16 v[50:53], v[138:141], v[170:173], v[50:53]
	v_mfma_f32_16x16x32_bf16 v[50:53], v[142:145], v[174:177], v[50:53]
	v_mfma_f32_16x16x32_bf16 v[46:49], v[130:133], v[178:181], v[46:49]
	v_mfma_f32_16x16x32_bf16 v[46:49], v[134:137], v[182:185], v[46:49]
	v_mfma_f32_16x16x32_bf16 v[42:45], v[138:141], v[178:181], v[42:45]
	v_mfma_f32_16x16x32_bf16 v[42:45], v[142:145], v[182:185], v[42:45]
	v_mfma_f32_16x16x32_bf16 v[38:41], v[130:133], v[186:189], v[38:41]
	v_mfma_f32_16x16x32_bf16 v[38:41], v[134:137], v[190:193], v[38:41]
	s_waitcnt lgkmcnt(0)
	v_mfma_f32_16x16x32_bf16 v[34:37], v[138:141], v[186:189], v[34:37]
	v_mfma_f32_16x16x32_bf16 v[34:37], v[142:145], v[190:193], v[34:37]
	s_setprio 0
	s_setprio 1
	v_mfma_f32_16x16x32_bf16 v[30:33], v[146:149], v[162:165], v[30:33]
	v_mfma_f32_16x16x32_bf16 v[30:33], v[150:153], v[166:169], v[30:33]
	v_mfma_f32_16x16x32_bf16 v[26:29], v[154:157], v[162:165], v[26:29]
	v_mfma_f32_16x16x32_bf16 v[26:29], v[158:161], v[166:169], v[26:29]
	v_mfma_f32_16x16x32_bf16 v[22:25], v[146:149], v[170:173], v[22:25]
	v_mfma_f32_16x16x32_bf16 v[22:25], v[150:153], v[174:177], v[22:25]
	v_mfma_f32_16x16x32_bf16 v[18:21], v[154:157], v[170:173], v[18:21]
	v_mfma_f32_16x16x32_bf16 v[18:21], v[158:161], v[174:177], v[18:21]
	v_mfma_f32_16x16x32_bf16 v[14:17], v[146:149], v[178:181], v[14:17]
	v_mfma_f32_16x16x32_bf16 v[14:17], v[150:153], v[182:185], v[14:17]
	v_mfma_f32_16x16x32_bf16 v[10:13], v[154:157], v[178:181], v[10:13]
	v_mfma_f32_16x16x32_bf16 v[10:13], v[158:161], v[182:185], v[10:13]
	v_mfma_f32_16x16x32_bf16 v[6:9], v[146:149], v[186:189], v[6:9]
	v_mfma_f32_16x16x32_bf16 v[6:9], v[150:153], v[190:193], v[6:9]
	s_setprio 2
	s_barrier
	v_mfma_f32_16x16x32_bf16 v[2:5], v[154:157], v[186:189], v[2:5]
	v_mfma_f32_16x16x32_bf16 v[2:5], v[158:161], v[190:193], v[2:5]
	s_setprio 0
	s_nop 0
	s_add_i32 s15, s90, 2
	s_cmp_gt_u32 s90, 13
	s_cbranch_scc1 .LBB0_2124
	v_mov_b32_e32 v130, v198
	s_mov_b32 s90, s15
	s_branch .LBB0_2099

.LBB0_2229:
	s_add_i32 s22, s46, 2
	s_lshl_b64 s[42:43], s[22:23], 15
	s_add_u32 s44, s2, s42
	s_addc_u32 s45, s3, s43
	s_and_b64 s[38:39], s[14:15], exec
	s_cselect_b32 s39, s45, s29
	s_cselect_b32 s38, s44, s28
	s_add_u32 s42, s16, s42
	s_waitcnt vmcnt(8)
	s_addc_u32 s43, s17, s43
	s_waitcnt lgkmcnt(0)
	s_and_b64 s[14:15], s[14:15], exec
	s_cselect_b32 s15, s43, s31
	s_cselect_b32 s14, s42, s30
	s_setprio 1
	s_barrier
	v_mfma_f32_16x16x32_bf16 v[126:129], v[146:149], v[186:189], v[126:129]
	v_mfma_f32_16x16x32_bf16 v[126:129], v[150:153], v[190:193], v[126:129]
	s_waitcnt lgkmcnt(5)
	v_mfma_f32_16x16x32_bf16 v[122:125], v[154:157], v[186:189], v[122:125]
	v_mfma_f32_16x16x32_bf16 v[122:125], v[158:161], v[190:193], v[122:125]
	s_waitcnt lgkmcnt(3)
	v_mfma_f32_16x16x32_bf16 v[118:121], v[146:149], v[178:181], v[118:121]
	v_mfma_f32_16x16x32_bf16 v[118:121], v[150:153], v[182:185], v[118:121]
	s_waitcnt lgkmcnt(1)
	v_mfma_f32_16x16x32_bf16 v[114:117], v[154:157], v[178:181], v[114:117]
	v_mfma_f32_16x16x32_bf16 v[114:117], v[158:161], v[182:185], v[114:117]
	v_mfma_f32_16x16x32_bf16 v[110:113], v[146:149], v[170:173], v[110:113]
	v_mfma_f32_16x16x32_bf16 v[110:113], v[150:153], v[174:177], v[110:113]
	v_mfma_f32_16x16x32_bf16 v[106:109], v[154:157], v[170:173], v[106:109]
	v_mfma_f32_16x16x32_bf16 v[106:109], v[158:161], v[174:177], v[106:109]
	v_mfma_f32_16x16x32_bf16 v[102:105], v[146:149], v[162:165], v[102:105]
	v_mfma_f32_16x16x32_bf16 v[102:105], v[150:153], v[166:169], v[102:105]
	s_waitcnt lgkmcnt(0)
	v_mfma_f32_16x16x32_bf16 v[98:101], v[154:157], v[162:165], v[98:101]
	v_mfma_f32_16x16x32_bf16 v[98:101], v[158:161], v[166:169], v[98:101]
	s_setprio 0
	s_setprio 1
	v_mfma_f32_16x16x32_bf16 v[94:97], v[130:133], v[186:189], v[94:97]
	v_mfma_f32_16x16x32_bf16 v[94:97], v[134:137], v[190:193], v[94:97]
	v_mfma_f32_16x16x32_bf16 v[90:93], v[138:141], v[186:189], v[90:93]
	v_mfma_f32_16x16x32_bf16 v[90:93], v[142:145], v[190:193], v[90:93]
	v_mfma_f32_16x16x32_bf16 v[86:89], v[130:133], v[178:181], v[86:89]
	v_mfma_f32_16x16x32_bf16 v[86:89], v[134:137], v[182:185], v[86:89]
	v_mfma_f32_16x16x32_bf16 v[82:85], v[138:141], v[178:181], v[82:85]
	v_mfma_f32_16x16x32_bf16 v[82:85], v[142:145], v[182:185], v[82:85]
	v_mfma_f32_16x16x32_bf16 v[78:81], v[130:133], v[170:173], v[78:81]
	v_mfma_f32_16x16x32_bf16 v[78:81], v[134:137], v[174:177], v[78:81]
	v_mfma_f32_16x16x32_bf16 v[74:77], v[138:141], v[170:173], v[74:77]
	v_mfma_f32_16x16x32_bf16 v[74:77], v[142:145], v[174:177], v[74:77]
	v_mfma_f32_16x16x32_bf16 v[70:73], v[130:133], v[162:165], v[70:73]
	v_mfma_f32_16x16x32_bf16 v[70:73], v[134:137], v[166:169], v[70:73]
	s_setprio 2
	s_barrier
	v_mfma_f32_16x16x32_bf16 v[66:69], v[138:141], v[162:165], v[66:69]
	v_mfma_f32_16x16x32_bf16 v[66:69], v[142:145], v[166:169], v[66:69]
	s_setprio 0
	s_nop 0
	ds_read_b128 v[186:189], v215 offset:16384
	ds_read_b128 v[190:193], v215 offset:17408
	ds_read_b128 v[178:181], v215 offset:18432
	ds_read_b128 v[182:185], v215 offset:19456
	ds_read_b128 v[170:173], v215 offset:20480
	ds_read_b128 v[174:177], v215 offset:21504
	ds_read_b128 v[162:165], v215 offset:22528
	ds_read_b128 v[166:169], v215 offset:23552
	s_mov_b32 m0, s57
	s_nop 0
	global_load_lds_dwordx4 v195, s[14:15]
	s_add_u32 m0, s57, 0x2000
	s_nop 0
	global_load_lds_dwordx4 v208, s[14:15]
	s_add_u32 s42, s14, 0x4000
	s_addc_u32 s43, s15, 0
	s_mov_b32 m0, s58
	s_nop 0
	global_load_lds_dwordx4 v195, s[42:43]
	s_add_u32 m0, s58, 0x2000
	s_nop 0
	global_load_lds_dwordx4 v208, s[42:43]
	s_andn2_b64 vcc, exec, s[40:41]
	s_mov_b32 m0, s56
	s_nop 0
	global_load_lds_dwordx4 v195, s[38:39]
	s_add_u32 m0, s56, 0x2000
	s_nop 0
	global_load_lds_dwordx4 v208, s[38:39]
	s_cbranch_vccnz .LBB0_2231
	v_mov_b32_e32 v2, 0
	v_mov_b32_e32 v3, v2
	v_mov_b32_e32 v4, v2
	v_mov_b32_e32 v5, v2
	v_mov_b32_e32 v6, v2
	v_mov_b32_e32 v7, v2
	v_mov_b32_e32 v8, v2
	v_mov_b32_e32 v9, v2
	v_mov_b32_e32 v10, v2
	v_mov_b32_e32 v11, v2
	v_mov_b32_e32 v12, v2
	v_mov_b32_e32 v13, v2
	v_mov_b32_e32 v14, v2
	v_mov_b32_e32 v15, v2
	v_mov_b32_e32 v16, v2
	v_mov_b32_e32 v17, v2
	v_mov_b32_e32 v18, v2
	v_mov_b32_e32 v19, v2
	v_mov_b32_e32 v20, v2
	v_mov_b32_e32 v21, v2
	v_mov_b32_e32 v22, v2
	v_mov_b32_e32 v23, v2
	v_mov_b32_e32 v24, v2
	v_mov_b32_e32 v25, v2
	v_mov_b32_e32 v26, v2
	v_mov_b32_e32 v27, v2
	v_mov_b32_e32 v28, v2
	v_mov_b32_e32 v29, v2
	v_mov_b32_e32 v30, v2
	v_mov_b32_e32 v31, v2
	v_mov_b32_e32 v32, v2
	v_mov_b32_e32 v33, v2
	v_mov_b32_e32 v34, v2
	v_mov_b32_e32 v35, v2
	v_mov_b32_e32 v36, v2
	v_mov_b32_e32 v37, v2
	v_mov_b32_e32 v38, v2
	v_mov_b32_e32 v39, v2
	v_mov_b32_e32 v40, v2
	v_mov_b32_e32 v41, v2
	v_mov_b32_e32 v42, v2
	v_mov_b32_e32 v43, v2
	v_mov_b32_e32 v44, v2
	v_mov_b32_e32 v45, v2
	v_mov_b32_e32 v46, v2
	v_mov_b32_e32 v47, v2
	v_mov_b32_e32 v48, v2
	v_mov_b32_e32 v49, v2
	v_mov_b32_e32 v50, v2
	v_mov_b32_e32 v51, v2
	v_mov_b32_e32 v52, v2
	v_mov_b32_e32 v53, v2
	v_mov_b32_e32 v54, v2
	v_mov_b32_e32 v55, v2
	v_mov_b32_e32 v56, v2
	v_mov_b32_e32 v57, v2
	v_mov_b32_e32 v58, v2
	v_mov_b32_e32 v59, v2
	v_mov_b32_e32 v60, v2
	v_mov_b32_e32 v61, v2
	v_mov_b32_e32 v62, v2
	v_mov_b32_e32 v63, v2
	v_mov_b32_e32 v64, v2
	v_mov_b32_e32 v65, v2
.LBB0_2231:
	s_waitcnt vmcnt(8)
	s_add_u32 s40, s38, 0x8000
	s_waitcnt lgkmcnt(0)
	s_addc_u32 s41, s39, 0
	s_add_u32 s42, s14, 0x8000
	s_addc_u32 s43, s15, 0
	s_setprio 1
	s_barrier
	v_mfma_f32_16x16x32_bf16 v[62:65], v[146:149], v[186:189], v[62:65]
	v_mfma_f32_16x16x32_bf16 v[62:65], v[150:153], v[190:193], v[62:65]
	s_waitcnt lgkmcnt(5)
	v_mfma_f32_16x16x32_bf16 v[58:61], v[154:157], v[186:189], v[58:61]
	v_mfma_f32_16x16x32_bf16 v[58:61], v[158:161], v[190:193], v[58:61]
	s_waitcnt lgkmcnt(3)
	v_mfma_f32_16x16x32_bf16 v[54:57], v[146:149], v[178:181], v[54:57]
	v_mfma_f32_16x16x32_bf16 v[54:57], v[150:153], v[182:185], v[54:57]
	s_waitcnt lgkmcnt(1)
	v_mfma_f32_16x16x32_bf16 v[50:53], v[154:157], v[178:181], v[50:53]
	v_mfma_f32_16x16x32_bf16 v[50:53], v[158:161], v[182:185], v[50:53]
	v_mfma_f32_16x16x32_bf16 v[46:49], v[146:149], v[170:173], v[46:49]
	v_mfma_f32_16x16x32_bf16 v[46:49], v[150:153], v[174:177], v[46:49]
	v_mfma_f32_16x16x32_bf16 v[42:45], v[154:157], v[170:173], v[42:45]
	v_mfma_f32_16x16x32_bf16 v[42:45], v[158:161], v[174:177], v[42:45]
	v_mfma_f32_16x16x32_bf16 v[38:41], v[146:149], v[162:165], v[38:41]
	v_mfma_f32_16x16x32_bf16 v[38:41], v[150:153], v[166:169], v[38:41]
	s_waitcnt lgkmcnt(0)
	v_mfma_f32_16x16x32_bf16 v[34:37], v[154:157], v[162:165], v[34:37]
	v_mfma_f32_16x16x32_bf16 v[34:37], v[158:161], v[166:169], v[34:37]
	s_setprio 0
	s_setprio 1
	v_mfma_f32_16x16x32_bf16 v[30:33], v[130:133], v[186:189], v[30:33]
	v_mfma_f32_16x16x32_bf16 v[30:33], v[134:137], v[190:193], v[30:33]
	v_mfma_f32_16x16x32_bf16 v[26:29], v[138:141], v[186:189], v[26:29]
	v_mfma_f32_16x16x32_bf16 v[26:29], v[142:145], v[190:193], v[26:29]
	v_mfma_f32_16x16x32_bf16 v[22:25], v[130:133], v[178:181], v[22:25]
	v_mfma_f32_16x16x32_bf16 v[22:25], v[134:137], v[182:185], v[22:25]
	v_mfma_f32_16x16x32_bf16 v[18:21], v[138:141], v[178:181], v[18:21]
	v_mfma_f32_16x16x32_bf16 v[18:21], v[142:145], v[182:185], v[18:21]
	v_mfma_f32_16x16x32_bf16 v[14:17], v[130:133], v[170:173], v[14:17]
	v_mfma_f32_16x16x32_bf16 v[14:17], v[134:137], v[174:177], v[14:17]
	v_mfma_f32_16x16x32_bf16 v[10:13], v[138:141], v[170:173], v[10:13]
	v_mfma_f32_16x16x32_bf16 v[10:13], v[142:145], v[174:177], v[10:13]
	v_mfma_f32_16x16x32_bf16 v[6:9], v[130:133], v[162:165], v[6:9]
	v_mfma_f32_16x16x32_bf16 v[6:9], v[134:137], v[166:169], v[6:9]
	s_setprio 2
	s_barrier
	v_mfma_f32_16x16x32_bf16 v[2:5], v[138:141], v[162:165], v[2:5]
	v_mfma_f32_16x16x32_bf16 v[2:5], v[142:145], v[166:169], v[2:5]
	s_setprio 0
	s_nop 0
	v_add_u32_e32 v142, 0x18000, v214
	v_add_u32_e32 v158, 0x1c000, v214
	ds_read_b128 v[130:133], v142
	ds_read_b128 v[134:137], v142 offset:1024
	ds_read_b128 v[138:141], v142 offset:2048
	ds_read_b128 v[142:145], v142 offset:3072
	ds_read_b128 v[146:149], v158
	ds_read_b128 v[150:153], v158 offset:1024
	ds_read_b128 v[154:157], v158 offset:2048
	ds_read_b128 v[158:161], v158 offset:3072
	ds_read_b128 v[162:165], v215 offset:32768
	ds_read_b128 v[166:169], v215 offset:33792
	ds_read_b128 v[170:173], v215 offset:34816
	ds_read_b128 v[174:177], v215 offset:35840
	ds_read_b128 v[178:181], v215 offset:36864
	ds_read_b128 v[182:185], v215 offset:37888
	ds_read_b128 v[186:189], v215 offset:38912
	ds_read_b128 v[190:193], v215 offset:39936
	s_add_u32 s38, s38, 0x4000
	s_addc_u32 s39, s39, 0
	s_mov_b32 m0, s59
	s_nop 0
	global_load_lds_dwordx4 v195, s[38:39]
	s_add_u32 m0, s59, 0x2000
	s_nop 0
	global_load_lds_dwordx4 v208, s[38:39]
	s_waitcnt vmcnt(8)
	s_waitcnt lgkmcnt(0)
	s_setprio 1
	s_barrier
	v_mfma_f32_16x16x32_bf16 v[126:129], v[130:133], v[162:165], v[126:129]
	v_mfma_f32_16x16x32_bf16 v[126:129], v[134:137], v[166:169], v[126:129]
	s_waitcnt lgkmcnt(5)
	v_mfma_f32_16x16x32_bf16 v[122:125], v[138:141], v[162:165], v[122:125]
	v_mfma_f32_16x16x32_bf16 v[122:125], v[142:145], v[166:169], v[122:125]
	s_waitcnt lgkmcnt(3)
	v_mfma_f32_16x16x32_bf16 v[118:121], v[130:133], v[170:173], v[118:121]
	v_mfma_f32_16x16x32_bf16 v[118:121], v[134:137], v[174:177], v[118:121]
	s_waitcnt lgkmcnt(1)
	v_mfma_f32_16x16x32_bf16 v[114:117], v[138:141], v[170:173], v[114:117]
	v_mfma_f32_16x16x32_bf16 v[114:117], v[142:145], v[174:177], v[114:117]
	v_mfma_f32_16x16x32_bf16 v[110:113], v[130:133], v[178:181], v[110:113]
	v_mfma_f32_16x16x32_bf16 v[110:113], v[134:137], v[182:185], v[110:113]
	v_mfma_f32_16x16x32_bf16 v[106:109], v[138:141], v[178:181], v[106:109]
	v_mfma_f32_16x16x32_bf16 v[106:109], v[142:145], v[182:185], v[106:109]
	v_mfma_f32_16x16x32_bf16 v[102:105], v[130:133], v[186:189], v[102:105]
	v_mfma_f32_16x16x32_bf16 v[102:105], v[134:137], v[190:193], v[102:105]
	s_waitcnt lgkmcnt(0)
	v_mfma_f32_16x16x32_bf16 v[98:101], v[138:141], v[186:189], v[98:101]
	v_mfma_f32_16x16x32_bf16 v[98:101], v[142:145], v[190:193], v[98:101]
	s_setprio 0
	s_setprio 1
	v_mfma_f32_16x16x32_bf16 v[94:97], v[146:149], v[162:165], v[94:97]
	v_mfma_f32_16x16x32_bf16 v[94:97], v[150:153], v[166:169], v[94:97]
	v_mfma_f32_16x16x32_bf16 v[90:93], v[154:157], v[162:165], v[90:93]
	v_mfma_f32_16x16x32_bf16 v[90:93], v[158:161], v[166:169], v[90:93]
	v_mfma_f32_16x16x32_bf16 v[86:89], v[146:149], v[170:173], v[86:89]
	v_mfma_f32_16x16x32_bf16 v[86:89], v[150:153], v[174:177], v[86:89]
	v_mfma_f32_16x16x32_bf16 v[82:85], v[154:157], v[170:173], v[82:85]
	v_mfma_f32_16x16x32_bf16 v[82:85], v[158:161], v[174:177], v[82:85]
	v_mfma_f32_16x16x32_bf16 v[78:81], v[146:149], v[178:181], v[78:81]
	v_mfma_f32_16x16x32_bf16 v[78:81], v[150:153], v[182:185], v[78:81]
	v_mfma_f32_16x16x32_bf16 v[74:77], v[154:157], v[178:181], v[74:77]
	v_mfma_f32_16x16x32_bf16 v[74:77], v[158:161], v[182:185], v[74:77]
	v_mfma_f32_16x16x32_bf16 v[70:73], v[146:149], v[186:189], v[70:73]
	v_mfma_f32_16x16x32_bf16 v[70:73], v[150:153], v[190:193], v[70:73]
	s_setprio 2
	s_barrier
	v_mfma_f32_16x16x32_bf16 v[66:69], v[154:157], v[186:189], v[66:69]
	v_mfma_f32_16x16x32_bf16 v[66:69], v[158:161], v[190:193], v[66:69]
	s_setprio 0
	s_nop 0
	ds_read_b128 v[162:165], v215 offset:49152
	ds_read_b128 v[166:169], v215 offset:50176
	ds_read_b128 v[170:173], v215 offset:51200
	ds_read_b128 v[174:177], v215 offset:52224
	ds_read_b128 v[178:181], v215 offset:53248
	ds_read_b128 v[182:185], v215 offset:54272
	ds_read_b128 v[186:189], v215 offset:55296
	ds_read_b128 v[190:193], v215 offset:56320
	s_mov_b32 m0, s63
	s_nop 0
	global_load_lds_dwordx4 v195, s[42:43]
	s_add_u32 m0, s63, 0x2000
	s_nop 0
	global_load_lds_dwordx4 v208, s[42:43]
	s_add_u32 s14, s14, 0xc000
	s_addc_u32 s15, s15, 0
	s_mov_b32 m0, s65
	s_nop 0
	global_load_lds_dwordx4 v195, s[14:15]
	s_add_u32 m0, s65, 0x2000
	s_nop 0
	global_load_lds_dwordx4 v208, s[14:15]
	s_nop 0
	s_mov_b32 m0, s64
	s_nop 0
	global_load_lds_dwordx4 v195, s[40:41]
	s_add_u32 m0, s64, 0x2000
	s_nop 0
	global_load_lds_dwordx4 v208, s[40:41]
	s_waitcnt vmcnt(8)
	s_waitcnt lgkmcnt(0)
	s_setprio 1
	s_barrier
	v_mfma_f32_16x16x32_bf16 v[62:65], v[130:133], v[162:165], v[62:65]
	v_mfma_f32_16x16x32_bf16 v[62:65], v[134:137], v[166:169], v[62:65]
	s_waitcnt lgkmcnt(5)
	v_mfma_f32_16x16x32_bf16 v[58:61], v[138:141], v[162:165], v[58:61]
	v_mfma_f32_16x16x32_bf16 v[58:61], v[142:145], v[166:169], v[58:61]
	s_waitcnt lgkmcnt(3)
	v_mfma_f32_16x16x32_bf16 v[54:57], v[130:133], v[170:173], v[54:57]
	v_mfma_f32_16x16x32_bf16 v[54:57], v[134:137], v[174:177], v[54:57]
	s_waitcnt lgkmcnt(1)
	v_mfma_f32_16x16x32_bf16 v[50:53], v[138:141], v[170:173], v[50:53]
	v_mfma_f32_16x16x32_bf16 v[50:53], v[142:145], v[174:177], v[50:53]
	v_mfma_f32_16x16x32_bf16 v[46:49], v[130:133], v[178:181], v[46:49]
	v_mfma_f32_16x16x32_bf16 v[46:49], v[134:137], v[182:185], v[46:49]
	v_mfma_f32_16x16x32_bf16 v[42:45], v[138:141], v[178:181], v[42:45]
	v_mfma_f32_16x16x32_bf16 v[42:45], v[142:145], v[182:185], v[42:45]
	v_mfma_f32_16x16x32_bf16 v[38:41], v[130:133], v[186:189], v[38:41]
	v_mfma_f32_16x16x32_bf16 v[38:41], v[134:137], v[190:193], v[38:41]
	s_waitcnt lgkmcnt(0)
	v_mfma_f32_16x16x32_bf16 v[34:37], v[138:141], v[186:189], v[34:37]
	v_mfma_f32_16x16x32_bf16 v[34:37], v[142:145], v[190:193], v[34:37]
	s_setprio 0
	s_setprio 1
	v_mfma_f32_16x16x32_bf16 v[30:33], v[146:149], v[162:165], v[30:33]
	v_mfma_f32_16x16x32_bf16 v[30:33], v[150:153], v[166:169], v[30:33]
	v_mfma_f32_16x16x32_bf16 v[26:29], v[154:157], v[162:165], v[26:29]
	v_mfma_f32_16x16x32_bf16 v[26:29], v[158:161], v[166:169], v[26:29]
	v_mfma_f32_16x16x32_bf16 v[22:25], v[146:149], v[170:173], v[22:25]
	v_mfma_f32_16x16x32_bf16 v[22:25], v[150:153], v[174:177], v[22:25]
	v_mfma_f32_16x16x32_bf16 v[18:21], v[154:157], v[170:173], v[18:21]
	v_mfma_f32_16x16x32_bf16 v[18:21], v[158:161], v[174:177], v[18:21]
	v_mfma_f32_16x16x32_bf16 v[14:17], v[146:149], v[178:181], v[14:17]
	v_mfma_f32_16x16x32_bf16 v[14:17], v[150:153], v[182:185], v[14:17]
	v_mfma_f32_16x16x32_bf16 v[10:13], v[154:157], v[178:181], v[10:13]
	v_mfma_f32_16x16x32_bf16 v[10:13], v[158:161], v[182:185], v[10:13]
	v_mfma_f32_16x16x32_bf16 v[6:9], v[146:149], v[186:189], v[6:9]
	v_mfma_f32_16x16x32_bf16 v[6:9], v[150:153], v[190:193], v[6:9]
	s_setprio 2
	s_barrier
	v_mfma_f32_16x16x32_bf16 v[2:5], v[154:157], v[186:189], v[2:5]
	v_mfma_f32_16x16x32_bf16 v[2:5], v[158:161], v[190:193], v[2:5]
	s_setprio 0
	s_nop 0
	s_cmp_gt_u32 s46, 41
	s_cbranch_scc1 .LBB0_2233
	v_mov_b32_e32 v130, v196
	s_mov_b32 s46, s22
	s_branch .LBB0_2208
